# v26: v24 plus first K reads hoisted, G3 layer-0 spreading, prep_unit prefetch (measurement 1)
# speedup vs baseline: 1.0021x; 1.0021x over previous
.LBB0_675:
	v_ashrrev_i32_e32 v65, 3, v64
	v_add_u32_e32 v2, s10, v65
	v_lshlrev_b32_e32 v4, 7, v64
	v_mad_i64_i32 v[22:23], s[6:7], v2, s3, v[20:21]
	v_and_b32_e32 v18, 0x200, v4
	v_lshl_add_u64 v[2:3], v[22:23], 0, v[18:19]
	v_and_b32_e32 v18, 0x180, v4
	v_lshl_add_u64 v[2:3], v[2:3], 0, v[18:19]
	global_load_dwordx4 v[28:31], v[2:3], off offset:3136
	global_load_dwordx4 v[32:35], v[2:3], off offset:3152
	global_load_dwordx4 v[68:71], v[2:3], off offset:3168
	global_load_dwordx4 v[72:75], v[2:3], off offset:3184
	global_load_dwordx4 v[14:17], v[2:3], off offset:3200
	global_load_dwordx4 v[10:13], v[2:3], off offset:3216
	global_load_dwordx4 v[6:9], v[2:3], off offset:3232
	s_nop 0
	global_load_dwordx4 v[2:5], v[2:3], off offset:3248
	v_and_b32_e32 v120, 7, v64
	v_lshlrev_b32_e32 v120, 7, v120
	v_mov_b32_e32 v121, 0
	v_lshl_add_u64 v[122:123], v[22:23], 0, v[120:121]
	global_load_dword v124, v[122:123], off offset:2112
	v_add_u32_e32 v126, 0x800, v120
	v_mov_b32_e32 v127, 0
	v_lshl_add_u64 v[126:127], v[22:23], 0, v[126:127]
	global_load_dword v125, v[126:127], off offset:2112
	v_add_u32_e32 v18, s14, v65
	v_add_u32_e32 v18, 0xffffff00, v18
	v_bfe_u32 v66, v64, 2, 1
	v_ashrrev_i32_e32 v25, 3, v18
	v_and_b32_e32 v67, 3, v64
	v_lshlrev_b32_e32 v18, 9, v66
	v_and_b32_e32 v26, -8, v25
	s_cmp_gt_i32 s2, 3
	v_and_b32_e32 v24, 0x1f8, v64
	v_lshl_add_u64 v[22:23], v[22:23], 0, v[18:19]
	v_lshlrev_b32_e32 v18, 7, v67
	v_lshlrev_b32_e32 v26, 1, v26
	s_cselect_b64 s[18:19], -1, 0
	s_cmp_lt_i32 s2, 4
	v_lshl_add_u64 v[22:23], v[22:23], 0, v[18:19]
	v_lshlrev_b32_e32 v18, 3, v24
	v_ashrrev_i32_e32 v27, 31, v26
	v_lshl_or_b32 v24, v25, 1, 14
	s_waitcnt vmcnt(9)
	v_lshlrev_b32_e32 v49, 16, v29
	v_lshlrev_b32_e32 v48, 16, v28
	v_and_b32_e32 v45, 0xffff0000, v29
	v_and_b32_e32 v44, 0xffff0000, v28
	s_waitcnt vmcnt(8)
	v_lshlrev_b32_e32 v61, 16, v33
	v_lshlrev_b32_e32 v60, 16, v32
	v_and_b32_e32 v59, 0xffff0000, v33
	v_and_b32_e32 v58, 0xffff0000, v32
	v_lshlrev_b32_e32 v41, 16, v31
	v_lshlrev_b32_e32 v40, 16, v30
	v_and_b32_e32 v39, 0xffff0000, v31
	v_and_b32_e32 v38, 0xffff0000, v30
	v_lshlrev_b32_e32 v57, 16, v35
	v_lshlrev_b32_e32 v56, 16, v34
	v_and_b32_e32 v55, 0xffff0000, v35
	v_and_b32_e32 v54, 0xffff0000, v34
	s_waitcnt vmcnt(7)
	v_and_b32_e32 v30, 0xffff0000, v70
	v_lshlrev_b32_e32 v37, 16, v69
	v_lshlrev_b32_e32 v36, 16, v68
	v_and_b32_e32 v35, 0xffff0000, v69
	v_and_b32_e32 v34, 0xffff0000, v68
	s_waitcnt vmcnt(6)
	v_lshlrev_b32_e32 v53, 16, v73
	v_lshlrev_b32_e32 v52, 16, v72
	v_and_b32_e32 v51, 0xffff0000, v73
	v_and_b32_e32 v50, 0xffff0000, v72
	v_and_b32_e32 v28, 0xffff0000, v74
	v_lshlrev_b32_e32 v33, 16, v71
	v_lshlrev_b32_e32 v32, 16, v70
	v_lshlrev_b32_e32 v47, 16, v75
	v_lshlrev_b32_e32 v46, 16, v74
	v_and_b32_e32 v43, 0xffff0000, v71
	v_and_b32_e32 v42, 0xffff0000, v75
	s_cbranch_scc1 .LBB0_677
	v_lshl_add_u64 v[80:81], v[26:27], 2, s[8:9]
	v_lshl_add_u64 v[84:85], s[8:9], 0, v[18:19]
	v_ashrrev_i32_e32 v25, 31, v24
	global_load_dwordx4 v[68:71], v[80:81], off
	global_load_dwordx4 v[72:75], v[80:81], off offset:16
	global_load_dwordx4 v[76:79], v[80:81], off offset:32
	global_load_dwordx2 v[96:97], v[80:81], off offset:48
	v_lshl_add_u64 v[92:93], v[84:85], 0, s[12:13]
	v_lshl_add_u64 v[86:87], v[24:25], 2, s[8:9]
	global_load_dwordx4 v[80:83], v[92:93], off offset:48
	global_load_dwordx2 v[98:99], v[86:87], off
	v_add_co_u32_e32 v84, vcc, s26, v84
	s_waitcnt vmcnt(5)
	v_mov_b32_e32 v100, v68
	v_addc_co_u32_e32 v85, vcc, 0, v85, vcc
	global_load_dwordx4 v[84:87], v[84:85], off
	s_nop 0
	global_load_dwordx4 v[88:91], v[92:93], off offset:16
	s_nop 0
	global_load_dwordx4 v[92:95], v[92:93], off offset:32
	s_waitcnt vmcnt(7)
	v_mov_b32_e32 v101, v72
	v_mov_b32_e32 v72, v69
	v_mov_b32_e32 v69, v74
	v_mov_b32_e32 v74, v71
	s_waitcnt vmcnt(5)
	v_mov_b32_e32 v71, v96
	v_mov_b32_e32 v96, v77
	v_mov_b32_e32 v68, v70
	v_mov_b32_e32 v70, v76
	v_mov_b32_e32 v76, v78
	v_pk_mul_f32 v[104:105], v[72:73], v[48:49]
	v_pk_mul_f32 v[106:107], v[74:75], v[44:45]
	v_pk_mul_f32 v[72:73], v[72:73], v[60:61]
	v_pk_mul_f32 v[110:111], v[96:97], v[40:41]
	s_waitcnt vmcnt(3)
	v_mov_b32_e32 v77, v98
	v_mov_b32_e32 v98, v79
	v_pk_mul_f32 v[78:79], v[96:97], v[56:57]
	v_pk_mul_f32 v[74:75], v[74:75], v[58:59]
	v_pk_fma_f32 v[96:97], v[100:101], v[60:61], v[104:105]
	v_pk_fma_f32 v[104:105], v[68:69], v[58:59], v[106:107]
	v_pk_fma_f32 v[48:49], v[100:101], v[48:49], v[72:73] neg_lo:[0,0,1] neg_hi:[0,0,1]
	v_pk_fma_f32 v[72:73], v[70:71], v[56:57], v[110:111]
	v_pk_mul_f32 v[56:57], v[98:99], v[38:39]
	v_pk_fma_f32 v[40:41], v[70:71], v[40:41], v[78:79] neg_lo:[0,0,1] neg_hi:[0,0,1]
	v_pk_mul_f32 v[58:59], v[98:99], v[54:55]
	v_pk_fma_f32 v[44:45], v[68:69], v[44:45], v[74:75] neg_lo:[0,0,1] neg_hi:[0,0,1]
	v_pk_fma_f32 v[74:75], v[76:77], v[54:55], v[56:57]
	v_pk_fma_f32 v[38:39], v[76:77], v[38:39], v[58:59] neg_lo:[0,0,1] neg_hi:[0,0,1]
	v_bfe_u32 v54, v41, 16, 1
	v_bfe_u32 v55, v48, 16, 1
	v_bfe_u32 v56, v49, 16, 1
	v_bfe_u32 v25, v45, 16, 1
	v_bfe_u32 v31, v40, 16, 1
	v_bfe_u32 v57, v105, 16, 1
	v_bfe_u32 v59, v72, 16, 1
	v_bfe_u32 v60, v73, 16, 1
	v_bfe_u32 v69, v39, 16, 1
	v_bfe_u32 v70, v38, 16, 1
	v_add3_u32 v56, v49, v56, s27
	v_add3_u32 v55, v48, v55, s27
	v_add3_u32 v54, v41, v54, s27
	v_bfe_u32 v29, v44, 16, 1
	v_bfe_u32 v61, v96, 16, 1
	v_bfe_u32 v68, v97, 16, 1
	v_add3_u32 v25, v45, v25, s27
	v_add3_u32 v31, v40, v31, s27
	v_bfe_u32 v71, v75, 16, 1
	v_add3_u32 v77, v105, v57, s27
	v_add3_u32 v60, v73, v60, s27
	v_add3_u32 v57, v72, v59, s27
	v_add3_u32 v59, v38, v70, s27
	v_add3_u32 v69, v39, v69, s27
	v_lshrrev_b32_e32 v70, 16, v54
	v_lshrrev_b32_e32 v54, 16, v55
	v_lshrrev_b32_e32 v55, 16, v56
	v_add3_u32 v29, v44, v29, s27
	v_bfe_u32 v76, v74, 16, 1
	v_add3_u32 v68, v97, v68, s27
	v_add3_u32 v61, v96, v61, s27
	v_lshrrev_b32_e32 v31, 16, v31
	v_add3_u32 v71, v75, v71, s27
	v_lshrrev_b32_e32 v78, 16, v57
	v_and_or_b32 v55, v25, s25, v55
	v_and_or_b32 v57, v69, s25, v70
	v_lshrrev_b32_e32 v25, 16, v60
	v_add3_u32 v76, v74, v76, s27
	v_and_or_b32 v54, v29, s25, v54
	v_and_or_b32 v56, v59, s25, v31
	v_lshrrev_b32_e32 v29, 16, v61
	v_lshrrev_b32_e32 v31, 16, v68
	v_and_or_b32 v61, v71, s25, v25
	v_and_or_b32 v59, v77, s25, v31
	v_and_or_b32 v60, v76, s25, v78
	v_bfe_u32 v58, v104, 16, 1
	v_add3_u32 v58, v104, v58, s27
	v_pk_mul_f32 v[102:103], v[82:83], v[42:43]
	v_and_or_b32 v58, v58, s25, v29
	v_mov_b32_e32 v29, v42
	s_waitcnt vmcnt(2)
	v_mov_b32_e32 v68, v84
	s_waitcnt vmcnt(1)
	v_mov_b32_e32 v69, v88
	v_mov_b32_e32 v88, v85
	v_pk_mul_f32 v[70:71], v[88:89], v[36:37]
	v_mov_b32_e32 v31, v43
	v_pk_fma_f32 v[76:77], v[68:69], v[52:53], v[70:71]
	v_mov_b32_e32 v71, v90
	v_mov_b32_e32 v90, v87
	v_mov_b32_e32 v70, v86
	v_pk_mul_f32 v[78:79], v[90:91], v[34:35]
	v_pk_mul_f32 v[52:53], v[88:89], v[52:53]
	v_pk_fma_f32 v[78:79], v[70:71], v[50:51], v[78:79]
	v_pk_mul_f32 v[50:51], v[90:91], v[50:51]
	v_pk_fma_f32 v[36:37], v[68:69], v[36:37], v[52:53] neg_lo:[0,0,1] neg_hi:[0,0,1]
	v_pk_fma_f32 v[34:35], v[70:71], v[34:35], v[50:51] neg_lo:[0,0,1] neg_hi:[0,0,1]
	v_mov_b32_e32 v51, v80
	s_waitcnt vmcnt(0)
	v_mov_b32_e32 v80, v93
	v_mov_b32_e32 v50, v92
	v_pk_mul_f32 v[52:53], v[80:81], v[32:33]
	v_mov_b32_e32 v71, v82
	v_mov_b32_e32 v82, v95
	v_pk_fma_f32 v[84:85], v[50:51], v[46:47], v[52:53]
	v_mul_f32_e32 v52, v94, v28
	v_mov_b32_e32 v70, v94
	v_pk_mul_f32 v[28:29], v[82:83], v[28:29]
	v_mul_f32_e32 v68, v95, v30
	v_pk_fma_f32 v[30:31], v[70:71], v[30:31], v[28:29] neg_lo:[0,0,1] neg_hi:[0,0,1]
	v_pk_mul_f32 v[28:29], v[80:81], v[46:47]
	v_mov_b32_e32 v53, v102
	v_pk_fma_f32 v[32:33], v[50:51], v[32:33], v[28:29] neg_lo:[0,0,1] neg_hi:[0,0,1]
	v_mov_b32_e32 v69, v103
	v_bfe_u32 v47, v32, 16, 1
	v_bfe_u32 v50, v33, 16, 1
	v_bfe_u32 v51, v36, 16, 1
	v_pk_add_f32 v[28:29], v[52:53], v[68:69]
	v_bfe_u32 v25, v31, 16, 1
	v_bfe_u32 v42, v30, 16, 1
	v_bfe_u32 v46, v34, 16, 1
	v_bfe_u32 v52, v37, 16, 1
	v_add3_u32 v50, v33, v50, s27
	v_add3_u32 v47, v32, v47, s27
	v_add3_u32 v51, v36, v51, s27
	v_bfe_u32 v43, v35, 16, 1
	v_add3_u32 v42, v30, v42, s27
	v_add3_u32 v25, v31, v25, s27
	v_add3_u32 v46, v34, v46, s27
	v_add3_u32 v52, v37, v52, s27
	v_lshrrev_b32_e32 v47, 16, v47
	v_lshrrev_b32_e32 v50, 16, v50
	v_lshrrev_b32_e32 v68, 16, v51
	v_add3_u32 v43, v35, v43, s27
	v_lshrrev_b32_e32 v51, 16, v52
	v_and_or_b32 v53, v25, s25, v50
	v_and_or_b32 v52, v42, s25, v47
	v_and_or_b32 v50, v46, s25, v68
	v_bfe_u32 v47, v84, 16, 1
	v_bfe_u32 v68, v85, 16, 1
	v_bfe_u32 v69, v76, 16, 1
	v_bfe_u32 v70, v77, 16, 1
	v_and_or_b32 v51, v43, s25, v51
	v_bfe_u32 v25, v29, 16, 1
	v_bfe_u32 v42, v28, 16, 1
	v_bfe_u32 v43, v79, 16, 1
	v_bfe_u32 v46, v78, 16, 1
	v_add3_u32 v68, v85, v68, s27
	v_add3_u32 v47, v84, v47, s27
	v_add3_u32 v70, v77, v70, s27
	v_add3_u32 v69, v76, v69, s27
	v_add3_u32 v46, v78, v46, s27
	v_add3_u32 v43, v79, v43, s27
	v_add3_u32 v42, v28, v42, s27
	v_add3_u32 v25, v29, v25, s27
	v_lshrrev_b32_e32 v47, 16, v47
	v_lshrrev_b32_e32 v68, 16, v68
	v_lshrrev_b32_e32 v80, 16, v69
	v_lshrrev_b32_e32 v69, 16, v70
	v_and_or_b32 v71, v25, s25, v68
	v_and_or_b32 v70, v42, s25, v47
	v_and_or_b32 v69, v43, s25, v69
	v_and_or_b32 v68, v46, s25, v80
	global_store_dwordx4 v[22:23], v[54:57], off offset:3136
	global_store_dwordx4 v[22:23], v[58:61], off offset:3152
	global_store_dwordx4 v[22:23], v[50:53], off offset:3168
	global_store_dwordx4 v[22:23], v[68:71], off offset:3184
	v_mov_b32_e32 v60, v96
	v_mov_b32_e32 v58, v104
	v_mov_b32_e32 v61, v97
	v_mov_b32_e32 v59, v105
	v_mov_b32_e32 v56, v72
	v_mov_b32_e32 v54, v74
	v_mov_b32_e32 v57, v73
	v_mov_b32_e32 v55, v75
	v_mov_b32_e32 v43, v31
	v_mov_b32_e32 v52, v76
	v_mov_b32_e32 v50, v78
	v_mov_b32_e32 v53, v77
	v_mov_b32_e32 v51, v79
	v_mov_b32_e32 v46, v84
	v_mov_b32_e32 v47, v85
	v_mov_b32_e32 v42, v29

.LBB0_925:
	s_waitcnt lgkmcnt(1)
	v_mfma_f32_16x16x32_bf16 v[172:175], v[130:133], v[34:37], v[2:5]
	ds_read_b128 v[184:187], v247 offset:2048
	v_mfma_f32_16x16x32_bf16 v[180:183], v[130:133], v[38:41], v[10:13]
	ds_read_b128 v[130:133], v247
	s_nop 2
	s_nop 1
	v_exp_f32_e32 v200, v172
	v_exp_f32_e32 v201, v175
	s_waitcnt lgkmcnt(2)
	v_mfma_f32_16x16x32_bf16 v[176:179], v[168:171], v[34:37], v[2:5]
	v_exp_f32_e32 v180, v180
	ds_read_b64 v[216:217], v248 offset:37376
	ds_read_b64 v[218:219], v248 offset:37408
	v_mfma_f32_16x16x32_bf16 v[168:171], v[168:171], v[38:41], v[10:13]
	ds_read_b64 v[220:221], v248 offset:39680
	ds_read_b64 v[222:223], v248 offset:39712
	s_nop 2
	v_exp_f32_e32 v204, v176
	v_exp_f32_e32 v176, v173
	s_waitcnt lgkmcnt(4)
	v_mfma_f32_16x16x32_bf16 v[188:191], v[130:133], v[42:45], v[6:9]
	v_exp_f32_e32 v205, v177
	v_exp_f32_e32 v213, v168
	v_exp_f32_e32 v168, v181
	v_mfma_f32_16x16x32_bf16 v[196:199], v[130:133], v[46:49], v[14:17]
	ds_read_b128 v[130:133], v246 offset:4096
	v_exp_f32_e32 v181, v169
	v_exp_f32_e32 v169, v182
	v_exp_f32_e32 v182, v170
	v_exp_f32_e32 v170, v183
	v_exp_f32_e32 v171, v171
	v_exp_f32_e32 v177, v174
	v_cvt_pk_bf16_f32 v168, v180, v168
	v_cvt_pk_bf16_f32 v169, v169, v170
	v_cvt_pk_bf16_f32 v170, v213, v181
	v_cvt_pk_bf16_f32 v171, v182, v171
	ds_read_b64 v[180:181], v248 offset:32768
	ds_read_b64 v[182:183], v248 offset:32800
	ds_read_b64 v[212:213], v248 offset:35072
	ds_read_b64 v[214:215], v248 offset:35104
	ds_read_b128 v[172:175], v246 offset:6144
	v_cvt_pk_bf16_f32 v176, v200, v176
	v_cvt_pk_bf16_f32 v177, v177, v201
	s_waitcnt lgkmcnt(5)
	v_mfma_f32_16x16x32_bf16 v[200:203], v[130:133], v[34:37], v[2:5]
	v_exp_f32_e32 v231, v190
	v_exp_f32_e32 v206, v178
	v_exp_f32_e32 v179, v179
	v_mfma_f32_16x16x32_bf16 v[208:211], v[130:133], v[38:41], v[10:13]
	v_exp_f32_e32 v188, v188
	v_mfma_f32_16x16x32_bf16 v[192:195], v[184:187], v[42:45], v[6:9]
	v_exp_f32_e32 v189, v189
	v_exp_f32_e32 v196, v196
	v_cvt_pk_bf16_f32 v178, v204, v205
	v_mfma_f32_16x16x32_bf16 v[184:187], v[184:187], v[46:49], v[14:17]
	v_cvt_pk_bf16_f32 v179, v206, v179
	s_nop 2
	v_exp_f32_e32 v192, v192
	v_exp_f32_e32 v193, v193
	v_mfma_f32_16x16x32_bf16 v[86:89], v[240:243], v[168:171], v[86:89]
	v_exp_f32_e32 v194, v194
	v_exp_f32_e32 v187, v187
	ds_read_b128 v[224:227], v247 offset:4096
	s_waitcnt lgkmcnt(4)
	v_mfma_f32_16x16x32_bf16 v[78:81], v[180:183], v[168:171], v[78:81]
	s_add_i32 s38, s38, 2
	s_addk_i32 s12, 0x80
	v_lshl_add_u64 v[148:149], v[148:149], 0, s[16:17]
	s_waitcnt lgkmcnt(2)
	v_mfma_f32_16x16x32_bf16 v[74:77], v[212:215], v[168:171], v[74:77]
	s_and_b64 vcc, exec, s[0:1]
	v_mfma_f32_16x16x32_bf16 v[70:73], v[216:219], v[168:171], v[70:73]
	v_mfma_f32_16x16x32_bf16 v[62:65], v[220:223], v[168:171], v[62:65]
	v_exp_f32_e32 v169, v191
	v_exp_f32_e32 v171, v195
	v_cvt_pk_bf16_f32 v168, v188, v189
	s_waitcnt lgkmcnt(1)
	v_mfma_f32_16x16x32_bf16 v[204:207], v[172:175], v[34:37], v[2:5]
	v_cvt_pk_bf16_f32 v169, v231, v169
	v_exp_f32_e32 v231, v184
	v_exp_f32_e32 v184, v197
	v_exp_f32_e32 v197, v185
	v_exp_f32_e32 v185, v198
	v_exp_f32_e32 v198, v186
	v_exp_f32_e32 v186, v199
	v_cvt_pk_bf16_f32 v170, v192, v193
	v_cvt_pk_bf16_f32 v171, v194, v171
	v_cvt_pk_bf16_f32 v184, v196, v184
	v_cvt_pk_bf16_f32 v185, v185, v186
	v_cvt_pk_bf16_f32 v186, v231, v197
	v_cvt_pk_bf16_f32 v187, v198, v187
	v_mfma_f32_16x16x32_bf16 v[172:175], v[172:175], v[38:41], v[10:13]
	v_exp_f32_e32 v196, v200
	v_exp_f32_e32 v197, v204
	v_exp_f32_e32 v198, v201
	v_mfma_f32_16x16x32_bf16 v[122:125], v[180:183], v[176:179], v[122:125]
	v_exp_f32_e32 v200, v207
	v_exp_f32_e32 v199, v203
	v_mfma_f32_16x16x32_bf16 v[102:105], v[180:183], v[168:171], v[102:105]
	v_mfma_f32_16x16x32_bf16 v[58:61], v[180:183], v[184:187], v[58:61]
	v_exp_f32_e32 v182, v205
	v_exp_f32_e32 v183, v206
	v_exp_f32_e32 v181, v202
	v_mfma_f32_16x16x32_bf16 v[126:129], v[240:243], v[176:179], v[126:129]
	v_cvt_pk_bf16_f32 v180, v196, v198
	v_cvt_pk_bf16_f32 v182, v197, v182
	v_cvt_pk_bf16_f32 v183, v183, v200
	v_mfma_f32_16x16x32_bf16 v[118:121], v[212:215], v[176:179], v[118:121]
	v_exp_f32_e32 v196, v208
	v_exp_f32_e32 v197, v172
	v_exp_f32_e32 v172, v209
	v_mfma_f32_16x16x32_bf16 v[110:113], v[216:219], v[176:179], v[110:113]
	v_exp_f32_e32 v200, v174
	v_cvt_pk_bf16_f32 v181, v181, v199
	v_exp_f32_e32 v198, v173
	v_mfma_f32_16x16x32_bf16 v[106:109], v[220:223], v[176:179], v[106:109]
	ds_read_b128 v[176:179], v247 offset:6144
	v_exp_f32_e32 v199, v210
	ds_read_b128 v[204:207], v246 offset:14336
	v_mfma_f32_16x16x32_bf16 v[114:117], v[240:243], v[168:171], v[114:117]
	v_mfma_f32_16x16x32_bf16 v[98:101], v[212:215], v[168:171], v[98:101]
	v_mfma_f32_16x16x32_bf16 v[94:97], v[216:219], v[168:171], v[94:97]
	v_mfma_f32_16x16x32_bf16 v[90:93], v[220:223], v[168:171], v[90:93]
	v_exp_f32_e32 v171, v175
	v_exp_f32_e32 v169, v211
	v_cvt_pk_bf16_f32 v168, v196, v172
	v_mfma_f32_16x16x32_bf16 v[82:85], v[240:243], v[184:187], v[82:85]
	v_cvt_pk_bf16_f32 v171, v200, v171
	v_mfma_f32_16x16x32_bf16 v[54:57], v[212:215], v[184:187], v[54:57]
	ds_read_b64 v[172:173], v248 offset:32832
	ds_read_b64 v[174:175], v248 offset:32864
	v_cvt_pk_bf16_f32 v169, v199, v169
	v_mfma_f32_16x16x32_bf16 v[50:53], v[216:219], v[184:187], v[50:53]
	v_cvt_pk_bf16_f32 v170, v197, v198
	ds_read_b64 v[196:197], v248 offset:37440
	ds_read_b64 v[198:199], v248 offset:37472
	ds_read_b64 v[200:201], v248 offset:39744
	ds_read_b64 v[202:203], v248 offset:39776
	v_mfma_f32_16x16x32_bf16 v[66:69], v[220:223], v[184:187], v[66:69]
	ds_read_b64 v[184:185], v248 offset:35136
	ds_read_b64 v[186:187], v248 offset:35168
	s_waitcnt lgkmcnt(10)
	v_mfma_f32_16x16x32_bf16 v[188:191], v[224:227], v[42:45], v[6:9]
	ds_read_b64 v[216:217], v248 offset:46592
	ds_read_b64 v[218:219], v248 offset:46624
	s_waitcnt lgkmcnt(11)
	v_mfma_f32_16x16x32_bf16 v[192:195], v[176:179], v[42:45], v[6:9]
	ds_read_b64 v[220:221], v248 offset:48896
	ds_read_b64 v[222:223], v248 offset:48928
	s_nop 1
	v_exp_f32_e32 v188, v188
	v_exp_f32_e32 v189, v189
	v_mfma_f32_16x16x32_bf16 v[224:227], v[224:227], v[46:49], v[14:17]
	v_exp_f32_e32 v190, v190
	s_nop 0
	v_exp_f32_e32 v192, v192
	v_exp_f32_e32 v193, v193
	v_mfma_f32_16x16x32_bf16 v[176:179], v[176:179], v[46:49], v[14:17]
	v_exp_f32_e32 v191, v191
	v_exp_f32_e32 v194, v194
	v_exp_f32_e32 v195, v195
	v_mfma_f32_16x16x32_bf16 v[126:129], v[240:243], v[180:183], v[126:129]
	v_cvt_pk_bf16_f32 v188, v188, v189
	v_cvt_pk_bf16_f32 v189, v190, v191
	v_cvt_pk_bf16_f32 v190, v192, v193
	v_mfma_f32_16x16x32_bf16 v[86:89], v[240:243], v[168:171], v[86:89]
	v_exp_f32_e32 v192, v224
	v_exp_f32_e32 v176, v176
	v_exp_f32_e32 v193, v225
	s_waitcnt lgkmcnt(10)
	v_mfma_f32_16x16x32_bf16 v[122:125], v[172:175], v[180:183], v[122:125]
	v_exp_f32_e32 v177, v177
	v_exp_f32_e32 v178, v178
	v_cvt_pk_bf16_f32 v191, v194, v195
	v_mfma_f32_16x16x32_bf16 v[78:81], v[172:175], v[168:171], v[78:81]
	s_waitcnt lgkmcnt(4)
	v_mfma_f32_16x16x32_bf16 v[118:121], v[184:187], v[180:183], v[118:121]
	v_mfma_f32_16x16x32_bf16 v[74:77], v[184:187], v[168:171], v[74:77]
	v_mfma_f32_16x16x32_bf16 v[110:113], v[196:199], v[180:183], v[110:113]
	v_mfma_f32_16x16x32_bf16 v[70:73], v[196:199], v[168:171], v[70:73]
	v_mfma_f32_16x16x32_bf16 v[106:109], v[200:203], v[180:183], v[106:109]
	v_exp_f32_e32 v180, v226
	v_mfma_f32_16x16x32_bf16 v[62:65], v[200:203], v[168:171], v[62:65]
	v_exp_f32_e32 v169, v227
	v_exp_f32_e32 v171, v179
	v_cvt_pk_bf16_f32 v168, v192, v193
	v_cvt_pk_bf16_f32 v170, v176, v177
	v_cvt_pk_bf16_f32 v169, v180, v169
	v_cvt_pk_bf16_f32 v171, v178, v171
	v_mfma_f32_16x16x32_bf16 v[102:105], v[172:175], v[188:191], v[102:105]
	ds_read_b128 v[224:227], v247 offset:12288
	v_mfma_f32_16x16x32_bf16 v[82:85], v[240:243], v[168:171], v[82:85]
	v_mfma_f32_16x16x32_bf16 v[58:61], v[172:175], v[168:171], v[58:61]
	ds_read_b128 v[172:175], v246 offset:8192
	v_mfma_f32_16x16x32_bf16 v[54:57], v[184:187], v[168:171], v[54:57]
	v_mfma_f32_16x16x32_bf16 v[50:53], v[196:199], v[168:171], v[50:53]
	v_mfma_f32_16x16x32_bf16 v[66:69], v[200:203], v[168:171], v[66:69]
	ds_read_b128 v[168:171], v246 offset:10240
	s_waitcnt lgkmcnt(1)
	v_mfma_f32_16x16x32_bf16 v[176:179], v[172:175], v[34:37], v[2:5]
	s_waitcnt lgkmcnt(0)
	v_mfma_f32_16x16x32_bf16 v[180:183], v[168:171], v[34:37], v[2:5]
	s_nop 5
	v_exp_f32_e32 v176, v176
	v_mfma_f32_16x16x32_bf16 v[172:175], v[172:175], v[38:41], v[10:13]
	v_exp_f32_e32 v208, v180
	v_exp_f32_e32 v177, v177
	v_exp_f32_e32 v209, v181
	v_mfma_f32_16x16x32_bf16 v[168:171], v[168:171], v[38:41], v[10:13]
	v_exp_f32_e32 v178, v178
	s_nop 2
	v_exp_f32_e32 v172, v172
	v_exp_f32_e32 v210, v182
	v_mfma_f32_16x16x32_bf16 v[114:117], v[240:243], v[188:191], v[114:117]
	v_exp_f32_e32 v179, v179
	v_exp_f32_e32 v213, v168
	v_exp_f32_e32 v168, v173
	v_exp_f32_e32 v173, v169
	v_exp_f32_e32 v169, v174
	v_exp_f32_e32 v174, v170
	v_exp_f32_e32 v170, v175
	v_exp_f32_e32 v171, v171
	v_mfma_f32_16x16x32_bf16 v[98:101], v[184:187], v[188:191], v[98:101]
	ds_read_b128 v[184:187], v247 offset:8192
	v_cvt_pk_bf16_f32 v168, v172, v168
	v_cvt_pk_bf16_f32 v169, v169, v170
	v_mfma_f32_16x16x32_bf16 v[94:97], v[196:199], v[188:191], v[94:97]
	v_cvt_pk_bf16_f32 v170, v213, v173
	v_cvt_pk_bf16_f32 v171, v174, v171
	ds_read_b64 v[172:173], v248 offset:41984
	ds_read_b64 v[174:175], v248 offset:42016
	v_mfma_f32_16x16x32_bf16 v[90:93], v[200:203], v[188:191], v[90:93]
	ds_read_b128 v[188:191], v247 offset:10240
	ds_read_b64 v[212:213], v248 offset:44288
	ds_read_b64 v[214:215], v248 offset:44320
	ds_read_b128 v[200:203], v246 offset:12288
	s_waitcnt lgkmcnt(6)
	v_mfma_f32_16x16x32_bf16 v[192:195], v[184:187], v[42:45], v[6:9]
	v_exp_f32_e32 v211, v183
	v_cvt_pk_bf16_f32 v176, v176, v177
	v_cvt_pk_bf16_f32 v177, v178, v179
	s_waitcnt lgkmcnt(3)
	v_mfma_f32_16x16x32_bf16 v[196:199], v[188:191], v[42:45], v[6:9]
	v_cvt_pk_bf16_f32 v178, v208, v209
	s_nop 1
	v_exp_f32_e32 v192, v192
	v_exp_f32_e32 v193, v193
	v_mfma_f32_16x16x32_bf16 v[184:187], v[184:187], v[46:49], v[14:17]
	s_nop 1
	v_exp_f32_e32 v196, v196
	v_exp_f32_e32 v197, v197
	v_exp_f32_e32 v228, v194
	v_mfma_f32_16x16x32_bf16 v[188:191], v[188:191], v[46:49], v[14:17]
	v_exp_f32_e32 v198, v198
	s_nop 0
	v_exp_f32_e32 v184, v184
	v_exp_f32_e32 v185, v185
	v_mfma_f32_16x16x32_bf16 v[86:89], v[240:243], v[168:171], v[86:89]
	v_exp_f32_e32 v186, v186
	s_nop 1
	v_exp_f32_e32 v188, v188
	v_exp_f32_e32 v189, v189
	v_mfma_f32_16x16x32_bf16 v[78:81], v[172:175], v[168:171], v[78:81]
	v_exp_f32_e32 v190, v190
	v_exp_f32_e32 v187, v187
	v_exp_f32_e32 v191, v191
	s_waitcnt lgkmcnt(1)
	v_mfma_f32_16x16x32_bf16 v[74:77], v[212:215], v[168:171], v[74:77]
	v_cvt_pk_bf16_f32 v179, v210, v211
	v_cvt_pk_bf16_f32 v184, v184, v185
	v_cvt_pk_bf16_f32 v185, v186, v187
	v_mfma_f32_16x16x32_bf16 v[70:73], v[216:219], v[168:171], v[70:73]
	v_cvt_pk_bf16_f32 v186, v188, v189
	v_cvt_pk_bf16_f32 v187, v190, v191
	v_mfma_f32_16x16x32_bf16 v[62:65], v[220:223], v[168:171], v[62:65]
	v_exp_f32_e32 v169, v195
	v_exp_f32_e32 v171, v199
	v_cvt_pk_bf16_f32 v168, v192, v193
	s_waitcnt lgkmcnt(0)
	v_mfma_f32_16x16x32_bf16 v[180:183], v[200:203], v[34:37], v[2:5]
	v_cvt_pk_bf16_f32 v169, v228, v169
	v_cvt_pk_bf16_f32 v170, v196, v197
	v_cvt_pk_bf16_f32 v171, v198, v171
	v_mfma_f32_16x16x32_bf16 v[208:211], v[204:207], v[34:37], v[2:5]
	v_mfma_f32_16x16x32_bf16 v[200:203], v[200:203], v[38:41], v[10:13]
	s_nop 2
	v_exp_f32_e32 v180, v180
	s_nop 2
	v_exp_f32_e32 v188, v208
	v_mfma_f32_16x16x32_bf16 v[204:207], v[204:207], v[38:41], v[10:13]
	v_mfma_f32_16x16x32_bf16 v[122:125], v[172:175], v[176:179], v[122:125]
	v_exp_f32_e32 v190, v202
	s_nop 5
	v_exp_f32_e32 v189, v205
	v_exp_f32_e32 v191, v207
	v_mfma_f32_16x16x32_bf16 v[102:105], v[172:175], v[168:171], v[102:105]
	v_mfma_f32_16x16x32_bf16 v[58:61], v[172:175], v[184:187], v[58:61]
	v_exp_f32_e32 v172, v181
	v_exp_f32_e32 v174, v209
	v_exp_f32_e32 v173, v182
	v_exp_f32_e32 v181, v183
	v_mfma_f32_16x16x32_bf16 v[126:129], v[240:243], v[176:179], v[126:129]
	v_exp_f32_e32 v175, v210
	v_exp_f32_e32 v182, v211
	v_cvt_pk_bf16_f32 v172, v180, v172
	v_mfma_f32_16x16x32_bf16 v[118:121], v[212:215], v[176:179], v[118:121]
	v_cvt_pk_bf16_f32 v173, v173, v181
	v_cvt_pk_bf16_f32 v174, v188, v174
	v_exp_f32_e32 v180, v200
	v_mfma_f32_16x16x32_bf16 v[110:113], v[216:219], v[176:179], v[110:113]
	v_exp_f32_e32 v188, v204
	v_exp_f32_e32 v181, v201
	v_cvt_pk_bf16_f32 v175, v175, v182
	v_mfma_f32_16x16x32_bf16 v[106:109], v[220:223], v[176:179], v[106:109]
	ds_read_b128 v[176:179], v247 offset:14336
	v_mfma_f32_16x16x32_bf16 v[114:117], v[240:243], v[168:171], v[114:117]
	v_mfma_f32_16x16x32_bf16 v[98:101], v[212:215], v[168:171], v[98:101]
	v_mfma_f32_16x16x32_bf16 v[94:97], v[216:219], v[168:171], v[94:97]
	v_mfma_f32_16x16x32_bf16 v[90:93], v[220:223], v[168:171], v[90:93]
	v_exp_f32_e32 v171, v206
	v_exp_f32_e32 v169, v203
	v_mfma_f32_16x16x32_bf16 v[82:85], v[240:243], v[184:187], v[82:85]
	v_cvt_pk_bf16_f32 v168, v180, v181
	ds_read_b64 v[180:181], v248 offset:42048
	ds_read_b64 v[182:183], v248 offset:42080
	v_cvt_pk_bf16_f32 v170, v188, v189
	v_mfma_f32_16x16x32_bf16 v[54:57], v[212:215], v[184:187], v[54:57]
	v_cvt_pk_bf16_f32 v169, v190, v169
	v_cvt_pk_bf16_f32 v171, v171, v191
	v_mfma_f32_16x16x32_bf16 v[50:53], v[216:219], v[184:187], v[50:53]
	ds_read_b64 v[188:189], v248 offset:46656
	ds_read_b64 v[190:191], v248 offset:46688
	ds_read_b64 v[200:201], v248 offset:48960
	ds_read_b64 v[202:203], v248 offset:48992
	v_mfma_f32_16x16x32_bf16 v[66:69], v[220:223], v[184:187], v[66:69]
	ds_read_b64 v[184:185], v248 offset:44352
	ds_read_b64 v[186:187], v248 offset:44384
	v_mfma_f32_16x16x32_bf16 v[192:195], v[224:227], v[42:45], v[6:9]
	s_waitcnt lgkmcnt(8)
	v_mfma_f32_16x16x32_bf16 v[196:199], v[176:179], v[42:45], v[6:9]
	v_mfma_f32_16x16x32_bf16 v[224:227], v[224:227], v[46:49], v[14:17]
	s_nop 4
	v_exp_f32_e32 v192, v192
	s_nop 0
	v_exp_f32_e32 v196, v196
	v_exp_f32_e32 v193, v193
	v_mfma_f32_16x16x32_bf16 v[176:179], v[176:179], v[46:49], v[14:17]
	v_exp_f32_e32 v197, v197
	v_exp_f32_e32 v194, v194
	v_exp_f32_e32 v195, v195
	v_mfma_f32_16x16x32_bf16 v[126:129], v[240:243], v[172:175], v[126:129]
	v_exp_f32_e32 v198, v198
	v_exp_f32_e32 v199, v199
	v_cvt_pk_bf16_f32 v192, v192, v193
	v_mfma_f32_16x16x32_bf16 v[86:89], v[240:243], v[168:171], v[86:89]
	v_cvt_pk_bf16_f32 v193, v194, v195
	v_cvt_pk_bf16_f32 v194, v196, v197
	v_exp_f32_e32 v196, v224
	s_waitcnt lgkmcnt(6)
	v_mfma_f32_16x16x32_bf16 v[122:125], v[180:183], v[172:175], v[122:125]
	v_exp_f32_e32 v176, v176
	v_exp_f32_e32 v197, v225
	v_cvt_pk_bf16_f32 v195, v198, v199
	v_mfma_f32_16x16x32_bf16 v[78:81], v[180:183], v[168:171], v[78:81]
	s_waitcnt lgkmcnt(0)
	v_mfma_f32_16x16x32_bf16 v[118:121], v[184:187], v[172:175], v[118:121]
	v_mfma_f32_16x16x32_bf16 v[74:77], v[184:187], v[168:171], v[74:77]
	v_mfma_f32_16x16x32_bf16 v[110:113], v[188:191], v[172:175], v[110:113]
	v_mfma_f32_16x16x32_bf16 v[70:73], v[188:191], v[168:171], v[70:73]
	v_mfma_f32_16x16x32_bf16 v[106:109], v[200:203], v[172:175], v[106:109]
	v_exp_f32_e32 v172, v177
	v_exp_f32_e32 v173, v226
	v_exp_f32_e32 v174, v178
	v_mfma_f32_16x16x32_bf16 v[62:65], v[200:203], v[168:171], v[62:65]
	v_exp_f32_e32 v169, v227
	v_exp_f32_e32 v171, v179
	v_cvt_pk_bf16_f32 v168, v196, v197
	v_cvt_pk_bf16_f32 v170, v176, v172
	v_cvt_pk_bf16_f32 v169, v173, v169
	v_cvt_pk_bf16_f32 v171, v174, v171
	v_mfma_f32_16x16x32_bf16 v[114:117], v[240:243], v[192:195], v[114:117]
	s_nop 0
	v_mfma_f32_16x16x32_bf16 v[82:85], v[240:243], v[168:171], v[82:85]
	v_mfma_f32_16x16x32_bf16 v[102:105], v[180:183], v[192:195], v[102:105]
	v_mfma_f32_16x16x32_bf16 v[58:61], v[180:183], v[168:171], v[58:61]
	v_mfma_f32_16x16x32_bf16 v[98:101], v[184:187], v[192:195], v[98:101]
	v_mfma_f32_16x16x32_bf16 v[54:57], v[184:187], v[168:171], v[54:57]
	v_mfma_f32_16x16x32_bf16 v[94:97], v[188:191], v[192:195], v[94:97]
	v_mfma_f32_16x16x32_bf16 v[50:53], v[188:191], v[168:171], v[50:53]
	v_mfma_f32_16x16x32_bf16 v[90:93], v[200:203], v[192:195], v[90:93]
	v_mfma_f32_16x16x32_bf16 v[66:69], v[200:203], v[168:171], v[66:69]
	v_xor_b32_e32 v246, 0x4000, v246
	v_xor_b32_e32 v247, 0x4000, v247
	v_xor_b32_e32 v244, 0x4000, v244
	v_add_u32_e32 v248, s99, v248
	v_add_u32_e32 v245, s99, v245
	s_sub_i32 s99, 0, s99
	s_cbranch_vccnz .LBB0_928
.LBB0_926:
	s_and_b32 s0, s12, 0x80
	s_lshl_b32 s1, s0, 7
	s_add_i32 s39, s1, 0
	s_lshl_b32 s0, s0, 4
	s_add_i32 s2, s39, s0
	s_cmpk_gt_u32 s38, 0x101
	s_cselect_b64 s[0:1], -1, 0
	s_and_b64 vcc, exec, s[0:1]
	s_waitcnt vmcnt(3)
	ds_write_b128 v244, v[18:21]
	s_waitcnt vmcnt(1)
	ds_write_b128 v245, v[22:25] offset:32768
	s_waitcnt vmcnt(1)
	ds_write_b128 v244, v[26:29] offset:8192
	s_waitcnt vmcnt(0)
	ds_write_b128 v245, v[30:33] offset:41984
	s_waitcnt lgkmcnt(0)
	s_barrier
	ds_read_b128 v[130:133], v246
	ds_read_b128 v[168:171], v246 offset:2048
	s_cbranch_vccnz .LBB0_925
	s_add_i32 s40, s35, s12
	s_add_i32 s41, s40, 0xffffff80
	s_sub_i32 s42, s40, 64
	s_cmp_eq_u32 s12, 0
	s_cselect_b32 s40, s36, s41
	v_add_u32_e32 v18, s40, v161
	v_mad_i64_i32 v[18:19], s[40:41], v18, s21, v[146:147]
	s_cselect_b32 s40, s37, s42
	s_nop 0
	v_add_u32_e32 v20, s40, v161
	v_mad_i64_i32 v[22:23], s[40:41], v20, s21, v[146:147]
	global_load_dwordx4 v[18:21], v[18:19], off offset:3648
	s_nop 0
	global_load_dwordx4 v[26:29], v[22:23], off offset:3648
	s_nop 0
	global_load_dwordx4 v[22:25], v[148:149], off
	global_load_dwordx4 v[30:33], v[148:149], off offset:128
	s_branch .LBB0_925

.LBB0_1010:
	s_and_b32 s0, s3, 3
	v_add_u32_e32 v3, s31, v2
	v_mad_i64_i32 v[52:53], s[4:5], v3, s27, v[138:139]
	s_lshl_b32 s18, s0, 7
	s_mov_b32 s19, s15
	v_lshl_add_u64 v[4:5], v[52:53], 0, s[18:19]
	global_load_dwordx4 v[20:23], v[4:5], off offset:512
	global_load_dwordx4 v[24:27], v[4:5], off offset:528
	global_load_dwordx4 v[28:31], v[4:5], off offset:544
	global_load_dwordx4 v[32:35], v[4:5], off offset:560
	global_load_dwordx4 v[36:39], v[4:5], off offset:576
	global_load_dwordx4 v[40:43], v[4:5], off offset:592
	global_load_dwordx4 v[44:47], v[4:5], off offset:608
	global_load_dwordx4 v[48:51], v[4:5], off offset:624
	s_lshl_b32 s14, s0, 6
	v_lshl_add_u32 v71, v2, 1, s17
	s_cmp_gt_i32 s33, 3
	v_ashrrev_i32_e32 v70, 4, v2
	s_cselect_b32 s1, 0x107, 3
	v_ashrrev_i32_e32 v3, 31, v2
	v_add_u32_e32 v54, 0x400, v2
	v_add_u32_e32 v56, 0x440, v2
	v_add_u32_e32 v58, 0x480, v2
	v_add_u32_e32 v60, 0x4c0, v2
	v_add_u32_e32 v62, 0x500, v2
	v_add_u32_e32 v64, 0x540, v2
	v_add_u32_e32 v66, 0x580, v2
	v_add_u32_e32 v68, 0x5c0, v2
	v_add_u32_e32 v18, 0x600, v2
	v_add_u32_e32 v14, 0x640, v2
	v_add_u32_e32 v16, 0x680, v2
	v_add_u32_e32 v12, 0x6c0, v2
	v_add_u32_e32 v10, 0x700, v2
	v_add_u32_e32 v8, 0x740, v2
	v_add_u32_e32 v4, 0x780, v2
	v_add_u32_e32 v6, 0x7c0, v2
	s_sub_i32 s35, s1, s33
	s_lshl_b32 s1, s2, 3
	v_lshlrev_b32_e32 v120, 2, v70
	v_and_b32_e32 v140, 15, v2
	v_ashrrev_i32_e32 v55, 31, v54
	v_ashrrev_i32_e32 v57, 31, v56
	v_ashrrev_i32_e32 v59, 31, v58
	v_ashrrev_i32_e32 v61, 31, v60
	v_ashrrev_i32_e32 v63, 31, v62
	v_ashrrev_i32_e32 v65, 31, v64
	v_ashrrev_i32_e32 v67, 31, v66
	v_ashrrev_i32_e32 v69, 31, v68
	v_ashrrev_i32_e32 v19, 31, v18
	v_ashrrev_i32_e32 v15, 31, v14
	v_ashrrev_i32_e32 v17, 31, v16
	v_ashrrev_i32_e32 v13, 31, v12
	v_ashrrev_i32_e32 v11, 31, v10
	v_ashrrev_i32_e32 v9, 31, v8
	v_ashrrev_i32_e32 v5, 31, v4
	v_ashrrev_i32_e32 v7, 31, v6
	s_or_b32 s36, s1, s0
	s_ashr_i32 s34, s33, 31
	v_lshlrev_b64 v[94:95], 7, v[2:3]
	v_lshl_add_u64 v[110:111], v[52:53], 0, s[14:15]
	v_lshl_add_u32 v142, v2, 6, s17
	v_ashrrev_i32_e32 v121, 31, v120
	s_waitcnt vmcnt(7)
	ds_write_b16 v71, v20 offset:8192
	ds_write_b16_d16_hi v71, v20 offset:8320
	ds_write_b16 v71, v21 offset:8448
	ds_write_b16_d16_hi v71, v21 offset:8576
	ds_write_b16 v71, v22 offset:8704
	ds_write_b16_d16_hi v71, v22 offset:8832
	ds_write_b16 v71, v23 offset:8960
	ds_write_b16_d16_hi v71, v23 offset:9088
	s_waitcnt vmcnt(6)
	ds_write_b16 v71, v24 offset:9216
	ds_write_b16_d16_hi v71, v24 offset:9344
	ds_write_b16 v71, v25 offset:9472
	ds_write_b16_d16_hi v71, v25 offset:9600
	ds_write_b16 v71, v26 offset:9728
	ds_write_b16_d16_hi v71, v26 offset:9856
	ds_write_b16 v71, v27 offset:9984
	ds_write_b16_d16_hi v71, v27 offset:10112
	s_waitcnt vmcnt(5)
	ds_write_b16 v71, v28 offset:10240
	ds_write_b16_d16_hi v71, v28 offset:10368
	ds_write_b16 v71, v29 offset:10496
	ds_write_b16_d16_hi v71, v29 offset:10624
	ds_write_b16 v71, v30 offset:10752
	ds_write_b16_d16_hi v71, v30 offset:10880
	ds_write_b16 v71, v31 offset:11008
	ds_write_b16_d16_hi v71, v31 offset:11136
	s_waitcnt vmcnt(4)
	ds_write_b16 v71, v32 offset:11264
	ds_write_b16_d16_hi v71, v32 offset:11392
	ds_write_b16 v71, v33 offset:11520
	ds_write_b16_d16_hi v71, v33 offset:11648
	ds_write_b16 v71, v34 offset:11776
	ds_write_b16_d16_hi v71, v34 offset:11904
	ds_write_b16 v71, v35 offset:12032
	ds_write_b16_d16_hi v71, v35 offset:12160
	s_waitcnt vmcnt(3)
	ds_write_b16 v71, v36 offset:12288
	ds_write_b16_d16_hi v71, v36 offset:12416
	ds_write_b16 v71, v37 offset:12544
	ds_write_b16_d16_hi v71, v37 offset:12672
	ds_write_b16 v71, v38 offset:12800
	ds_write_b16_d16_hi v71, v38 offset:12928
	ds_write_b16 v71, v39 offset:13056
	ds_write_b16_d16_hi v71, v39 offset:13184
	s_waitcnt vmcnt(2)
	ds_write_b16 v71, v40 offset:13312
	ds_write_b16_d16_hi v71, v40 offset:13440
	ds_write_b16 v71, v41 offset:13568
	ds_write_b16_d16_hi v71, v41 offset:13696
	ds_write_b16 v71, v42 offset:13824
	ds_write_b16_d16_hi v71, v42 offset:13952
	ds_write_b16 v71, v43 offset:14080
	ds_write_b16_d16_hi v71, v43 offset:14208
	s_waitcnt vmcnt(1)
	ds_write_b16 v71, v44 offset:14336
	ds_write_b16_d16_hi v71, v44 offset:14464
	ds_write_b16 v71, v45 offset:14592
	ds_write_b16_d16_hi v71, v45 offset:14720
	ds_write_b16 v71, v46 offset:14848
	ds_write_b16_d16_hi v71, v46 offset:14976
	ds_write_b16 v71, v47 offset:15104
	ds_write_b16_d16_hi v71, v47 offset:15232
	s_waitcnt vmcnt(0)
	ds_write_b16 v71, v48 offset:15360
	ds_write_b16_d16_hi v71, v48 offset:15488
	ds_write_b16 v71, v49 offset:15616
	ds_write_b16_d16_hi v71, v49 offset:15744
	ds_write_b16 v71, v50 offset:15872
	ds_write_b16_d16_hi v71, v50 offset:16000
	ds_write_b16 v71, v51 offset:16128
	ds_write_b16_d16_hi v71, v51 offset:16256
	v_and_b32_e32 v47, -16, v2
	v_lshlrev_b32_e32 v20, 3, v70
	v_add_u32_e32 v134, s17, v47
	v_sub_u32_e32 v46, v134, v20
	s_mul_i32 s0, s36, 0x104
	s_mul_hi_i32 s1, s36, 0x104
	s_add_u32 s0, s0, s33
	s_addc_u32 s1, s1, s34
	s_lshl_b64 s[0:1], s[0:1], 13
	s_add_u32 s4, s21, s0
	s_addc_u32 s5, s22, s1
	v_lshlrev_b64 v[96:97], 2, v[2:3]
	v_lshl_add_u64 v[2:3], s[4:5], 0, v[96:97]
	global_load_dword v26, v[2:3], off
	global_load_dword v27, v[2:3], off offset:256
	global_load_dword v28, v[2:3], off offset:512
	global_load_dword v29, v[2:3], off offset:768
	global_load_dword v30, v[2:3], off offset:1024
	global_load_dword v31, v[2:3], off offset:1280
	global_load_dword v32, v[2:3], off offset:1536
	global_load_dword v33, v[2:3], off offset:1792
	global_load_dword v38, v[2:3], off offset:2048
	global_load_dword v39, v[2:3], off offset:2304
	global_load_dword v40, v[2:3], off offset:2560
	global_load_dword v41, v[2:3], off offset:2816
	global_load_dword v44, v[2:3], off offset:3072
	global_load_dword v45, v[2:3], off offset:3328
	global_load_dword v48, v[2:3], off offset:3584
	v_lshlrev_b64 v[98:99], 2, v[54:55]
	global_load_dword v49, v[2:3], off offset:3840
	v_lshlrev_b64 v[100:101], 2, v[56:57]
	v_lshlrev_b64 v[130:131], 2, v[4:5]
	v_lshl_add_u64 v[4:5], s[4:5], 0, v[98:99]
	v_lshlrev_b64 v[128:129], 2, v[8:9]
	v_lshl_add_u64 v[8:9], s[4:5], 0, v[100:101]
	global_load_dword v50, v[4:5], off
	global_load_dword v51, v[8:9], off
	v_lshlrev_b64 v[102:103], 2, v[58:59]
	v_lshlrev_b64 v[104:105], 2, v[60:61]
	v_lshlrev_b64 v[126:127], 2, v[10:11]
	v_lshl_add_u64 v[10:11], s[4:5], 0, v[102:103]
	v_lshlrev_b64 v[124:125], 2, v[12:13]
	v_lshl_add_u64 v[12:13], s[4:5], 0, v[104:105]
	global_load_dword v52, v[10:11], off
	global_load_dword v53, v[12:13], off
	v_lshlrev_b64 v[106:107], 2, v[62:63]
	v_lshlrev_b64 v[112:113], 2, v[66:67]
	v_lshlrev_b64 v[108:109], 2, v[64:65]
	v_lshlrev_b64 v[114:115], 2, v[68:69]
	v_lshlrev_b64 v[116:117], 2, v[18:19]
	v_lshlrev_b64 v[118:119], 2, v[14:15]
	v_lshlrev_b64 v[122:123], 2, v[16:17]
	v_lshl_add_u64 v[14:15], s[4:5], 0, v[106:107]
	v_lshl_add_u64 v[16:17], s[4:5], 0, v[112:113]
	v_lshl_add_u64 v[2:3], s[4:5], 0, v[108:109]
	v_lshl_add_u64 v[4:5], s[4:5], 0, v[114:115]
	v_lshl_add_u64 v[18:19], s[4:5], 0, v[116:117]
	v_lshl_add_u64 v[20:21], s[4:5], 0, v[118:119]
	v_lshl_add_u64 v[8:9], s[4:5], 0, v[122:123]
	v_lshl_add_u64 v[22:23], s[4:5], 0, v[124:125]
	v_lshl_add_u64 v[10:11], s[4:5], 0, v[126:127]
	v_lshl_add_u64 v[24:25], s[4:5], 0, v[128:129]
	v_lshl_add_u64 v[12:13], s[4:5], 0, v[130:131]
	global_load_dword v14, v[14:15], off
	s_nop 0
	global_load_dword v15, v[2:3], off
	s_nop 0
	global_load_dword v16, v[16:17], off
	s_nop 0
	global_load_dword v17, v[4:5], off
	global_load_dword v54, v[18:19], off
	global_load_dword v55, v[20:21], off
	global_load_dword v56, v[8:9], off
	global_load_dword v57, v[22:23], off
	global_load_dword v58, v[10:11], off
	global_load_dword v59, v[24:25], off
	global_load_dword v60, v[12:13], off
	v_lshlrev_b64 v[132:133], 2, v[6:7]
	v_lshl_add_u64 v[6:7], s[4:5], 0, v[132:133]
	s_add_u32 s0, s23, s0
	s_addc_u32 s1, s24, s1
	v_lshl_add_u64 v[42:43], s[0:1], 0, v[94:95]
	v_add_u32_e32 v161, 16, v120
	v_cmp_gt_i32_e64 s[10:11], v120, v140
	v_cmp_le_i32_e32 vcc, v161, v140
	v_add_u32_e32 v162, 17, v120
	v_cmp_le_i32_e64 s[0:1], v162, v140
	v_or_b32_e32 v164, 2, v120
	v_add_u32_e32 v163, 18, v120
	v_or_b32_e32 v166, 3, v120
	v_add_u32_e32 v165, 19, v120
	v_or_b32_e32 v168, 16, v140
	v_cmp_lt_i32_e64 s[8:9], v120, v168
	v_or_b32_e32 v160, 32, v140
	v_cmp_lt_i32_e64 s[6:7], v120, v160
	v_lshl_add_u32 v173, v160, 6, v134
	v_add_u32_e32 v167, 48, v120
	v_or_b32_e32 v169, 1, v120
	s_waitcnt vmcnt(30)
	v_bfe_u32 v2, v26, 16, 1
	v_add3_u32 v2, v26, v2, s28
	global_load_dword v26, v[6:7], off
	global_load_dwordx4 v[22:25], v[42:43], off offset:16
	global_load_dwordx4 v[34:37], v[42:43], off
	global_load_dwordx4 v[18:21], v[110:111], off
	s_waitcnt vmcnt(32)
	v_bfe_u32 v4, v28, 16, 1
	s_waitcnt vmcnt(30)
	v_bfe_u32 v8, v30, 16, 1
	v_bfe_u32 v3, v27, 16, 1
	s_waitcnt vmcnt(26)
	v_bfe_u32 v6, v38, 16, 1
	v_add3_u32 v6, v38, v6, s28
	s_waitcnt vmcnt(25)
	v_bfe_u32 v7, v39, 16, 1
	v_bfe_u32 v5, v29, 16, 1
	v_bfe_u32 v9, v31, 16, 1
	v_add3_u32 v4, v28, v4, s28
	v_add3_u32 v8, v30, v8, s28
	v_lshrrev_b32_e32 v6, 16, v6
	v_add3_u32 v7, v39, v7, s28
	v_add3_u32 v3, v27, v3, s28
	v_add3_u32 v5, v29, v5, s28
	v_add3_u32 v9, v31, v9, s28
	v_lshrrev_b32_e32 v2, 16, v2
	v_lshrrev_b32_e32 v4, 16, v4
	v_lshrrev_b32_e32 v8, 16, v8
	v_and_or_b32 v6, v7, s29, v6
	s_waitcnt vmcnt(24)
	v_bfe_u32 v7, v40, 16, 1
	v_and_or_b32 v2, v3, s29, v2
	v_and_or_b32 v3, v5, s29, v4
	v_and_or_b32 v4, v9, s29, v8
	v_add3_u32 v7, v40, v7, s28
	s_waitcnt vmcnt(23)
	v_bfe_u32 v8, v41, 16, 1
	v_lshrrev_b32_e32 v7, 16, v7
	v_add3_u32 v8, v41, v8, s28
	v_and_or_b32 v7, v8, s29, v7
	s_waitcnt vmcnt(22)
	v_bfe_u32 v8, v44, 16, 1
	v_bfe_u32 v10, v32, 16, 1
	v_add3_u32 v8, v44, v8, s28
	s_waitcnt vmcnt(21)
	v_bfe_u32 v9, v45, 16, 1
	v_add3_u32 v10, v32, v10, s28
	v_bfe_u32 v5, v33, 16, 1
	v_lshrrev_b32_e32 v8, 16, v8
	v_add3_u32 v9, v45, v9, s28
	v_lshrrev_b32_e32 v10, 16, v10
	v_add3_u32 v5, v33, v5, s28
	v_and_or_b32 v8, v9, s29, v8
	s_waitcnt vmcnt(20)
	v_bfe_u32 v9, v48, 16, 1
	v_and_or_b32 v5, v5, s29, v10
	v_add3_u32 v9, v48, v9, s28
	s_waitcnt vmcnt(19)
	v_bfe_u32 v10, v49, 16, 1
	v_lshrrev_b32_e32 v9, 16, v9
	v_add3_u32 v10, v49, v10, s28
	v_and_or_b32 v9, v10, s29, v9
	s_waitcnt vmcnt(18)
	v_bfe_u32 v10, v50, 16, 1
	v_add3_u32 v10, v50, v10, s28
	s_waitcnt vmcnt(17)
	v_bfe_u32 v11, v51, 16, 1
	v_lshrrev_b32_e32 v10, 16, v10
	v_add3_u32 v11, v51, v11, s28
	v_and_or_b32 v10, v11, s29, v10
	s_waitcnt vmcnt(16)
	v_bfe_u32 v11, v52, 16, 1
	v_add3_u32 v11, v52, v11, s28
	s_waitcnt vmcnt(15)
	v_bfe_u32 v12, v53, 16, 1
	v_lshrrev_b32_e32 v11, 16, v11
	v_add3_u32 v12, v53, v12, s28
	v_and_or_b32 v11, v12, s29, v11
	s_waitcnt vmcnt(14)
	v_bfe_u32 v12, v14, 16, 1
	v_add3_u32 v12, v14, v12, s28
	s_waitcnt vmcnt(13)
	v_bfe_u32 v13, v15, 16, 1
	v_lshrrev_b32_e32 v12, 16, v12
	v_add3_u32 v13, v15, v13, s28
	v_and_or_b32 v12, v13, s29, v12
	s_waitcnt vmcnt(12)
	v_bfe_u32 v13, v16, 16, 1
	v_add3_u32 v13, v16, v13, s28
	s_waitcnt vmcnt(11)
	v_bfe_u32 v14, v17, 16, 1
	v_lshrrev_b32_e32 v13, 16, v13
	v_add3_u32 v14, v17, v14, s28
	global_load_dwordx4 v[38:41], v[110:111], off offset:256
	v_and_or_b32 v13, v14, s29, v13
	s_waitcnt vmcnt(11)
	v_bfe_u32 v14, v54, 16, 1
	v_add3_u32 v14, v54, v14, s28
	s_waitcnt vmcnt(10)
	v_bfe_u32 v15, v55, 16, 1
	v_lshrrev_b32_e32 v14, 16, v14
	v_add3_u32 v15, v55, v15, s28
	v_and_or_b32 v14, v15, s29, v14
	s_waitcnt vmcnt(9)
	v_bfe_u32 v15, v56, 16, 1
	v_add3_u32 v15, v56, v15, s28
	s_waitcnt vmcnt(8)
	v_bfe_u32 v16, v57, 16, 1
	v_lshrrev_b32_e32 v15, 16, v15
	v_add3_u32 v16, v57, v16, s28
	v_and_or_b32 v15, v16, s29, v15
	s_waitcnt vmcnt(7)
	v_bfe_u32 v16, v58, 16, 1
	v_add3_u32 v16, v58, v16, s28
	s_waitcnt vmcnt(6)
	v_bfe_u32 v17, v59, 16, 1
	v_lshrrev_b32_e32 v16, 16, v16
	v_add3_u32 v17, v59, v17, s28
	v_and_or_b32 v16, v17, s29, v16
	s_waitcnt vmcnt(5)
	v_bfe_u32 v17, v60, 16, 1
	v_add3_u32 v17, v60, v17, s28
	s_waitcnt vmcnt(4)
	v_bfe_u32 v27, v26, 16, 1
	v_lshrrev_b32_e32 v17, 16, v17
	v_add3_u32 v26, v26, v27, s28
	v_and_or_b32 v17, v26, s29, v17
	global_load_dwordx4 v[26:29], v[42:43], off offset:48
	global_load_dwordx4 v[30:33], v[42:43], off offset:32
	s_waitcnt vmcnt(5)
	v_mul_f32_e32 v23, 0x3fb8aa3b, v23
	s_waitcnt vmcnt(4)
	v_mul_f32_e32 v34, 0x3fb8aa3b, v34
	v_exp_f32_e32 v52, v23
	v_mul_f32_e32 v23, 0x3fb8aa3b, v36
	v_exp_f32_e32 v44, v34
	v_mul_f32_e32 v34, 0x3fb8aa3b, v35
	v_exp_f32_e32 v45, v23
	v_mul_f32_e32 v23, 0x3fb8aa3b, v24
	v_mul_f32_e32 v24, 0x3fb8aa3b, v37
	v_exp_f32_e32 v48, v34
	v_exp_f32_e32 v49, v24
	global_load_dwordx4 v[34:37], v[110:111], off offset:16
	s_waitcnt vmcnt(4)
	v_lshlrev_b32_e32 v51, 16, v19
	v_lshlrev_b32_e32 v50, 16, v18
	v_and_b32_e32 v19, 0xffff0000, v19
	v_and_b32_e32 v18, 0xffff0000, v18
	v_pk_mul_f32 v[50:51], v[50:51], s[16:17] op_sel_hi:[1,0]
	v_pk_mul_f32 v[18:19], v[18:19], s[16:17] op_sel_hi:[1,0]
	v_rcp_f32_e32 v54, v48
	v_pk_mul_f32 v[56:57], v[50:51], v[44:45]
	v_pk_mul_f32 v[18:19], v[18:19], v[48:49]
	v_rcp_f32_e32 v55, v49
	global_load_dwordx4 v[48:51], v[110:111], off offset:272
	v_mul_f32_e32 v22, 0x3fb8aa3b, v22
	v_mul_f32_e32 v24, 0x3fb8aa3b, v25
	v_exp_f32_e32 v22, v22
	v_exp_f32_e32 v23, v23
	v_exp_f32_e32 v53, v24
	v_rcp_f32_e32 v24, v44
	v_rcp_f32_e32 v25, v45
	v_lshlrev_b32_e32 v59, 16, v21
	v_lshlrev_b32_e32 v58, 16, v20
	v_and_b32_e32 v21, 0xffff0000, v21
	v_and_b32_e32 v20, 0xffff0000, v20
	v_pk_mul_f32 v[58:59], v[58:59], s[16:17] op_sel_hi:[1,0]
	v_pk_mul_f32 v[20:21], v[20:21], s[16:17] op_sel_hi:[1,0]
	v_pk_mul_f32 v[58:59], v[58:59], v[22:23]
	v_pk_mul_f32 v[20:21], v[20:21], v[52:53]
	s_waitcnt vmcnt(4)
	v_lshlrev_b32_e32 v45, 16, v39
	v_lshlrev_b32_e32 v44, 16, v38
	v_pk_mul_f32 v[24:25], v[24:25], v[44:45]
	v_rcp_f32_e32 v44, v22
	v_rcp_f32_e32 v45, v23
	v_and_b32_e32 v39, 0xffff0000, v39
	v_and_b32_e32 v38, 0xffff0000, v38
	v_pk_mul_f32 v[38:39], v[54:55], v[38:39]
	v_rcp_f32_e32 v54, v52
	v_rcp_f32_e32 v55, v53
	v_lshlrev_b32_e32 v23, 16, v41
	v_lshlrev_b32_e32 v22, 16, v40
	v_bfe_u32 v52, v19, 16, 1
	v_pk_mul_f32 v[22:23], v[44:45], v[22:23]
	v_bfe_u32 v44, v21, 16, 1
	v_add3_u32 v19, v19, v52, s28
	v_bfe_u32 v52, v58, 16, 1
	v_bfe_u32 v45, v20, 16, 1
	v_bfe_u32 v53, v18, 16, 1
	v_add3_u32 v21, v21, v44, s28
	v_bfe_u32 v44, v56, 16, 1
	v_add3_u32 v52, v58, v52, s28
	v_and_b32_e32 v41, 0xffff0000, v41
	v_and_b32_e32 v40, 0xffff0000, v40
	v_add3_u32 v18, v18, v53, s28
	v_add3_u32 v20, v20, v45, s28
	v_bfe_u32 v45, v57, 16, 1
	v_bfe_u32 v53, v59, 16, 1
	v_add3_u32 v44, v56, v44, s28
	v_lshrrev_b32_e32 v52, 16, v52
	v_pk_mul_f32 v[40:41], v[54:55], v[40:41]
	v_add3_u32 v53, v59, v53, s28
	v_add3_u32 v45, v57, v45, s28
	v_lshrrev_b32_e32 v44, 16, v44
	v_and_or_b32 v20, v20, s29, v52
	v_bfe_u32 v52, v39, 16, 1
	v_lshrrev_b32_e32 v45, 16, v45
	v_lshrrev_b32_e32 v53, 16, v53
	v_and_or_b32 v18, v18, s29, v44
	v_bfe_u32 v44, v41, 16, 1
	v_add3_u32 v39, v39, v52, s28
	v_bfe_u32 v52, v22, 16, 1
	v_and_or_b32 v21, v21, s29, v53
	v_and_or_b32 v19, v19, s29, v45
	v_bfe_u32 v45, v40, 16, 1
	v_bfe_u32 v53, v38, 16, 1
	v_add3_u32 v41, v41, v44, s28
	v_bfe_u32 v44, v24, 16, 1
	v_add3_u32 v22, v22, v52, s28
	v_add3_u32 v38, v38, v53, s28
	v_add3_u32 v40, v40, v45, s28
	v_bfe_u32 v45, v25, 16, 1
	v_bfe_u32 v53, v23, 16, 1
	v_add3_u32 v24, v24, v44, s28
	v_lshrrev_b32_e32 v22, 16, v22
	s_waitcnt vmcnt(3)
	v_mul_f32_e32 v27, 0x3fb8aa3b, v27
	v_add3_u32 v23, v23, v53, s28
	v_add3_u32 v25, v25, v45, s28
	v_lshrrev_b32_e32 v44, 16, v24
	v_and_or_b32 v24, v40, s29, v22
	s_waitcnt vmcnt(2)
	v_mul_f32_e32 v30, 0x3fb8aa3b, v30
	v_mul_f32_e32 v31, 0x3fb8aa3b, v31
	v_exp_f32_e32 v40, v27
	v_mul_f32_e32 v27, 0x3fb8aa3b, v32
	v_lshrrev_b32_e32 v45, 16, v25
	v_lshrrev_b32_e32 v23, 16, v23
	v_and_or_b32 v22, v38, s29, v44
	v_exp_f32_e32 v30, v30
	v_exp_f32_e32 v38, v31
	v_exp_f32_e32 v31, v27
	v_mul_f32_e32 v27, 0x3fb8aa3b, v28
	v_mul_f32_e32 v28, 0x3fb8aa3b, v33
	v_and_or_b32 v25, v41, s29, v23
	v_and_or_b32 v23, v39, s29, v45
	v_exp_f32_e32 v39, v28
	v_mul_f32_e32 v26, 0x3fb8aa3b, v26
	global_load_dwordx4 v[52:55], v[42:43], off offset:80
	global_load_dwordx4 v[56:59], v[42:43], off offset:64
	v_exp_f32_e32 v26, v26
	v_exp_f32_e32 v27, v27
	v_mul_f32_e32 v28, 0x3fb8aa3b, v29
	s_waitcnt vmcnt(3)
	v_lshlrev_b32_e32 v45, 16, v35
	v_lshlrev_b32_e32 v44, 16, v34
	v_and_b32_e32 v35, 0xffff0000, v35
	v_and_b32_e32 v34, 0xffff0000, v34
	v_exp_f32_e32 v41, v28
	v_rcp_f32_e32 v28, v30
	v_pk_mul_f32 v[34:35], v[34:35], s[16:17] op_sel_hi:[1,0]
	v_rcp_f32_e32 v29, v31
	v_pk_mul_f32 v[60:61], v[34:35], v[38:39]
	v_lshlrev_b32_e32 v35, 16, v37
	v_lshlrev_b32_e32 v34, 16, v36
	v_pk_mul_f32 v[44:45], v[44:45], s[16:17] op_sel_hi:[1,0]
	v_pk_mul_f32 v[34:35], v[34:35], s[16:17] op_sel_hi:[1,0]
	v_pk_mul_f32 v[44:45], v[44:45], v[30:31]
	s_waitcnt vmcnt(2)
	v_lshlrev_b32_e32 v31, 16, v49
	v_lshlrev_b32_e32 v30, 16, v48
	v_pk_mul_f32 v[62:63], v[34:35], v[26:27]
	v_and_b32_e32 v35, 0xffff0000, v37
	v_and_b32_e32 v34, 0xffff0000, v36
	v_pk_mul_f32 v[30:31], v[28:29], v[30:31]
	v_and_b32_e32 v29, 0xffff0000, v49
	v_and_b32_e32 v28, 0xffff0000, v48
	v_pk_mul_f32 v[48:49], v[34:35], s[16:17] op_sel_hi:[1,0]
	global_load_dwordx4 v[34:37], v[110:111], off offset:32
	v_rcp_f32_e32 v32, v38
	v_rcp_f32_e32 v33, v39
	v_rcp_f32_e32 v38, v40
	v_pk_mul_f32 v[64:65], v[48:49], v[40:41]
	v_rcp_f32_e32 v39, v41
	v_pk_mul_f32 v[32:33], v[32:33], v[28:29]
	v_rcp_f32_e32 v28, v26
	v_rcp_f32_e32 v29, v27
	v_lshlrev_b32_e32 v27, 16, v51
	v_lshlrev_b32_e32 v26, 16, v50
	v_pk_mul_f32 v[40:41], v[28:29], v[26:27]
	v_and_b32_e32 v27, 0xffff0000, v51
	v_and_b32_e32 v26, 0xffff0000, v50
	global_load_dwordx4 v[48:51], v[110:111], off offset:288
	v_pk_mul_f32 v[38:39], v[38:39], v[26:27]
	v_bfe_u32 v26, v65, 16, 1
	v_bfe_u32 v27, v64, 16, 1
	v_bfe_u32 v28, v61, 16, 1
	v_bfe_u32 v29, v60, 16, 1
	v_add3_u32 v60, v60, v29, s28
	v_add3_u32 v61, v61, v28, s28
	v_add3_u32 v27, v64, v27, s28
	v_add3_u32 v26, v65, v26, s28
	v_bfe_u32 v28, v44, 16, 1
	v_bfe_u32 v29, v45, 16, 1
	v_bfe_u32 v64, v62, 16, 1
	v_bfe_u32 v65, v63, 16, 1
	v_add3_u32 v63, v63, v65, s28
	v_add3_u32 v62, v62, v64, s28
	v_add3_u32 v29, v45, v29, s28
	v_add3_u32 v28, v44, v28, s28
	v_lshrrev_b32_e32 v44, 16, v28
	v_lshrrev_b32_e32 v45, 16, v29
	v_lshrrev_b32_e32 v28, 16, v62
	v_lshrrev_b32_e32 v29, 16, v63
	v_and_or_b32 v29, v26, s29, v29
	v_and_or_b32 v28, v27, s29, v28
	v_and_or_b32 v27, v61, s29, v45
	v_and_or_b32 v26, v60, s29, v44
	v_bfe_u32 v44, v39, 16, 1
	v_bfe_u32 v45, v38, 16, 1
	v_bfe_u32 v60, v33, 16, 1
	v_bfe_u32 v61, v32, 16, 1
	v_add3_u32 v61, v32, v61, s28
	v_add3_u32 v60, v33, v60, s28
	v_add3_u32 v32, v38, v45, s28
	v_add3_u32 v33, v39, v44, s28
	v_bfe_u32 v39, v31, 16, 1
	v_bfe_u32 v44, v40, 16, 1
	v_bfe_u32 v45, v41, 16, 1
	v_bfe_u32 v38, v30, 16, 1
	v_add3_u32 v41, v41, v45, s28
	v_add3_u32 v40, v40, v44, s28
	v_add3_u32 v31, v31, v39, s28
	v_add3_u32 v30, v30, v38, s28
	v_lshrrev_b32_e32 v31, 16, v31
	v_lshrrev_b32_e32 v38, 16, v40
	v_lshrrev_b32_e32 v39, 16, v41
	s_waitcnt vmcnt(3)
	v_mul_f32_e32 v52, 0x3fb8aa3b, v52
	v_and_or_b32 v33, v33, s29, v39
	v_and_or_b32 v32, v32, s29, v38
	v_and_or_b32 v31, v60, s29, v31
	global_load_dwordx4 v[38:41], v[42:43], off offset:112
	s_nop 0
	global_load_dwordx4 v[42:45], v[42:43], off offset:96
	v_exp_f32_e32 v60, v52
	s_waitcnt vmcnt(4)
	v_mul_f32_e32 v52, 0x3fb8aa3b, v57
	v_exp_f32_e32 v62, v52
	v_mul_f32_e32 v52, 0x3fb8aa3b, v53
	v_exp_f32_e32 v64, v52
	v_mul_f32_e32 v52, 0x3fb8aa3b, v58
	v_lshrrev_b32_e32 v30, 16, v30
	v_mul_f32_e32 v56, 0x3fb8aa3b, v56
	v_exp_f32_e32 v57, v52
	v_mul_f32_e32 v52, 0x3fb8aa3b, v54
	v_and_or_b32 v30, v61, s29, v30
	v_exp_f32_e32 v56, v56
	v_exp_f32_e32 v61, v52
	v_mul_f32_e32 v52, 0x3fb8aa3b, v59
	v_exp_f32_e32 v63, v52
	v_mul_f32_e32 v52, 0x3fb8aa3b, v55
	v_exp_f32_e32 v65, v52
	global_load_dwordx4 v[52:55], v[110:111], off offset:48
	s_waitcnt vmcnt(4)
	v_lshlrev_b32_e32 v59, 16, v35
	v_lshlrev_b32_e32 v58, 16, v34
	v_pk_mul_f32 v[58:59], v[58:59], s[16:17] op_sel_hi:[1,0]
	v_rcp_f32_e32 v66, v56
	v_pk_mul_f32 v[70:71], v[58:59], v[56:57]
	v_rcp_f32_e32 v67, v57
	global_load_dwordx4 v[56:59], v[110:111], off offset:304
	v_and_b32_e32 v35, 0xffff0000, v35
	v_and_b32_e32 v34, 0xffff0000, v34
	v_rcp_f32_e32 v68, v62
	v_pk_mul_f32 v[34:35], v[34:35], s[16:17] op_sel_hi:[1,0]
	v_rcp_f32_e32 v69, v63
	v_pk_mul_f32 v[34:35], v[34:35], v[62:63]
	s_waitcnt vmcnt(4)
	v_lshlrev_b32_e32 v63, 16, v49
	v_lshlrev_b32_e32 v62, 16, v48
	v_pk_mul_f32 v[62:63], v[66:67], v[62:63]
	v_rcp_f32_e32 v66, v60
	v_lshlrev_b32_e32 v73, 16, v37
	v_lshlrev_b32_e32 v72, 16, v36
	v_and_b32_e32 v37, 0xffff0000, v37
	v_and_b32_e32 v36, 0xffff0000, v36
	v_rcp_f32_e32 v67, v61
	v_and_b32_e32 v49, 0xffff0000, v49
	v_and_b32_e32 v48, 0xffff0000, v48
	v_pk_mul_f32 v[36:37], v[36:37], s[16:17] op_sel_hi:[1,0]
	v_pk_mul_f32 v[48:49], v[68:69], v[48:49]
	v_rcp_f32_e32 v68, v64
	v_pk_mul_f32 v[72:73], v[72:73], s[16:17] op_sel_hi:[1,0]
	v_pk_mul_f32 v[36:37], v[36:37], v[64:65]
	v_rcp_f32_e32 v69, v65
	v_pk_mul_f32 v[72:73], v[72:73], v[60:61]
	v_lshlrev_b32_e32 v61, 16, v51
	v_lshlrev_b32_e32 v60, 16, v50
	v_bfe_u32 v64, v37, 16, 1
	v_pk_mul_f32 v[60:61], v[66:67], v[60:61]
	v_bfe_u32 v66, v35, 16, 1
	v_add3_u32 v37, v37, v64, s28
	v_bfe_u32 v64, v70, 16, 1
	v_and_b32_e32 v51, 0xffff0000, v51
	v_and_b32_e32 v50, 0xffff0000, v50
	v_bfe_u32 v67, v34, 16, 1
	v_add3_u32 v35, v35, v66, s28
	v_bfe_u32 v66, v72, 16, 1
	v_add3_u32 v64, v70, v64, s28
	v_pk_mul_f32 v[50:51], v[68:69], v[50:51]
	v_bfe_u32 v65, v36, 16, 1
	v_add3_u32 v34, v34, v67, s28
	v_bfe_u32 v67, v73, 16, 1
	v_add3_u32 v66, v72, v66, s28
	v_lshrrev_b32_e32 v64, 16, v64
	v_add3_u32 v36, v36, v65, s28
	v_bfe_u32 v65, v71, 16, 1
	v_add3_u32 v67, v73, v67, s28
	v_lshrrev_b32_e32 v66, 16, v66
	v_and_or_b32 v34, v34, s29, v64
	v_bfe_u32 v64, v51, 16, 1
	v_add3_u32 v65, v71, v65, s28
	v_lshrrev_b32_e32 v67, 16, v67
	v_and_or_b32 v36, v36, s29, v66
	v_bfe_u32 v66, v49, 16, 1
	v_add3_u32 v51, v51, v64, s28
	v_bfe_u32 v64, v62, 16, 1
	v_lshrrev_b32_e32 v65, 16, v65
	v_and_or_b32 v37, v37, s29, v67
	v_bfe_u32 v67, v48, 16, 1
	v_add3_u32 v49, v49, v66, s28
	v_bfe_u32 v66, v60, 16, 1
	v_add3_u32 v62, v62, v64, s28
	v_and_or_b32 v35, v35, s29, v65
	v_bfe_u32 v65, v50, 16, 1
	v_add3_u32 v48, v48, v67, s28
	v_bfe_u32 v67, v61, 16, 1
	v_add3_u32 v60, v60, v66, s28
	v_lshrrev_b32_e32 v62, 16, v62
	s_waitcnt vmcnt(3)
	v_mul_f32_e32 v39, 0x3fb8aa3b, v39
	v_add3_u32 v50, v50, v65, s28
	v_add3_u32 v61, v61, v67, s28
	v_lshrrev_b32_e32 v60, 16, v60
	v_and_or_b32 v48, v48, s29, v62
	s_waitcnt vmcnt(2)
	v_mul_f32_e32 v42, 0x3fb8aa3b, v42
	v_mul_f32_e32 v43, 0x3fb8aa3b, v43
	v_exp_f32_e32 v62, v39
	v_mul_f32_e32 v39, 0x3fb8aa3b, v44
	v_lshrrev_b32_e32 v61, 16, v61
	v_and_or_b32 v50, v50, s29, v60
	v_exp_f32_e32 v42, v42
	v_exp_f32_e32 v60, v43
	v_exp_f32_e32 v43, v39
	v_mul_f32_e32 v39, 0x3fb8aa3b, v40
	v_mul_f32_e32 v40, 0x3fb8aa3b, v45
	v_bfe_u32 v65, v63, 16, 1
	v_and_or_b32 v51, v51, s29, v61
	v_exp_f32_e32 v61, v40
	v_add3_u32 v63, v63, v65, s28
	v_lshrrev_b32_e32 v63, 16, v63
	v_mul_f32_e32 v40, 0x3fb8aa3b, v41
	v_and_or_b32 v49, v49, s29, v63
	v_mul_f32_e32 v38, 0x3fb8aa3b, v38
	v_exp_f32_e32 v63, v40
	v_rcp_f32_e32 v40, v42
	v_rcp_f32_e32 v41, v43
	v_exp_f32_e32 v38, v38
	v_exp_f32_e32 v39, v39
	v_rcp_f32_e32 v44, v60
	s_waitcnt vmcnt(1)
	v_lshlrev_b32_e32 v65, 16, v53
	v_lshlrev_b32_e32 v64, 16, v52
	v_rcp_f32_e32 v45, v61
	v_pk_mul_f32 v[64:65], v[64:65], s[16:17] op_sel_hi:[1,0]
	v_and_b32_e32 v53, 0xffff0000, v53
	v_pk_mul_f32 v[64:65], v[64:65], v[42:43]
	s_waitcnt vmcnt(0)
	v_lshlrev_b32_e32 v43, 16, v57
	v_lshlrev_b32_e32 v42, 16, v56
	v_and_b32_e32 v52, 0xffff0000, v52
	v_pk_mul_f32 v[42:43], v[40:41], v[42:43]
	v_and_b32_e32 v41, 0xffff0000, v57
	v_and_b32_e32 v40, 0xffff0000, v56
	v_pk_mul_f32 v[52:53], v[52:53], s[16:17] op_sel_hi:[1,0]
	v_pk_mul_f32 v[44:45], v[44:45], v[40:41]
	v_rcp_f32_e32 v40, v38
	v_rcp_f32_e32 v41, v39
	v_pk_mul_f32 v[52:53], v[52:53], v[60:61]
	v_rcp_f32_e32 v56, v62
	v_lshlrev_b32_e32 v61, 16, v55
	v_lshlrev_b32_e32 v60, 16, v54
	v_rcp_f32_e32 v57, v63
	v_pk_mul_f32 v[60:61], v[60:61], s[16:17] op_sel_hi:[1,0]
	v_and_b32_e32 v55, 0xffff0000, v55
	v_and_b32_e32 v54, 0xffff0000, v54
	v_pk_mul_f32 v[60:61], v[60:61], v[38:39]
	v_pk_mul_f32 v[54:55], v[54:55], s[16:17] op_sel_hi:[1,0]
	v_lshlrev_b32_e32 v39, 16, v59
	v_lshlrev_b32_e32 v38, 16, v58
	v_pk_mul_f32 v[54:55], v[54:55], v[62:63]
	v_pk_mul_f32 v[62:63], v[40:41], v[38:39]
	v_and_b32_e32 v39, 0xffff0000, v59
	v_and_b32_e32 v38, 0xffff0000, v58
	v_pk_mul_f32 v[56:57], v[56:57], v[38:39]
	v_bfe_u32 v38, v55, 16, 1
	v_bfe_u32 v39, v54, 16, 1
	v_bfe_u32 v40, v53, 16, 1
	v_bfe_u32 v41, v52, 16, 1
	v_add3_u32 v52, v52, v41, s28
	v_add3_u32 v53, v53, v40, s28
	v_add3_u32 v39, v54, v39, s28
	v_add3_u32 v38, v55, v38, s28
	v_bfe_u32 v40, v64, 16, 1
	v_bfe_u32 v41, v65, 16, 1
	v_bfe_u32 v54, v60, 16, 1
	v_bfe_u32 v55, v61, 16, 1
	v_add3_u32 v55, v61, v55, s28
	v_add3_u32 v54, v60, v54, s28
	v_add3_u32 v41, v65, v41, s28
	v_add3_u32 v40, v64, v40, s28
	v_lshrrev_b32_e32 v58, 16, v40
	v_lshrrev_b32_e32 v59, 16, v41
	v_lshrrev_b32_e32 v40, 16, v54
	v_lshrrev_b32_e32 v41, 16, v55
	v_and_or_b32 v41, v38, s29, v41
	v_and_or_b32 v40, v39, s29, v40
	v_and_or_b32 v39, v53, s29, v59
	v_and_or_b32 v38, v52, s29, v58
	v_bfe_u32 v52, v57, 16, 1
	v_bfe_u32 v53, v56, 16, 1
	v_bfe_u32 v54, v45, 16, 1
	v_bfe_u32 v55, v44, 16, 1
	v_add3_u32 v55, v44, v55, s28
	v_add3_u32 v54, v45, v54, s28
	v_add3_u32 v44, v56, v53, s28
	v_add3_u32 v45, v57, v52, s28
	v_bfe_u32 v52, v42, 16, 1
	v_bfe_u32 v53, v43, 16, 1
	v_bfe_u32 v56, v62, 16, 1
	v_bfe_u32 v57, v63, 16, 1
	v_add3_u32 v57, v63, v57, s28
	v_add3_u32 v56, v62, v56, s28
	v_add3_u32 v43, v43, v53, s28
	v_add3_u32 v42, v42, v52, s28
	s_waitcnt lgkmcnt(0)
	ds_write_b128 v142, v[18:21]
	ds_write_b128 v142, v[26:29] offset:16
	ds_write_b128 v142, v[34:37] offset:32
	ds_write_b128 v142, v[38:41] offset:48
	ds_write_b128 v142, v[2:5] offset:4096
	ds_write_b128 v142, v[6:9] offset:4112
	ds_write_b128 v142, v[10:13] offset:4128
	ds_write_b128 v142, v[14:17] offset:4144
	v_lshlrev_b32_e32 v26, 6, v140
	v_lshrrev_b32_e32 v42, 16, v42
	v_lshrrev_b32_e32 v43, 16, v43
	v_lshrrev_b32_e32 v52, 16, v56
	v_lshrrev_b32_e32 v53, 16, v57
	v_add_u32_e32 v172, v134, v26
	v_and_or_b32 v45, v45, s29, v53
	v_and_or_b32 v44, v44, s29, v52
	v_and_or_b32 v43, v54, s29, v43
	v_and_or_b32 v42, v55, s29, v42
	s_waitcnt lgkmcnt(0)
	ds_read_b128 v[14:17], v172
	ds_read_b128 v[10:13], v172 offset:1024
	ds_read_b128 v[6:9], v172 offset:2048
	ds_read_b128 v[2:5], v172 offset:3072
	s_waitcnt lgkmcnt(0)
	ds_write_b128 v142, v[22:25]
	ds_write_b128 v142, v[30:33] offset:16
	ds_write_b128 v142, v[48:51] offset:32
	ds_write_b128 v142, v[42:45] offset:48
	s_waitcnt lgkmcnt(0)
	ds_read_b128 v[18:21], v172 offset:4096
	ds_read_b128 v[34:37], v172
	s_waitcnt lgkmcnt(1)
	v_mfma_f32_16x16x32_bf16 v[38:41], v[18:21], v[14:17], 0
	v_add3_u32 v143, s17, v26, v47
	v_mfma_f32_16x16x32_bf16 v[42:45], v[18:21], v[10:13], 0
	v_mfma_f32_16x16x32_bf16 v[82:85], v[18:21], v[6:9], 0
	v_mfma_f32_16x16x32_bf16 v[86:89], v[18:21], v[2:5], 0
	ds_read_b128 v[18:21], v172 offset:5120
	ds_read_b128 v[22:25], v172 offset:6144
	ds_read_b128 v[90:93], v143 offset:1024
	s_waitcnt lgkmcnt(2)
	v_mfma_f32_16x16x32_bf16 v[50:53], v[18:21], v[14:17], 0
	v_mfma_f32_16x16x32_bf16 v[54:57], v[18:21], v[10:13], 0
	v_mfma_f32_16x16x32_bf16 v[58:61], v[18:21], v[6:9], 0
	v_mfma_f32_16x16x32_bf16 v[62:65], v[18:21], v[2:5], 0
	ds_read_b128 v[18:21], v172 offset:7168
	v_mfma_f32_16x16x32_bf16 v[152:155], v[34:37], v[14:17], 0
	s_waitcnt lgkmcnt(1)
	v_mfma_f32_16x16x32_bf16 v[156:159], v[90:93], v[14:17], 0
	v_mfma_f32_16x16x32_bf16 v[174:177], v[34:37], v[10:13], 0
	s_nop 4
	v_cndmask_b32_e64 v47, v152, 0, s[10:11]
	s_nop 0
	v_cndmask_b32_e32 v48, 0, v156, vcc
	v_cmp_lt_i32_e32 vcc, v120, v140
	v_cndmask_b32_e64 v135, 0, v157, s[0:1]
	v_cmp_le_i32_e64 s[0:1], v164, v140
	v_cndmask_b32_e32 v49, 0, v153, vcc
	v_bfe_u32 v152, v47, 16, 1
	v_cndmask_b32_e64 v136, 0, v154, s[0:1]
	v_cmp_le_i32_e64 s[0:1], v163, v140
	v_add3_u32 v47, v47, v152, s28
	v_bfe_u32 v152, v49, 16, 1
	v_cndmask_b32_e64 v137, 0, v158, s[0:1]
	v_cmp_le_i32_e64 s[0:1], v166, v140
	v_lshrrev_b32_e32 v47, 16, v47
	v_add3_u32 v49, v49, v152, s28
	v_cndmask_b32_e64 v144, 0, v155, s[0:1]
	v_and_or_b32 v154, v49, s29, v47
	v_bfe_u32 v47, v136, 16, 1
	v_add3_u32 v47, v136, v47, s28
	v_bfe_u32 v49, v144, 16, 1
	v_lshrrev_b32_e32 v47, 16, v47
	v_add3_u32 v49, v144, v49, s28
	v_and_or_b32 v155, v49, s29, v47
	v_bfe_u32 v47, v48, 16, 1
	v_add3_u32 v47, v48, v47, s28
	v_bfe_u32 v48, v135, 16, 1
	v_cmp_le_i32_e64 s[0:1], v165, v140
	v_lshrrev_b32_e32 v47, 16, v47
	v_add3_u32 v48, v135, v48, s28
	v_cndmask_b32_e64 v145, 0, v159, s[0:1]
	v_and_or_b32 v156, v48, s29, v47
	v_bfe_u32 v47, v137, 16, 1
	v_mfma_f32_16x16x32_bf16 v[178:181], v[90:93], v[10:13], 0
	v_add3_u32 v47, v137, v47, s28
	v_bfe_u32 v48, v145, 16, 1
	v_lshrrev_b32_e32 v47, 16, v47
	v_add3_u32 v48, v145, v48, s28
	v_cmp_le_i32_e64 s[0:1], v120, v168
	v_and_or_b32 v157, v48, s29, v47
	v_cndmask_b32_e64 v49, 0, v175, s[8:9]
	v_cndmask_b32_e64 v47, 0, v174, s[0:1]
	v_cmp_le_i32_e64 s[0:1], v162, v168
	v_bfe_u32 v152, v47, 16, 1
	v_add3_u32 v47, v47, v152, s28
	v_cndmask_b32_e64 v135, 0, v179, s[0:1]
	v_cmp_le_i32_e64 s[0:1], v164, v168
	v_bfe_u32 v152, v49, 16, 1
	v_lshrrev_b32_e32 v47, 16, v47
	v_cndmask_b32_e64 v136, 0, v176, s[0:1]
	v_cmp_le_i32_e64 s[0:1], v163, v168
	v_add3_u32 v49, v49, v152, s28
	v_and_or_b32 v174, v49, s29, v47
	v_cndmask_b32_e64 v137, 0, v180, s[0:1]
	v_cmp_le_i32_e64 s[0:1], v166, v168
	v_bfe_u32 v47, v136, 16, 1
	v_add3_u32 v47, v136, v47, s28
	v_cndmask_b32_e64 v144, 0, v177, s[0:1]
	v_bfe_u32 v49, v144, 16, 1
	v_cndmask_b32_e64 v48, v178, 0, s[10:11]
	v_lshrrev_b32_e32 v47, 16, v47
	v_add3_u32 v49, v144, v49, s28
	v_and_or_b32 v175, v49, s29, v47
	v_bfe_u32 v47, v48, 16, 1
	v_cmp_le_i32_e64 s[0:1], v165, v168
	v_add3_u32 v47, v48, v47, s28
	v_bfe_u32 v48, v135, 16, 1
	v_cndmask_b32_e64 v145, 0, v181, s[0:1]
	v_lshrrev_b32_e32 v47, 16, v47
	v_add3_u32 v48, v135, v48, s28
	v_mfma_f32_16x16x32_bf16 v[178:181], v[34:37], v[6:9], 0
	v_and_or_b32 v176, v48, s29, v47
	v_bfe_u32 v47, v137, 16, 1
	v_add3_u32 v47, v137, v47, s28
	v_mfma_f32_16x16x32_bf16 v[182:185], v[90:93], v[6:9], 0
	v_bfe_u32 v48, v145, 16, 1
	v_lshrrev_b32_e32 v47, 16, v47
	v_add3_u32 v48, v145, v48, s28
	v_cmp_le_i32_e64 s[0:1], v120, v160
	v_and_or_b32 v177, v48, s29, v47
	v_cndmask_b32_e64 v49, 0, v179, s[6:7]
	v_cndmask_b32_e64 v47, 0, v178, s[0:1]
	v_cmp_le_i32_e64 s[0:1], v161, v160
	v_bfe_u32 v152, v47, 16, 1
	v_add3_u32 v47, v47, v152, s28
	v_cndmask_b32_e64 v48, 0, v182, s[0:1]
	v_cmp_le_i32_e64 s[0:1], v162, v160
	v_bfe_u32 v152, v49, 16, 1
	v_lshrrev_b32_e32 v47, 16, v47
	v_cndmask_b32_e64 v135, 0, v183, s[0:1]
	v_cmp_le_i32_e64 s[0:1], v164, v160
	v_add3_u32 v49, v49, v152, s28
	v_and_or_b32 v178, v49, s29, v47
	v_cndmask_b32_e64 v136, 0, v180, s[0:1]
	v_cmp_le_i32_e64 s[0:1], v163, v160
	v_bfe_u32 v47, v136, 16, 1
	v_add3_u32 v47, v136, v47, s28
	v_cndmask_b32_e64 v137, 0, v184, s[0:1]
	v_cmp_le_i32_e64 s[0:1], v166, v160
	v_lshrrev_b32_e32 v47, 16, v47
	v_mfma_f32_16x16x32_bf16 v[34:37], v[34:37], v[2:5], 0
	v_cndmask_b32_e64 v144, 0, v181, s[0:1]
	v_bfe_u32 v49, v144, 16, 1
	v_add3_u32 v49, v144, v49, s28
	v_and_or_b32 v179, v49, s29, v47
	v_bfe_u32 v47, v48, 16, 1
	v_add3_u32 v47, v48, v47, s28
	v_bfe_u32 v48, v135, 16, 1
	v_cmp_le_i32_e64 s[0:1], v165, v160
	v_lshrrev_b32_e32 v47, 16, v47
	v_add3_u32 v48, v135, v48, s28
	v_cndmask_b32_e64 v145, 0, v185, s[0:1]
	v_and_or_b32 v180, v48, s29, v47
	v_bfe_u32 v47, v137, 16, 1
	v_or_b32_e32 v152, 48, v140
	v_add3_u32 v47, v137, v47, s28
	v_bfe_u32 v48, v145, 16, 1
	v_mfma_f32_16x16x32_bf16 v[90:93], v[90:93], v[2:5], 0
	v_cmp_le_i32_e64 s[0:1], v120, v152
	v_lshrrev_b32_e32 v47, 16, v47
	v_add3_u32 v48, v145, v48, s28
	v_cndmask_b32_e64 v34, 0, v34, s[0:1]
	v_cmp_lt_i32_e64 s[4:5], v120, v152
	v_and_or_b32 v181, v48, s29, v47
	v_bfe_u32 v47, v34, 16, 1
	v_cndmask_b32_e64 v35, 0, v35, s[4:5]
	v_lshl_add_u32 v135, v140, 7, v46
	v_cmp_le_i32_e64 s[0:1], v161, v152
	v_add3_u32 v34, v34, v47, s28
	v_bfe_u32 v47, v35, 16, 1
	v_add_u32_e32 v144, 0x2000, v135
	v_cndmask_b32_e64 v90, 0, v90, s[0:1]
	v_cmp_le_i32_e64 s[0:1], v162, v152
	v_add3_u32 v35, v35, v47, s28
	ds_read2_b64 v[46:49], v144 offset1:4
	v_cndmask_b32_e64 v91, 0, v91, s[0:1]
	v_cmp_le_i32_e64 s[0:1], v164, v152
	v_lshrrev_b32_e32 v34, 16, v34
	v_and_or_b32 v182, v35, s29, v34
	v_cndmask_b32_e64 v36, 0, v36, s[0:1]
	v_cmp_le_i32_e64 s[0:1], v163, v152
	v_bfe_u32 v34, v36, 16, 1
	v_add3_u32 v34, v36, v34, s28
	v_cndmask_b32_e64 v92, 0, v92, s[0:1]
	v_cmp_le_i32_e64 s[0:1], v166, v152
	v_lshrrev_b32_e32 v34, 16, v34
	v_add_u32_e32 v145, 0x2800, v135
	v_cndmask_b32_e64 v37, 0, v37, s[0:1]
	v_bfe_u32 v35, v37, 16, 1
	v_add3_u32 v35, v37, v35, s28
	v_and_or_b32 v183, v35, s29, v34
	v_bfe_u32 v34, v90, 16, 1
	v_add3_u32 v34, v90, v34, s28
	v_lshrrev_b32_e32 v90, 16, v34
	s_waitcnt lgkmcnt(0)
	v_mfma_f32_16x16x32_bf16 v[34:37], v[46:49], v[154:157], v[38:41]
	v_cmp_le_i32_e64 s[0:1], v165, v152
	v_add_u32_e32 v171, 0x3000, v135
	v_add_u32_e32 v170, 0x3800, v135
	v_bfe_u32 v38, v91, 16, 1
	v_add3_u32 v38, v91, v38, s28
	v_and_or_b32 v184, v38, s29, v90
	v_mfma_f32_16x16x32_bf16 v[38:41], v[46:49], v[174:177], v[42:45]
	v_cndmask_b32_e64 v93, 0, v93, s[0:1]
	ds_read2_b64 v[186:189], v170 offset1:4
	v_add_u32_e32 v153, 32, v120
	v_bfe_u32 v42, v92, 16, 1
	v_add3_u32 v42, v92, v42, s28
	v_lshrrev_b32_e32 v90, 16, v42
	v_mfma_f32_16x16x32_bf16 v[42:45], v[46:49], v[178:181], v[82:85]
	v_cmp_le_i32_e64 s[0:1], v153, v140
	v_add_u32_e32 v159, 35, v120
	v_add_u32_e32 v158, 51, v120
	v_bfe_u32 v82, v93, 16, 1
	v_add3_u32 v82, v93, v82, s28
	v_and_or_b32 v185, v82, s29, v90
	ds_read2_b64 v[82:85], v145 offset1:4
	s_waitcnt lgkmcnt(0)
	v_mfma_f32_16x16x32_bf16 v[50:53], v[82:85], v[154:157], v[50:53]
	v_mfma_f32_16x16x32_bf16 v[54:57], v[82:85], v[174:177], v[54:57]
	v_mfma_f32_16x16x32_bf16 v[58:61], v[82:85], v[178:181], v[58:61]
	v_mfma_f32_16x16x32_bf16 v[62:65], v[82:85], v[182:185], v[62:65]
	ds_read2_b64 v[82:85], v171 offset1:4
	v_mfma_f32_16x16x32_bf16 v[66:69], v[22:25], v[14:17], 0
	v_mfma_f32_16x16x32_bf16 v[70:73], v[22:25], v[10:13], 0
	v_mfma_f32_16x16x32_bf16 v[74:77], v[22:25], v[6:9], 0
	v_mfma_f32_16x16x32_bf16 v[78:81], v[22:25], v[2:5], 0
	v_mfma_f32_16x16x32_bf16 v[22:25], v[18:21], v[14:17], 0
	v_mfma_f32_16x16x32_bf16 v[26:29], v[18:21], v[10:13], 0
	s_waitcnt lgkmcnt(0)
	v_mfma_f32_16x16x32_bf16 v[66:69], v[82:85], v[154:157], v[66:69]
	v_mfma_f32_16x16x32_bf16 v[70:73], v[82:85], v[174:177], v[70:73]
	v_mfma_f32_16x16x32_bf16 v[74:77], v[82:85], v[178:181], v[74:77]
	v_mfma_f32_16x16x32_bf16 v[78:81], v[82:85], v[182:185], v[78:81]
	v_mfma_f32_16x16x32_bf16 v[82:85], v[186:189], v[154:157], v[22:25]
	v_add_u32_e32 v155, 33, v120
	v_add_u32_e32 v154, 49, v120
	v_add_u32_e32 v157, 34, v120
	ds_read_b128 v[22:25], v173
	v_mfma_f32_16x16x32_bf16 v[46:49], v[46:49], v[182:185], v[86:89]
	v_add_u32_e32 v156, 50, v120
	v_mfma_f32_16x16x32_bf16 v[86:89], v[186:189], v[174:177], v[26:29]
	s_nop 2
	ds_read_b128 v[26:29], v143 offset:3072
	v_mfma_f32_16x16x32_bf16 v[30:33], v[18:21], v[6:9], 0
	v_mfma_f32_16x16x32_bf16 v[90:93], v[186:189], v[178:181], v[30:33]
	s_waitcnt lgkmcnt(1)
	v_mfma_f32_16x16x32_bf16 v[30:33], v[22:25], v[14:17], 0
	s_waitcnt lgkmcnt(0)
	v_mfma_f32_16x16x32_bf16 v[14:17], v[26:29], v[14:17], 0
	v_mfma_f32_16x16x32_bf16 v[18:21], v[18:21], v[2:5], 0
	s_nop 4
	v_cndmask_b32_e64 v30, 0, v30, s[0:1]
	v_cmp_le_i32_e64 s[0:1], v167, v140
	v_mfma_f32_16x16x32_bf16 v[18:21], v[186:189], v[182:185], v[18:21]
	s_nop 0
	v_cndmask_b32_e64 v134, 0, v14, s[0:1]
	v_cmp_le_i32_e64 s[0:1], v155, v140
	s_nop 1
	v_cndmask_b32_e64 v14, 0, v31, s[0:1]
	v_cmp_le_i32_e64 s[0:1], v154, v140
	s_nop 1
	v_cndmask_b32_e64 v31, 0, v15, s[0:1]
	v_cmp_le_i32_e64 s[0:1], v157, v140
	s_nop 1
	v_cndmask_b32_e64 v15, 0, v32, s[0:1]
	v_cmp_le_i32_e64 s[0:1], v156, v140
	s_nop 1
	v_cndmask_b32_e64 v32, 0, v16, s[0:1]
	v_cmp_le_i32_e64 s[0:1], v159, v140
	s_nop 1
	v_cndmask_b32_e64 v16, 0, v33, s[0:1]
	v_bfe_u32 v33, v30, 16, 1
	v_add3_u32 v30, v30, v33, s28
	v_bfe_u32 v33, v14, 16, 1
	v_lshrrev_b32_e32 v30, 16, v30
	v_add3_u32 v14, v14, v33, s28
	v_and_or_b32 v14, v14, s29, v30
	v_bfe_u32 v30, v15, 16, 1
	v_add3_u32 v15, v15, v30, s28
	v_bfe_u32 v30, v16, 16, 1
	v_lshrrev_b32_e32 v15, 16, v15
	v_add3_u32 v16, v16, v30, s28
	v_and_or_b32 v15, v16, s29, v15
	v_bfe_u32 v16, v134, 16, 1
	v_add3_u32 v16, v134, v16, s28
	v_bfe_u32 v30, v31, 16, 1
	v_lshrrev_b32_e32 v16, 16, v16
	v_add3_u32 v30, v31, v30, s28
	v_and_or_b32 v16, v30, s29, v16
	v_bfe_u32 v30, v32, 16, 1
	v_add3_u32 v30, v32, v30, s28
	v_lshrrev_b32_e32 v134, 16, v30
	v_mfma_f32_16x16x32_bf16 v[30:33], v[22:25], v[10:13], 0
	v_cmp_le_i32_e64 s[0:1], v158, v140
	v_mfma_f32_16x16x32_bf16 v[10:13], v[26:29], v[10:13], 0
	s_nop 0
	v_cndmask_b32_e64 v17, 0, v17, s[0:1]
	v_cmp_le_i32_e64 s[0:1], v153, v168
	v_bfe_u32 v135, v17, 16, 1
	v_add3_u32 v17, v17, v135, s28
	s_nop 0
	v_cndmask_b32_e64 v30, 0, v30, s[0:1]
	v_cmp_le_i32_e64 s[0:1], v167, v168
	v_and_or_b32 v17, v17, s29, v134
	s_nop 0
	v_cndmask_b32_e64 v10, 0, v10, s[0:1]
	v_cmp_le_i32_e64 s[0:1], v155, v168
	s_nop 1
	v_cndmask_b32_e64 v31, 0, v31, s[0:1]
	v_cmp_le_i32_e64 s[0:1], v154, v168
	s_nop 1
	v_cndmask_b32_e64 v11, 0, v11, s[0:1]
	v_cmp_le_i32_e64 s[0:1], v157, v168
	s_nop 1
	v_cndmask_b32_e64 v32, 0, v32, s[0:1]
	v_cmp_le_i32_e64 s[0:1], v156, v168
	s_nop 1
	v_cndmask_b32_e64 v12, 0, v12, s[0:1]
	v_cmp_le_i32_e64 s[0:1], v159, v168
	s_nop 1
	v_cndmask_b32_e64 v33, 0, v33, s[0:1]
	v_cmp_le_i32_e64 s[0:1], v158, v168
	s_nop 1
	v_cndmask_b32_e64 v137, 0, v13, s[0:1]
	v_bfe_u32 v13, v30, 16, 1
	v_add3_u32 v13, v30, v13, s28
	v_bfe_u32 v30, v31, 16, 1
	v_lshrrev_b32_e32 v13, 16, v13
	v_add3_u32 v30, v31, v30, s28
	v_and_or_b32 v134, v30, s29, v13
	v_bfe_u32 v13, v32, 16, 1
	v_add3_u32 v13, v32, v13, s28
	v_bfe_u32 v30, v33, 16, 1
	v_lshrrev_b32_e32 v13, 16, v13
	v_add3_u32 v30, v33, v30, s28
	v_and_or_b32 v135, v30, s29, v13
	v_bfe_u32 v13, v10, 16, 1
	v_add3_u32 v10, v10, v13, s28
	v_bfe_u32 v13, v11, 16, 1
	v_lshrrev_b32_e32 v10, 16, v10
	v_add3_u32 v11, v11, v13, s28
	v_and_or_b32 v136, v11, s29, v10
	v_bfe_u32 v10, v12, 16, 1
	v_add3_u32 v10, v12, v10, s28
	v_lshrrev_b32_e32 v30, 16, v10
	v_mfma_f32_16x16x32_bf16 v[10:13], v[22:25], v[6:9], 0
	v_cmp_le_i32_e64 s[0:1], v167, v160
	v_bfe_u32 v31, v137, 16, 1
	v_add3_u32 v31, v137, v31, s28
	v_mfma_f32_16x16x32_bf16 v[6:9], v[26:29], v[6:9], 0
	v_and_or_b32 v137, v31, s29, v30
	s_nop 2
	v_cndmask_b32_e64 v10, v10, 0, s[10:11]
	s_nop 2
	v_cndmask_b32_e64 v6, 0, v6, s[0:1]
	v_cmp_le_i32_e64 s[0:1], v155, v160
	s_nop 1
	v_cndmask_b32_e64 v11, 0, v11, s[0:1]
	v_cmp_le_i32_e64 s[0:1], v154, v160
	s_nop 1
	v_cndmask_b32_e64 v7, 0, v7, s[0:1]
	v_cmp_le_i32_e64 s[0:1], v157, v160
	s_nop 1
	v_cndmask_b32_e64 v12, 0, v12, s[0:1]
	v_cmp_le_i32_e64 s[0:1], v156, v160
	s_nop 1
	v_cndmask_b32_e64 v8, 0, v8, s[0:1]
	v_cmp_le_i32_e64 s[0:1], v159, v160
	s_nop 1
	v_cndmask_b32_e64 v13, 0, v13, s[0:1]
	v_cmp_le_i32_e64 s[0:1], v158, v160
	s_nop 1
	v_cndmask_b32_e64 v30, 0, v9, s[0:1]
	v_bfe_u32 v9, v10, 16, 1
	v_add3_u32 v9, v10, v9, s28
	v_bfe_u32 v10, v11, 16, 1
	v_lshrrev_b32_e32 v9, 16, v9
	v_add3_u32 v10, v11, v10, s28
	v_and_or_b32 v174, v10, s29, v9
	v_bfe_u32 v9, v12, 16, 1
	v_add3_u32 v9, v12, v9, s28
	v_bfe_u32 v10, v13, 16, 1
	v_lshrrev_b32_e32 v9, 16, v9
	v_add3_u32 v10, v13, v10, s28
	v_and_or_b32 v175, v10, s29, v9
	v_bfe_u32 v9, v6, 16, 1
	v_add3_u32 v6, v6, v9, s28
	v_bfe_u32 v9, v7, 16, 1
	v_lshrrev_b32_e32 v6, 16, v6
	v_add3_u32 v7, v7, v9, s28
	v_and_or_b32 v176, v7, s29, v6
	v_bfe_u32 v6, v8, 16, 1
	v_add3_u32 v6, v8, v6, s28
	v_lshrrev_b32_e32 v10, 16, v6
	v_mfma_f32_16x16x32_bf16 v[6:9], v[22:25], v[2:5], 0
	v_bfe_u32 v11, v30, 16, 1
	v_cmp_le_i32_e64 s[0:1], v153, v152
	v_add3_u32 v11, v30, v11, s28
	v_mfma_f32_16x16x32_bf16 v[2:5], v[26:29], v[2:5], 0
	v_and_or_b32 v177, v11, s29, v10
	s_nop 2
	v_cndmask_b32_e64 v6, 0, v6, s[0:1]
	v_cmp_le_i32_e64 s[0:1], v155, v152
	s_nop 1
	v_cndmask_b32_e64 v10, v2, 0, s[10:11]
	v_cndmask_b32_e64 v2, 0, v7, s[0:1]
	v_cmp_le_i32_e64 s[0:1], v154, v152
	v_bfe_u32 v7, v6, 16, 1
	v_add3_u32 v6, v6, v7, s28
	v_cndmask_b32_e64 v11, 0, v3, s[0:1]
	v_cmp_le_i32_e64 s[0:1], v157, v152
	v_bfe_u32 v7, v2, 16, 1
	v_lshrrev_b32_e32 v6, 16, v6
	v_cndmask_b32_e64 v3, 0, v8, s[0:1]
	v_cmp_le_i32_e64 s[0:1], v156, v152
	v_add3_u32 v2, v2, v7, s28
	v_bfe_u32 v13, v3, 16, 1
	v_cndmask_b32_e64 v12, 0, v4, s[0:1]
	v_cmp_le_i32_e64 s[0:1], v159, v152
	v_and_or_b32 v2, v2, s29, v6
	v_add3_u32 v3, v3, v13, s28
	v_cndmask_b32_e64 v4, 0, v9, s[0:1]
	ds_read2_b64 v[6:9], v144 offset0:8 offset1:12
	v_bfe_u32 v13, v4, 16, 1
	v_lshrrev_b32_e32 v3, 16, v3
	v_add3_u32 v4, v4, v13, s28
	v_and_or_b32 v3, v4, s29, v3
	v_bfe_u32 v4, v10, 16, 1
	v_add3_u32 v4, v10, v4, s28
	v_bfe_u32 v10, v11, 16, 1
	v_cmp_le_i32_e64 s[0:1], v158, v152
	v_lshrrev_b32_e32 v4, 16, v4
	v_add3_u32 v10, v11, v10, s28
	v_cndmask_b32_e64 v5, 0, v5, s[0:1]
	v_and_or_b32 v4, v10, s29, v4
	v_bfe_u32 v10, v12, 16, 1
	v_add3_u32 v10, v12, v10, s28
	v_bfe_u32 v11, v5, 16, 1
	v_lshrrev_b32_e32 v10, 16, v10
	v_add3_u32 v5, v5, v11, s28
	v_and_or_b32 v5, v5, s29, v10
	s_waitcnt lgkmcnt(0)
	v_mfma_f32_16x16x32_bf16 v[22:25], v[6:9], v[14:17], v[34:37]
	v_mfma_f32_16x16x32_bf16 v[26:29], v[6:9], v[134:137], v[38:41]
	v_mfma_f32_16x16x32_bf16 v[30:33], v[6:9], v[174:177], v[42:45]
	v_mfma_f32_16x16x32_bf16 v[34:37], v[6:9], v[2:5], v[46:49]
	ds_read2_b64 v[6:9], v145 offset0:8 offset1:12
	s_waitcnt lgkmcnt(0)
	v_mfma_f32_16x16x32_bf16 v[38:41], v[6:9], v[14:17], v[50:53]
	ds_read2_b64 v[46:49], v170 offset0:8 offset1:12
	v_mfma_f32_16x16x32_bf16 v[42:45], v[6:9], v[134:137], v[54:57]
	v_mfma_f32_16x16x32_bf16 v[50:53], v[6:9], v[174:177], v[58:61]
	v_mfma_f32_16x16x32_bf16 v[54:57], v[6:9], v[2:5], v[62:65]
	ds_read2_b64 v[6:9], v171 offset0:8 offset1:12
	s_waitcnt lgkmcnt(0)
	v_mfma_f32_16x16x32_bf16 v[58:61], v[6:9], v[14:17], v[66:69]
	v_mfma_f32_16x16x32_bf16 v[62:65], v[6:9], v[134:137], v[70:73]
	v_mfma_f32_16x16x32_bf16 v[10:13], v[6:9], v[174:177], v[74:77]
	v_mfma_f32_16x16x32_bf16 v[6:9], v[6:9], v[2:5], v[78:81]
	v_mfma_f32_16x16x32_bf16 v[66:69], v[46:49], v[14:17], v[82:85]
	v_mfma_f32_16x16x32_bf16 v[70:73], v[46:49], v[134:137], v[86:89]
	v_mfma_f32_16x16x32_bf16 v[14:17], v[46:49], v[174:177], v[90:93]
	v_mfma_f32_16x16x32_bf16 v[2:5], v[46:49], v[2:5], v[18:21]
	s_or_b32 s0, s36, 4
	s_mul_i32 s10, s0, 0x104
	s_ashr_i32 s1, s35, 31
	s_mul_hi_i32 s2, s0, 0x104
	s_add_u32 s0, s10, s35
	s_addc_u32 s1, s2, s1
	s_lshl_b64 s[0:1], s[0:1], 13
	s_add_u32 s0, s21, s0
	s_addc_u32 s1, s22, s1
	v_lshl_add_u64 v[18:19], s[0:1], 0, v[96:97]
	global_load_dword v92, v[18:19], off
	global_load_dword v93, v[18:19], off offset:256
	global_load_dword v96, v[18:19], off offset:512
	global_load_dword v97, v[18:19], off offset:768
	global_load_dword v134, v[18:19], off offset:1024
	global_load_dword v135, v[18:19], off offset:1280
	global_load_dword v136, v[18:19], off offset:1536
	global_load_dword v137, v[18:19], off offset:1792
	global_load_dword v174, v[18:19], off offset:2048
	global_load_dword v175, v[18:19], off offset:2304
	global_load_dword v176, v[18:19], off offset:2560
	global_load_dword v177, v[18:19], off offset:2816
	global_load_dword v178, v[18:19], off offset:3072
	v_lshl_add_u64 v[48:49], s[0:1], 0, v[102:103]
	global_load_dword v102, v[18:19], off offset:3328
	global_load_dword v103, v[18:19], off offset:3584
	v_lshl_add_u64 v[74:75], s[0:1], 0, v[104:105]
	global_load_dword v104, v[18:19], off offset:3840
	v_lshl_add_u64 v[20:21], s[0:1], 0, v[98:99]
	v_lshl_add_u64 v[46:47], s[0:1], 0, v[100:101]
	v_lshl_add_u64 v[78:79], s[0:1], 0, v[108:109]
	global_load_dword v108, v[20:21], off
	global_load_dword v109, v[46:47], off
	v_lshl_add_u64 v[80:81], s[0:1], 0, v[112:113]
	global_load_dword v112, v[48:49], off
	v_lshl_add_u64 v[76:77], s[0:1], 0, v[106:107]
	global_load_dword v75, v[74:75], off
	v_lshl_add_u64 v[90:91], s[0:1], 0, v[132:133]
	v_lshl_add_u64 v[18:19], s[0:1], 0, v[114:115]
	v_lshl_add_u64 v[82:83], s[0:1], 0, v[116:117]
	v_lshl_add_u64 v[20:21], s[0:1], 0, v[118:119]
	v_lshl_add_u64 v[84:85], s[0:1], 0, v[122:123]
	v_lshl_add_u64 v[86:87], s[0:1], 0, v[124:125]
	v_lshl_add_u64 v[46:47], s[0:1], 0, v[126:127]
	v_lshl_add_u64 v[88:89], s[0:1], 0, v[128:129]
	v_lshl_add_u64 v[48:49], s[0:1], 0, v[130:131]
	global_load_dword v76, v[76:77], off
	s_nop 0
	global_load_dword v77, v[78:79], off
	s_nop 0
	global_load_dword v78, v[80:81], off
	global_load_dword v79, v[18:19], off
	s_nop 0
	global_load_dword v80, v[82:83], off
	global_load_dword v81, v[20:21], off
	global_load_dword v113, v[84:85], off
	global_load_dword v114, v[86:87], off
	global_load_dword v115, v[46:47], off
	global_load_dword v116, v[88:89], off
	global_load_dword v117, v[48:49], off
	s_nop 0
	global_load_dword v90, v[90:91], off
	s_add_u32 s0, s10, s33
	s_addc_u32 s1, s2, s34
	s_lshl_b64 s[0:1], s[0:1], 13
	s_add_u32 s0, s23, s0
	s_addc_u32 s1, s24, s1
	v_lshl_add_u64 v[106:107], s[0:1], 0, v[94:95]
	global_load_dwordx4 v[86:89], v[106:107], off offset:16
	global_load_dwordx4 v[98:101], v[106:107], off
	global_load_dwordx4 v[82:85], v[110:111], off
	v_cmp_ge_i32_e64 s[0:1], v161, v140
	v_or_b32_e32 v192, s31, v140
	v_readlane_b32 s36, v239, 33
	v_readlane_b32 s50, v239, 47
	v_readlane_b32 s51, v239, 48
	v_ashrrev_i32_e32 v193, 31, v192
	v_readlane_b32 s37, v239, 34
	v_readlane_b32 s38, v239, 35
	v_readlane_b32 s39, v239, 36
	v_readlane_b32 s40, v239, 37
	v_readlane_b32 s41, v239, 38
	v_readlane_b32 s42, v239, 39
	v_readlane_b32 s43, v239, 40
	v_readlane_b32 s44, v239, 41
	v_readlane_b32 s45, v239, 42
	v_readlane_b32 s46, v239, 43
	v_readlane_b32 s47, v239, 44
	v_readlane_b32 s48, v239, 45
	v_readlane_b32 s49, v239, 46
	s_waitcnt vmcnt(34)
	v_bfe_u32 v18, v92, 16, 1
	s_waitcnt vmcnt(33)
	v_bfe_u32 v19, v93, 16, 1
	s_waitcnt vmcnt(32)
	v_bfe_u32 v20, v96, 16, 1
	s_waitcnt vmcnt(31)
	v_bfe_u32 v21, v97, 16, 1
	s_waitcnt vmcnt(30)
	v_bfe_u32 v46, v134, 16, 1
	s_waitcnt vmcnt(29)
	v_bfe_u32 v47, v135, 16, 1
	v_add3_u32 v18, v92, v18, s28
	v_add3_u32 v20, v96, v20, s28
	v_add3_u32 v46, v134, v46, s28
	s_waitcnt vmcnt(26)
	v_bfe_u32 v74, v174, 16, 1
	v_add3_u32 v19, v93, v19, s28
	v_add3_u32 v21, v97, v21, s28
	v_add3_u32 v47, v135, v47, s28
	v_lshrrev_b32_e32 v18, 16, v18
	v_lshrrev_b32_e32 v20, 16, v20
	v_lshrrev_b32_e32 v46, 16, v46
	v_bfe_u32 v48, v136, 16, 1
	v_add3_u32 v74, v174, v74, s28
	v_and_or_b32 v18, v19, s29, v18
	v_and_or_b32 v19, v21, s29, v20
	v_and_or_b32 v20, v47, s29, v46
	s_waitcnt vmcnt(25)
	v_bfe_u32 v47, v175, 16, 1
	v_bfe_u32 v49, v137, 16, 1
	v_add3_u32 v48, v136, v48, s28
	v_lshrrev_b32_e32 v46, 16, v74
	v_add3_u32 v47, v175, v47, s28
	v_add3_u32 v49, v137, v49, s28
	v_lshrrev_b32_e32 v48, 16, v48
	v_and_or_b32 v46, v47, s29, v46
	s_waitcnt vmcnt(24)
	v_bfe_u32 v47, v176, 16, 1
	v_and_or_b32 v21, v49, s29, v48
	v_add3_u32 v47, v176, v47, s28
	s_waitcnt vmcnt(23)
	v_bfe_u32 v48, v177, 16, 1
	v_lshrrev_b32_e32 v47, 16, v47
	v_add3_u32 v48, v177, v48, s28
	v_and_or_b32 v47, v48, s29, v47
	s_waitcnt vmcnt(22)
	v_bfe_u32 v48, v178, 16, 1
	v_add3_u32 v48, v178, v48, s28
	s_waitcnt vmcnt(21)
	v_bfe_u32 v49, v102, 16, 1
	v_lshrrev_b32_e32 v48, 16, v48
	v_add3_u32 v49, v102, v49, s28
	v_and_or_b32 v48, v49, s29, v48
	s_waitcnt vmcnt(20)
	v_bfe_u32 v49, v103, 16, 1
	v_add3_u32 v49, v103, v49, s28
	s_waitcnt vmcnt(19)
	v_bfe_u32 v74, v104, 16, 1
	v_lshrrev_b32_e32 v49, 16, v49
	v_add3_u32 v74, v104, v74, s28
	v_and_or_b32 v49, v74, s29, v49
	s_waitcnt vmcnt(18)
	v_bfe_u32 v74, v108, 16, 1
	v_add3_u32 v74, v108, v74, s28
	s_waitcnt vmcnt(17)
	v_bfe_u32 v91, v109, 16, 1
	v_lshrrev_b32_e32 v74, 16, v74
	v_add3_u32 v91, v109, v91, s28
	v_and_or_b32 v74, v91, s29, v74
	s_waitcnt vmcnt(16)
	v_bfe_u32 v91, v112, 16, 1
	v_add3_u32 v91, v112, v91, s28
	s_waitcnt vmcnt(15)
	v_bfe_u32 v92, v75, 16, 1
	v_lshrrev_b32_e32 v91, 16, v91
	v_add3_u32 v75, v75, v92, s28
	v_and_or_b32 v75, v75, s29, v91
	s_waitcnt vmcnt(14)
	v_bfe_u32 v91, v76, 16, 1
	v_add3_u32 v76, v76, v91, s28
	s_waitcnt vmcnt(13)
	v_bfe_u32 v91, v77, 16, 1
	v_lshrrev_b32_e32 v76, 16, v76
	v_add3_u32 v77, v77, v91, s28
	v_and_or_b32 v76, v77, s29, v76
	s_waitcnt vmcnt(12)
	v_bfe_u32 v77, v78, 16, 1
	v_add3_u32 v77, v78, v77, s28
	s_waitcnt vmcnt(11)
	v_bfe_u32 v78, v79, 16, 1
	v_lshrrev_b32_e32 v77, 16, v77
	v_add3_u32 v78, v79, v78, s28
	global_load_dwordx4 v[102:105], v[110:111], off offset:256
	v_and_or_b32 v77, v78, s29, v77
	s_waitcnt vmcnt(11)
	v_bfe_u32 v78, v80, 16, 1
	v_add3_u32 v78, v80, v78, s28
	s_waitcnt vmcnt(10)
	v_bfe_u32 v79, v81, 16, 1
	v_lshrrev_b32_e32 v78, 16, v78
	v_add3_u32 v79, v81, v79, s28
	v_and_or_b32 v78, v79, s29, v78
	s_waitcnt vmcnt(9)
	v_bfe_u32 v79, v113, 16, 1
	v_add3_u32 v79, v113, v79, s28
	s_waitcnt vmcnt(8)
	v_bfe_u32 v80, v114, 16, 1
	v_lshrrev_b32_e32 v79, 16, v79
	v_add3_u32 v80, v114, v80, s28
	v_and_or_b32 v79, v80, s29, v79
	s_waitcnt vmcnt(7)
	v_bfe_u32 v80, v115, 16, 1
	v_add3_u32 v80, v115, v80, s28
	s_waitcnt vmcnt(6)
	v_bfe_u32 v81, v116, 16, 1
	v_lshrrev_b32_e32 v80, 16, v80
	v_add3_u32 v81, v116, v81, s28
	v_and_or_b32 v80, v81, s29, v80
	s_waitcnt vmcnt(5)
	v_bfe_u32 v81, v117, 16, 1
	v_add3_u32 v81, v117, v81, s28
	s_waitcnt vmcnt(4)
	v_bfe_u32 v91, v90, 16, 1
	v_lshrrev_b32_e32 v81, 16, v81
	v_add3_u32 v90, v90, v91, s28
	v_and_or_b32 v81, v90, s29, v81
	global_load_dwordx4 v[90:93], v[106:107], off offset:48
	global_load_dwordx4 v[94:97], v[106:107], off offset:32
	s_waitcnt vmcnt(5)
	v_mul_f32_e32 v87, 0x3fb8aa3b, v87
	s_waitcnt vmcnt(4)
	v_mul_f32_e32 v98, 0x3fb8aa3b, v98
	v_exp_f32_e32 v116, v87
	v_mul_f32_e32 v87, 0x3fb8aa3b, v100
	v_exp_f32_e32 v108, v98
	v_mul_f32_e32 v98, 0x3fb8aa3b, v99
	v_exp_f32_e32 v109, v87
	v_mul_f32_e32 v87, 0x3fb8aa3b, v88
	v_mul_f32_e32 v88, 0x3fb8aa3b, v101
	v_exp_f32_e32 v112, v98
	v_exp_f32_e32 v113, v88
	global_load_dwordx4 v[98:101], v[110:111], off offset:16
	s_waitcnt vmcnt(4)
	v_lshlrev_b32_e32 v115, 16, v83
	v_lshlrev_b32_e32 v114, 16, v82
	v_and_b32_e32 v83, 0xffff0000, v83
	v_and_b32_e32 v82, 0xffff0000, v82
	v_pk_mul_f32 v[114:115], v[114:115], s[16:17] op_sel_hi:[1,0]
	v_pk_mul_f32 v[82:83], v[82:83], s[16:17] op_sel_hi:[1,0]
	v_rcp_f32_e32 v118, v112
	v_pk_mul_f32 v[122:123], v[114:115], v[108:109]
	v_pk_mul_f32 v[82:83], v[82:83], v[112:113]
	v_rcp_f32_e32 v119, v113
	global_load_dwordx4 v[112:115], v[110:111], off offset:272
	v_mul_f32_e32 v86, 0x3fb8aa3b, v86
	v_mul_f32_e32 v88, 0x3fb8aa3b, v89
	v_exp_f32_e32 v86, v86
	v_exp_f32_e32 v87, v87
	v_exp_f32_e32 v117, v88
	v_rcp_f32_e32 v88, v108
	v_rcp_f32_e32 v89, v109
	v_lshlrev_b32_e32 v125, 16, v85
	v_lshlrev_b32_e32 v124, 16, v84
	v_and_b32_e32 v85, 0xffff0000, v85
	v_and_b32_e32 v84, 0xffff0000, v84
	v_pk_mul_f32 v[124:125], v[124:125], s[16:17] op_sel_hi:[1,0]
	v_pk_mul_f32 v[84:85], v[84:85], s[16:17] op_sel_hi:[1,0]
	v_pk_mul_f32 v[124:125], v[124:125], v[86:87]
	v_pk_mul_f32 v[84:85], v[84:85], v[116:117]
	s_waitcnt vmcnt(4)
	v_lshlrev_b32_e32 v109, 16, v103
	v_lshlrev_b32_e32 v108, 16, v102
	v_pk_mul_f32 v[88:89], v[88:89], v[108:109]
	v_rcp_f32_e32 v108, v86
	v_rcp_f32_e32 v109, v87
	v_and_b32_e32 v103, 0xffff0000, v103
	v_and_b32_e32 v102, 0xffff0000, v102
	v_pk_mul_f32 v[102:103], v[118:119], v[102:103]
	v_rcp_f32_e32 v118, v116
	v_rcp_f32_e32 v119, v117
	v_lshlrev_b32_e32 v87, 16, v105
	v_lshlrev_b32_e32 v86, 16, v104
	v_bfe_u32 v116, v83, 16, 1
	v_pk_mul_f32 v[86:87], v[108:109], v[86:87]
	v_bfe_u32 v108, v85, 16, 1
	v_add3_u32 v83, v83, v116, s28
	v_bfe_u32 v116, v124, 16, 1
	v_bfe_u32 v109, v84, 16, 1
	v_bfe_u32 v117, v82, 16, 1
	v_add3_u32 v85, v85, v108, s28
	v_bfe_u32 v108, v122, 16, 1
	v_add3_u32 v116, v124, v116, s28
	v_and_b32_e32 v105, 0xffff0000, v105
	v_and_b32_e32 v104, 0xffff0000, v104
	v_add3_u32 v82, v82, v117, s28
	v_add3_u32 v84, v84, v109, s28
	v_bfe_u32 v109, v123, 16, 1
	v_bfe_u32 v117, v125, 16, 1
	v_add3_u32 v108, v122, v108, s28
	v_lshrrev_b32_e32 v116, 16, v116
	v_pk_mul_f32 v[104:105], v[118:119], v[104:105]
	v_add3_u32 v117, v125, v117, s28
	v_add3_u32 v109, v123, v109, s28
	v_lshrrev_b32_e32 v108, 16, v108
	v_and_or_b32 v84, v84, s29, v116
	v_bfe_u32 v116, v103, 16, 1
	v_lshrrev_b32_e32 v109, 16, v109
	v_lshrrev_b32_e32 v117, 16, v117
	v_and_or_b32 v82, v82, s29, v108
	v_bfe_u32 v108, v105, 16, 1
	v_add3_u32 v103, v103, v116, s28
	v_bfe_u32 v116, v86, 16, 1
	v_and_or_b32 v85, v85, s29, v117
	v_and_or_b32 v83, v83, s29, v109
	v_bfe_u32 v109, v104, 16, 1
	v_bfe_u32 v117, v102, 16, 1
	v_add3_u32 v105, v105, v108, s28
	v_bfe_u32 v108, v88, 16, 1
	v_add3_u32 v86, v86, v116, s28
	v_add3_u32 v102, v102, v117, s28
	v_add3_u32 v104, v104, v109, s28
	v_bfe_u32 v109, v89, 16, 1
	v_bfe_u32 v117, v87, 16, 1
	v_add3_u32 v88, v88, v108, s28
	v_lshrrev_b32_e32 v86, 16, v86
	s_waitcnt vmcnt(3)
	v_mul_f32_e32 v91, 0x3fb8aa3b, v91
	v_add3_u32 v87, v87, v117, s28
	v_add3_u32 v89, v89, v109, s28
	v_lshrrev_b32_e32 v108, 16, v88
	v_and_or_b32 v88, v104, s29, v86
	s_waitcnt vmcnt(2)
	v_mul_f32_e32 v94, 0x3fb8aa3b, v94
	v_mul_f32_e32 v95, 0x3fb8aa3b, v95
	v_exp_f32_e32 v104, v91
	v_mul_f32_e32 v91, 0x3fb8aa3b, v96
	v_lshrrev_b32_e32 v109, 16, v89
	v_lshrrev_b32_e32 v87, 16, v87
	v_and_or_b32 v86, v102, s29, v108
	v_exp_f32_e32 v94, v94
	v_exp_f32_e32 v102, v95
	v_exp_f32_e32 v95, v91
	v_mul_f32_e32 v91, 0x3fb8aa3b, v92
	v_mul_f32_e32 v92, 0x3fb8aa3b, v97
	v_and_or_b32 v89, v105, s29, v87
	v_and_or_b32 v87, v103, s29, v109
	v_exp_f32_e32 v103, v92
	v_mul_f32_e32 v90, 0x3fb8aa3b, v90
	global_load_dwordx4 v[116:119], v[106:107], off offset:80
	global_load_dwordx4 v[122:125], v[106:107], off offset:64
	v_exp_f32_e32 v90, v90
	v_exp_f32_e32 v91, v91
	v_mul_f32_e32 v92, 0x3fb8aa3b, v93
	s_waitcnt vmcnt(3)
	v_lshlrev_b32_e32 v109, 16, v99
	v_lshlrev_b32_e32 v108, 16, v98
	v_and_b32_e32 v99, 0xffff0000, v99
	v_and_b32_e32 v98, 0xffff0000, v98
	v_exp_f32_e32 v105, v92
	v_rcp_f32_e32 v92, v94
	v_pk_mul_f32 v[98:99], v[98:99], s[16:17] op_sel_hi:[1,0]
	v_rcp_f32_e32 v93, v95
	v_pk_mul_f32 v[126:127], v[98:99], v[102:103]
	v_lshlrev_b32_e32 v99, 16, v101
	v_lshlrev_b32_e32 v98, 16, v100
	v_pk_mul_f32 v[108:109], v[108:109], s[16:17] op_sel_hi:[1,0]
	v_pk_mul_f32 v[98:99], v[98:99], s[16:17] op_sel_hi:[1,0]
	v_pk_mul_f32 v[108:109], v[108:109], v[94:95]
	s_waitcnt vmcnt(2)
	v_lshlrev_b32_e32 v95, 16, v113
	v_lshlrev_b32_e32 v94, 16, v112
	v_pk_mul_f32 v[128:129], v[98:99], v[90:91]
	v_and_b32_e32 v99, 0xffff0000, v101
	v_and_b32_e32 v98, 0xffff0000, v100
	v_pk_mul_f32 v[94:95], v[92:93], v[94:95]
	v_and_b32_e32 v93, 0xffff0000, v113
	v_and_b32_e32 v92, 0xffff0000, v112
	v_pk_mul_f32 v[112:113], v[98:99], s[16:17] op_sel_hi:[1,0]
	global_load_dwordx4 v[98:101], v[110:111], off offset:32
	v_rcp_f32_e32 v96, v102
	v_rcp_f32_e32 v97, v103
	v_rcp_f32_e32 v102, v104
	v_rcp_f32_e32 v103, v105
	v_pk_mul_f32 v[130:131], v[112:113], v[104:105]
	v_pk_mul_f32 v[96:97], v[96:97], v[92:93]
	v_rcp_f32_e32 v92, v90
	v_rcp_f32_e32 v93, v91
	v_lshlrev_b32_e32 v91, 16, v115
	v_lshlrev_b32_e32 v90, 16, v114
	v_pk_mul_f32 v[104:105], v[92:93], v[90:91]
	v_and_b32_e32 v91, 0xffff0000, v115
	v_and_b32_e32 v90, 0xffff0000, v114
	global_load_dwordx4 v[112:115], v[110:111], off offset:288
	v_pk_mul_f32 v[102:103], v[102:103], v[90:91]
	v_bfe_u32 v90, v131, 16, 1
	v_bfe_u32 v91, v130, 16, 1
	v_bfe_u32 v92, v127, 16, 1
	v_bfe_u32 v93, v126, 16, 1
	v_add3_u32 v126, v126, v93, s28
	v_add3_u32 v127, v127, v92, s28
	v_add3_u32 v91, v130, v91, s28
	v_add3_u32 v90, v131, v90, s28
	v_bfe_u32 v92, v108, 16, 1
	v_bfe_u32 v93, v109, 16, 1
	v_bfe_u32 v130, v128, 16, 1
	v_bfe_u32 v131, v129, 16, 1
	v_add3_u32 v129, v129, v131, s28
	v_add3_u32 v128, v128, v130, s28
	v_add3_u32 v93, v109, v93, s28
	v_add3_u32 v92, v108, v92, s28
	v_lshrrev_b32_e32 v108, 16, v92
	v_lshrrev_b32_e32 v109, 16, v93
	v_lshrrev_b32_e32 v92, 16, v128
	v_lshrrev_b32_e32 v93, 16, v129
	v_and_or_b32 v93, v90, s29, v93
	v_and_or_b32 v92, v91, s29, v92
	v_and_or_b32 v91, v127, s29, v109
	v_and_or_b32 v90, v126, s29, v108
	v_bfe_u32 v108, v103, 16, 1
	v_bfe_u32 v109, v102, 16, 1
	v_bfe_u32 v126, v97, 16, 1
	v_bfe_u32 v127, v96, 16, 1
	v_add3_u32 v127, v96, v127, s28
	v_add3_u32 v126, v97, v126, s28
	v_add3_u32 v96, v102, v109, s28
	v_add3_u32 v97, v103, v108, s28
	v_bfe_u32 v103, v95, 16, 1
	v_bfe_u32 v108, v104, 16, 1
	v_bfe_u32 v109, v105, 16, 1
	v_bfe_u32 v102, v94, 16, 1
	v_add3_u32 v105, v105, v109, s28
	v_add3_u32 v104, v104, v108, s28
	v_add3_u32 v95, v95, v103, s28
	v_add3_u32 v94, v94, v102, s28
	v_lshrrev_b32_e32 v95, 16, v95
	v_lshrrev_b32_e32 v102, 16, v104
	v_lshrrev_b32_e32 v103, 16, v105
	s_waitcnt vmcnt(3)
	v_mul_f32_e32 v116, 0x3fb8aa3b, v116
	v_and_or_b32 v97, v97, s29, v103
	v_and_or_b32 v96, v96, s29, v102
	v_and_or_b32 v95, v126, s29, v95
	global_load_dwordx4 v[102:105], v[106:107], off offset:112
	s_nop 0
	global_load_dwordx4 v[106:109], v[106:107], off offset:96
	v_exp_f32_e32 v126, v116
	s_waitcnt vmcnt(4)
	v_mul_f32_e32 v116, 0x3fb8aa3b, v123
	v_exp_f32_e32 v128, v116
	v_mul_f32_e32 v116, 0x3fb8aa3b, v117
	v_exp_f32_e32 v130, v116
	v_mul_f32_e32 v116, 0x3fb8aa3b, v124
	v_lshrrev_b32_e32 v94, 16, v94
	v_mul_f32_e32 v122, 0x3fb8aa3b, v122
	v_exp_f32_e32 v123, v116
	v_mul_f32_e32 v116, 0x3fb8aa3b, v118
	v_and_or_b32 v94, v127, s29, v94
	v_exp_f32_e32 v122, v122
	v_exp_f32_e32 v127, v116
	v_mul_f32_e32 v116, 0x3fb8aa3b, v125
	v_exp_f32_e32 v129, v116
	v_mul_f32_e32 v116, 0x3fb8aa3b, v119
	v_exp_f32_e32 v131, v116
	global_load_dwordx4 v[116:119], v[110:111], off offset:48
	s_waitcnt vmcnt(4)
	v_lshlrev_b32_e32 v125, 16, v99
	v_lshlrev_b32_e32 v124, 16, v98
	v_pk_mul_f32 v[124:125], v[124:125], s[16:17] op_sel_hi:[1,0]
	v_rcp_f32_e32 v132, v122
	v_pk_mul_f32 v[136:137], v[124:125], v[122:123]
	v_rcp_f32_e32 v133, v123
	global_load_dwordx4 v[122:125], v[110:111], off offset:304
	v_rcp_f32_e32 v134, v128
	v_rcp_f32_e32 v135, v129
	v_and_b32_e32 v99, 0xffff0000, v99
	v_and_b32_e32 v98, 0xffff0000, v98
	v_pk_mul_f32 v[98:99], v[98:99], s[16:17] op_sel_hi:[1,0]
	s_waitcnt vmcnt(4)
	v_lshlrev_b32_e32 v111, 16, v113
	v_pk_mul_f32 v[98:99], v[98:99], v[128:129]
	v_lshlrev_b32_e32 v110, 16, v112
	v_and_b32_e32 v113, 0xffff0000, v113
	v_and_b32_e32 v112, 0xffff0000, v112
	v_rcp_f32_e32 v128, v126
	v_rcp_f32_e32 v129, v127
	v_pk_mul_f32 v[112:113], v[134:135], v[112:113]
	v_lshlrev_b32_e32 v135, 16, v101
	v_lshlrev_b32_e32 v134, 16, v100
	v_and_b32_e32 v101, 0xffff0000, v101
	v_and_b32_e32 v100, 0xffff0000, v100
	v_pk_mul_f32 v[134:135], v[134:135], s[16:17] op_sel_hi:[1,0]
	v_pk_mul_f32 v[100:101], v[100:101], s[16:17] op_sel_hi:[1,0]
	v_pk_mul_f32 v[110:111], v[132:133], v[110:111]
	v_rcp_f32_e32 v132, v130
	v_pk_mul_f32 v[134:135], v[134:135], v[126:127]
	v_pk_mul_f32 v[100:101], v[100:101], v[130:131]
	v_rcp_f32_e32 v133, v131
	v_lshlrev_b32_e32 v127, 16, v115
	v_lshlrev_b32_e32 v126, 16, v114
	v_pk_mul_f32 v[126:127], v[128:129], v[126:127]
	v_bfe_u32 v128, v101, 16, 1
	v_bfe_u32 v130, v99, 16, 1
	v_bfe_u32 v129, v100, 16, 1
	v_bfe_u32 v131, v98, 16, 1
	v_add3_u32 v99, v99, v130, s28
	v_add3_u32 v101, v101, v128, s28
	v_bfe_u32 v128, v136, 16, 1
	v_bfe_u32 v130, v134, 16, 1
	v_and_b32_e32 v115, 0xffff0000, v115
	v_and_b32_e32 v114, 0xffff0000, v114
	v_add3_u32 v98, v98, v131, s28
	v_add3_u32 v100, v100, v129, s28
	v_bfe_u32 v129, v137, 16, 1
	v_bfe_u32 v131, v135, 16, 1
	v_add3_u32 v130, v134, v130, s28
	v_add3_u32 v128, v136, v128, s28
	v_pk_mul_f32 v[114:115], v[132:133], v[114:115]
	v_add3_u32 v131, v135, v131, s28
	v_add3_u32 v129, v137, v129, s28
	v_lshrrev_b32_e32 v128, 16, v128
	v_lshrrev_b32_e32 v130, 16, v130
	v_lshrrev_b32_e32 v129, 16, v129
	v_lshrrev_b32_e32 v131, 16, v131
	v_and_or_b32 v100, v100, s29, v130
	v_and_or_b32 v98, v98, s29, v128
	v_bfe_u32 v128, v115, 16, 1
	v_bfe_u32 v130, v113, 16, 1
	v_and_or_b32 v101, v101, s29, v131
	v_and_or_b32 v99, v99, s29, v129
	v_bfe_u32 v129, v114, 16, 1
	v_bfe_u32 v131, v112, 16, 1
	v_add3_u32 v130, v113, v130, s28
	v_add3_u32 v113, v115, v128, s28
	v_bfe_u32 v128, v126, 16, 1
	v_add3_u32 v131, v112, v131, s28
	v_add3_u32 v112, v114, v129, s28
	v_bfe_u32 v114, v110, 16, 1
	v_bfe_u32 v129, v127, 16, 1
	v_add3_u32 v126, v126, v128, s28
	s_waitcnt vmcnt(3)
	v_mul_f32_e32 v103, 0x3fb8aa3b, v103
	v_bfe_u32 v115, v111, 16, 1
	v_add3_u32 v127, v127, v129, s28
	v_add3_u32 v110, v110, v114, s28
	v_lshrrev_b32_e32 v114, 16, v126
	s_waitcnt vmcnt(2)
	v_mul_f32_e32 v106, 0x3fb8aa3b, v106
	v_mul_f32_e32 v107, 0x3fb8aa3b, v107
	v_exp_f32_e32 v126, v103
	v_mul_f32_e32 v103, 0x3fb8aa3b, v108
	v_add3_u32 v111, v111, v115, s28
	v_lshrrev_b32_e32 v115, 16, v127
	v_and_or_b32 v112, v112, s29, v114
	v_exp_f32_e32 v106, v106
	v_exp_f32_e32 v114, v107
	v_exp_f32_e32 v107, v103
	v_mul_f32_e32 v103, 0x3fb8aa3b, v104
	v_mul_f32_e32 v104, 0x3fb8aa3b, v109
	v_and_or_b32 v113, v113, s29, v115
	v_exp_f32_e32 v115, v104
	v_mul_f32_e32 v104, 0x3fb8aa3b, v105
	v_mul_f32_e32 v102, 0x3fb8aa3b, v102
	v_exp_f32_e32 v127, v104
	v_rcp_f32_e32 v104, v106
	v_rcp_f32_e32 v105, v107
	v_exp_f32_e32 v102, v102
	v_exp_f32_e32 v103, v103
	v_rcp_f32_e32 v108, v114
	s_waitcnt vmcnt(1)
	v_lshlrev_b32_e32 v129, 16, v117
	v_lshlrev_b32_e32 v128, 16, v116
	v_rcp_f32_e32 v109, v115
	v_pk_mul_f32 v[128:129], v[128:129], s[16:17] op_sel_hi:[1,0]
	v_and_b32_e32 v117, 0xffff0000, v117
	v_pk_mul_f32 v[128:129], v[128:129], v[106:107]
	s_waitcnt vmcnt(0)
	v_lshlrev_b32_e32 v107, 16, v123
	v_lshlrev_b32_e32 v106, 16, v122
	v_and_b32_e32 v116, 0xffff0000, v116
	v_pk_mul_f32 v[106:107], v[104:105], v[106:107]
	v_and_b32_e32 v105, 0xffff0000, v123
	v_and_b32_e32 v104, 0xffff0000, v122
	v_pk_mul_f32 v[116:117], v[116:117], s[16:17] op_sel_hi:[1,0]
	v_pk_mul_f32 v[108:109], v[108:109], v[104:105]
	v_rcp_f32_e32 v104, v102
	v_rcp_f32_e32 v105, v103
	v_pk_mul_f32 v[116:117], v[116:117], v[114:115]
	v_rcp_f32_e32 v114, v126
	v_lshlrev_b32_e32 v123, 16, v119
	v_lshlrev_b32_e32 v122, 16, v118
	v_rcp_f32_e32 v115, v127
	v_pk_mul_f32 v[122:123], v[122:123], s[16:17] op_sel_hi:[1,0]
	v_and_b32_e32 v119, 0xffff0000, v119
	v_and_b32_e32 v118, 0xffff0000, v118
	v_pk_mul_f32 v[122:123], v[122:123], v[102:103]
	v_pk_mul_f32 v[118:119], v[118:119], s[16:17] op_sel_hi:[1,0]
	v_lshlrev_b32_e32 v103, 16, v125
	v_lshlrev_b32_e32 v102, 16, v124
	v_pk_mul_f32 v[118:119], v[118:119], v[126:127]
	v_pk_mul_f32 v[126:127], v[104:105], v[102:103]
	v_and_b32_e32 v103, 0xffff0000, v125
	v_and_b32_e32 v102, 0xffff0000, v124
	v_pk_mul_f32 v[114:115], v[114:115], v[102:103]
	v_bfe_u32 v102, v119, 16, 1
	v_bfe_u32 v103, v118, 16, 1
	v_bfe_u32 v104, v117, 16, 1
	v_bfe_u32 v105, v116, 16, 1
	v_add3_u32 v116, v116, v105, s28
	v_add3_u32 v117, v117, v104, s28
	v_add3_u32 v103, v118, v103, s28
	v_add3_u32 v102, v119, v102, s28
	v_bfe_u32 v104, v128, 16, 1
	v_bfe_u32 v105, v129, 16, 1
	v_bfe_u32 v118, v122, 16, 1
	v_bfe_u32 v119, v123, 16, 1
	v_add3_u32 v119, v123, v119, s28
	v_add3_u32 v118, v122, v118, s28
	v_add3_u32 v105, v129, v105, s28
	v_add3_u32 v104, v128, v104, s28
	v_lshrrev_b32_e32 v122, 16, v104
	v_lshrrev_b32_e32 v123, 16, v105
	v_lshrrev_b32_e32 v104, 16, v118
	v_lshrrev_b32_e32 v105, 16, v119
	v_and_or_b32 v105, v102, s29, v105
	v_and_or_b32 v104, v103, s29, v104
	v_and_or_b32 v103, v117, s29, v123
	v_and_or_b32 v102, v116, s29, v122
	v_bfe_u32 v116, v115, 16, 1
	v_bfe_u32 v117, v114, 16, 1
	v_bfe_u32 v118, v109, 16, 1
	v_bfe_u32 v119, v108, 16, 1
	v_add3_u32 v119, v108, v119, s28
	v_add3_u32 v118, v109, v118, s28
	v_add3_u32 v108, v114, v117, s28
	v_add3_u32 v109, v115, v116, s28
	v_bfe_u32 v114, v106, 16, 1
	v_bfe_u32 v115, v107, 16, 1
	v_bfe_u32 v116, v126, 16, 1
	v_bfe_u32 v117, v127, 16, 1
	v_add3_u32 v117, v127, v117, s28
	v_add3_u32 v116, v126, v116, s28
	v_add3_u32 v107, v107, v115, s28
	v_add3_u32 v106, v106, v114, s28
	v_lshrrev_b32_e32 v110, 16, v110
	v_lshrrev_b32_e32 v111, 16, v111
	v_lshrrev_b32_e32 v106, 16, v106
	v_lshrrev_b32_e32 v107, 16, v107
	v_lshrrev_b32_e32 v114, 16, v116
	v_lshrrev_b32_e32 v115, 16, v117
	s_waitcnt lgkmcnt(0)
	ds_write_b128 v142, v[82:85]
	ds_write_b128 v142, v[90:93] offset:16
	ds_write_b128 v142, v[98:101] offset:32
	ds_write_b128 v142, v[102:105] offset:48
	ds_write_b128 v142, v[18:21] offset:4096
	ds_write_b128 v142, v[46:49] offset:4112
	ds_write_b128 v142, v[74:77] offset:4128
	ds_write_b128 v142, v[78:81] offset:4144
	v_and_or_b32 v111, v130, s29, v111
	v_and_or_b32 v110, v131, s29, v110
	v_and_or_b32 v109, v109, s29, v115
	v_and_or_b32 v108, v108, s29, v114
	v_and_or_b32 v107, v118, s29, v107
	v_and_or_b32 v106, v119, s29, v106
	s_waitcnt lgkmcnt(0)
	ds_read_b128 v[134:137], v172
	ds_read_b128 v[98:101], v172 offset:1024
	ds_read_b128 v[46:49], v172 offset:2048
	ds_read_b128 v[18:21], v172 offset:3072
	s_waitcnt lgkmcnt(0)
	ds_write_b128 v142, v[86:89]
	ds_write_b128 v142, v[94:97] offset:16
	ds_write_b128 v142, v[110:113] offset:32
	ds_write_b128 v142, v[106:109] offset:48
	s_waitcnt lgkmcnt(0)
	ds_read_b128 v[78:81], v172 offset:4096
	ds_read_b128 v[82:85], v172
	s_waitcnt lgkmcnt(1)
	v_mfma_f32_16x16x32_bf16 v[110:113], v[78:81], v[98:101], v[26:29]
	s_nop 2
	ds_read_b128 v[26:29], v172 offset:5120
	ds_read_b128 v[94:97], v172 offset:6144
	ds_read_b128 v[90:93], v172 offset:7168
	ds_read_b128 v[86:89], v143 offset:1024
	v_mfma_f32_16x16x32_bf16 v[74:77], v[78:81], v[46:49], v[30:33]
	s_waitcnt lgkmcnt(3)
	v_mfma_f32_16x16x32_bf16 v[30:33], v[26:29], v[134:137], v[38:41]
	s_waitcnt lgkmcnt(0)
	v_mfma_f32_16x16x32_bf16 v[38:41], v[86:89], v[134:137], 0
	v_mfma_f32_16x16x32_bf16 v[122:125], v[78:81], v[134:137], v[22:25]
	v_mfma_f32_16x16x32_bf16 v[22:25], v[78:81], v[18:21], v[34:37]
	s_nop 5
	v_cndmask_b32_e64 v38, 0, v38, s[0:1]
	v_cmp_ge_i32_e64 s[0:1], v169, v140
	v_mfma_f32_16x16x32_bf16 v[34:37], v[82:85], v[134:137], 0
	v_mfma_f32_16x16x32_bf16 v[114:117], v[26:29], v[98:101], v[42:45]
	v_mfma_f32_16x16x32_bf16 v[102:105], v[90:93], v[98:101], v[70:73]
	s_nop 5
	v_cndmask_b32_e64 v34, v34, 0, vcc
	v_cndmask_b32_e64 v35, 0, v35, s[0:1]
	v_cmp_ge_i32_e64 s[0:1], v162, v140
	v_bfe_u32 v42, v34, 16, 1
	v_add3_u32 v34, v34, v42, s28
	v_cndmask_b32_e64 v39, 0, v39, s[0:1]
	v_cmp_ge_i32_e64 s[0:1], v164, v140
	v_bfe_u32 v42, v35, 16, 1
	v_lshrrev_b32_e32 v34, 16, v34
	v_cndmask_b32_e64 v36, 0, v36, s[0:1]
	v_cmp_ge_i32_e64 s[0:1], v163, v140
	v_add3_u32 v35, v35, v42, s28
	v_and_or_b32 v70, v35, s29, v34
	v_cndmask_b32_e64 v40, 0, v40, s[0:1]
	v_cmp_ge_i32_e64 s[0:1], v166, v140
	v_bfe_u32 v34, v36, 16, 1
	v_add3_u32 v34, v36, v34, s28
	v_cndmask_b32_e64 v37, 0, v37, s[0:1]
	v_bfe_u32 v35, v37, 16, 1
	v_lshrrev_b32_e32 v34, 16, v34
	v_add3_u32 v35, v37, v35, s28
	v_and_or_b32 v71, v35, s29, v34
	v_bfe_u32 v34, v38, 16, 1
	v_add3_u32 v34, v38, v34, s28
	v_bfe_u32 v35, v39, 16, 1
	v_cmp_ge_i32_e64 s[0:1], v165, v140
	v_lshrrev_b32_e32 v34, 16, v34
	v_add3_u32 v35, v39, v35, s28
	v_cndmask_b32_e64 v41, 0, v41, s[0:1]
	v_and_or_b32 v72, v35, s29, v34
	v_bfe_u32 v34, v40, 16, 1
	v_add3_u32 v34, v40, v34, s28
	v_bfe_u32 v39, v41, 16, 1
	v_lshrrev_b32_e32 v38, 16, v34
	v_add3_u32 v39, v41, v39, s28
	v_mfma_f32_16x16x32_bf16 v[78:81], v[26:29], v[46:49], v[50:53]
	v_and_or_b32 v73, v39, s29, v38
	v_cmp_ge_i32_e64 s[0:1], v169, v168
	v_mfma_f32_16x16x32_bf16 v[50:53], v[94:97], v[134:137], v[58:61]
	v_mfma_f32_16x16x32_bf16 v[106:109], v[94:97], v[98:101], v[62:65]
	s_nop 1
	ds_read2_b64 v[58:61], v144 offset1:4
	v_mfma_f32_16x16x32_bf16 v[34:37], v[82:85], v[98:101], 0
	ds_read2_b64 v[62:65], v145 offset1:4
	v_mfma_f32_16x16x32_bf16 v[38:41], v[86:89], v[98:101], 0
	v_mfma_f32_16x16x32_bf16 v[26:29], v[26:29], v[18:21], v[54:57]
	s_nop 4
	v_cndmask_b32_e64 v34, v34, 0, s[8:9]
	s_nop 0
	v_cndmask_b32_e64 v142, v38, 0, vcc
	v_cndmask_b32_e64 v38, 0, v35, s[0:1]
	v_mfma_f32_16x16x32_bf16 v[54:57], v[90:93], v[134:137], v[66:69]
	v_cmp_ge_i32_e64 s[0:1], v162, v168
	v_bfe_u32 v35, v34, 16, 1
	v_add3_u32 v34, v34, v35, s28
	ds_read2_b64 v[66:69], v171 offset1:4
	v_cndmask_b32_e64 v174, 0, v39, s[0:1]
	v_cmp_ge_i32_e64 s[0:1], v164, v168
	v_lshrrev_b32_e32 v39, 16, v34
	s_waitcnt lgkmcnt(0)
	v_mfma_f32_16x16x32_bf16 v[126:129], v[66:69], v[70:73], v[50:53]
	v_cndmask_b32_e64 v42, 0, v36, s[0:1]
	v_cmp_ge_i32_e64 s[0:1], v163, v168
	v_bfe_u32 v188, v174, 16, 1
	s_add_u32 s8, s25, s18
	v_cndmask_b32_e64 v172, 0, v40, s[0:1]
	v_cmp_ge_i32_e64 s[0:1], v166, v168
	v_bfe_u32 v40, v38, 16, 1
	v_add3_u32 v38, v38, v40, s28
	v_cndmask_b32_e64 v119, 0, v37, s[0:1]
	v_cmp_ge_i32_e64 s[0:1], v165, v168
	v_mfma_f32_16x16x32_bf16 v[34:37], v[58:61], v[70:73], v[122:125]
	v_and_or_b32 v118, v38, s29, v39
	v_cndmask_b32_e64 v175, 0, v41, s[0:1]
	ds_read2_b64 v[38:41], v170 offset1:4
	v_mfma_f32_16x16x32_bf16 v[122:125], v[62:65], v[70:73], v[30:33]
	v_bfe_u32 v51, v119, 16, 1
	v_add3_u32 v51, v119, v51, s28
	v_cmp_ge_i32_e64 s[0:1], v153, v140
	v_bfe_u32 v30, v42, 16, 1
	v_add3_u32 v30, v42, v30, s28
	ds_read_b128 v[42:45], v173
	v_lshrrev_b32_e32 v50, 16, v30
	ds_read_b128 v[30:33], v143 offset:3072
	s_waitcnt lgkmcnt(2)
	v_mfma_f32_16x16x32_bf16 v[130:133], v[38:41], v[70:73], v[54:57]
	v_and_or_b32 v119, v51, s29, v50
	s_addc_u32 s9, s26, 0
	s_lshr_b32 s98, s3, 6
	s_add_i32 s98, s98, 0x800
	s_and_b32 s99, s3, 0xfffff83f
	s_cmp_eq_u32 s99, 0
	s_cselect_b32 s3, s98, 0x1000
	v_bfe_u32 v54, v142, 16, 1
	s_waitcnt lgkmcnt(1)
	v_mfma_f32_16x16x32_bf16 v[50:53], v[42:45], v[134:137], 0
	v_add3_u32 v54, v142, v54, s28
	v_lshrrev_b32_e32 v173, 16, v54
	s_cmpk_lt_i32 s3, 0x820
	s_waitcnt lgkmcnt(0)
	v_mfma_f32_16x16x32_bf16 v[54:57], v[30:33], v[134:137], 0
	s_nop 2
	v_cndmask_b32_e64 v50, 0, v50, s[0:1]
	v_cmp_ge_i32_e64 s[0:1], v167, v140
	v_lshlrev_b64 v[136:137], 1, v[120:121]
	v_lshl_add_u64 v[134:135], v[120:121], 2, s[50:51]
	global_load_dwordx4 v[180:183], v[134:135], off
	v_cndmask_b32_e64 v54, 0, v54, s[0:1]
	v_cmp_ge_i32_e64 s[0:1], v155, v140
	v_bfe_u32 v121, v172, 16, 1
	v_add3_u32 v121, v172, v121, s28
	v_cndmask_b32_e64 v51, 0, v51, s[0:1]
	v_cmp_ge_i32_e64 s[0:1], v154, v140
	v_bfe_u32 v70, v51, 16, 1
	v_add3_u32 v51, v51, v70, s28
	v_cndmask_b32_e64 v55, 0, v55, s[0:1]
	v_cmp_ge_i32_e64 s[0:1], v157, v140
	v_bfe_u32 v70, v50, 16, 1
	v_add3_u32 v50, v50, v70, s28
	v_cndmask_b32_e64 v52, 0, v52, s[0:1]
	v_cmp_ge_i32_e64 s[0:1], v156, v140
	v_lshrrev_b32_e32 v50, 16, v50
	v_and_or_b32 v176, v51, s29, v50
	v_cndmask_b32_e64 v56, 0, v56, s[0:1]
	v_cmp_ge_i32_e64 s[0:1], v159, v140
	v_bfe_u32 v51, v52, 16, 1
	v_add3_u32 v51, v52, v51, s28
	v_cndmask_b32_e64 v53, 0, v53, s[0:1]
	v_bfe_u32 v50, v53, 16, 1
	v_cmp_ge_i32_e64 s[0:1], v158, v140
	v_add3_u32 v50, v53, v50, s28
	v_lshrrev_b32_e32 v51, 16, v51
	v_cndmask_b32_e64 v57, 0, v57, s[0:1]
	v_and_or_b32 v177, v50, s29, v51
	v_mad_i64_i32 v[50:51], s[0:1], v192, s27, v[138:139]
	v_lshl_add_u64 v[50:51], v[50:51], 0, s[18:19]
	v_lshl_add_u64 v[142:143], v[50:51], 0, v[136:137]
	global_load_dwordx2 v[194:195], v[142:143], off offset:1024
	v_bfe_u32 v51, v54, 16, 1
	ds_read2_b64 v[70:73], v144 offset0:8 offset1:12
	v_bfe_u32 v50, v55, 16, 1
	v_add3_u32 v51, v54, v51, s28
	v_add3_u32 v50, v55, v50, s28
	v_lshrrev_b32_e32 v51, 16, v51
	v_and_or_b32 v178, v50, s29, v51
	v_bfe_u32 v50, v57, 16, 1
	v_bfe_u32 v51, v56, 16, 1
	v_add3_u32 v50, v57, v50, s28
	v_add3_u32 v51, v56, v51, s28
	ds_read2_b64 v[54:57], v145 offset0:8 offset1:12
	v_lshrrev_b32_e32 v51, 16, v51
	v_and_or_b32 v179, v50, s29, v51
	ds_read2_b64 v[50:53], v171 offset0:8 offset1:12
	v_lshrrev_b32_e32 v121, 16, v121
	s_waitcnt lgkmcnt(2)
	v_mfma_f32_16x16x32_bf16 v[184:187], v[70:73], v[176:179], v[34:37]
	v_cmp_lt_i32_e64 s[0:1], v147, v148
	s_nop 1
	v_add3_u32 v34, v174, v188, s28
	v_and_or_b32 v120, v34, s29, v173
	ds_read2_b64 v[34:37], v170 offset0:8 offset1:12
	s_waitcnt lgkmcnt(2)
	v_mfma_f32_16x16x32_bf16 v[188:191], v[54:57], v[176:179], v[122:125]
	v_mul_f32_e32 v140, v185, v185
	v_fmac_f32_e32 v140, v184, v184
	v_fmac_f32_e32 v140, v186, v186
	s_waitcnt lgkmcnt(1)
	v_mfma_f32_16x16x32_bf16 v[126:129], v[50:53], v[176:179], v[126:129]
	v_fmac_f32_e32 v140, v187, v187
	s_nop 1
	v_fmac_f32_e32 v140, v188, v188
	v_bfe_u32 v122, v175, 16, 1
	v_fmac_f32_e32 v140, v189, v189
	v_add3_u32 v122, v175, v122, s28
	v_fmac_f32_e32 v140, v190, v190
	v_and_or_b32 v121, v122, s29, v121
	s_waitcnt lgkmcnt(0)
	v_mfma_f32_16x16x32_bf16 v[122:125], v[34:37], v[176:179], v[130:133]
	v_fmac_f32_e32 v140, v191, v191
	global_load_dwordx2 v[176:177], v[142:143], off offset:1056
	v_mov_b32_e32 v178, v184
	v_pk_mul_f32 v[132:133], v[126:127], v[126:127]
	v_cndmask_b32_e64 v130, v146, v147, s[0:1]
	v_add_f32_e32 v132, v140, v132
	v_lshlrev_b32_e32 v170, 2, v130
	v_pk_mul_f32 v[130:131], v[128:129], v[128:129]
	v_add_f32_e32 v132, v133, v132
	v_add_f32_e32 v130, v130, v132
	v_add_f32_e32 v140, v131, v130
	v_pk_mul_f32 v[132:133], v[122:123], v[122:123]
	v_pk_mul_f32 v[130:131], v[124:125], v[124:125]
	v_add_f32_e32 v132, v140, v132
	v_add_f32_e32 v132, v133, v132
	v_add_f32_e32 v130, v130, v132
	v_add_f32_e32 v140, v131, v130
	ds_bpermute_b32 v144, v170, v140
	v_cmp_lt_i32_e64 s[0:1], v149, v148
	v_mfma_f32_16x16x32_bf16 v[130:133], v[58:61], v[118:121], v[110:113]
	v_mov_b32_e32 v179, v186
	v_mov_b32_e32 v186, v185
	s_waitcnt lgkmcnt(0)
	v_add_f32_e32 v140, v140, v144
	v_cndmask_b32_e64 v110, v146, v149, s[0:1]
	v_lshlrev_b32_e32 v171, 2, v110
	ds_bpermute_b32 v144, v171, v140
	v_mfma_f32_16x16x32_bf16 v[110:113], v[62:65], v[118:121], v[114:117]
	s_waitcnt lgkmcnt(0)
	s_nop 1
	v_add_f32_e32 v114, v140, v144
	v_fmamk_f32 v114, v114, 0x3c800000, v150
	v_mul_f32_e32 v115, 0x4b800000, v114
	v_cmp_gt_f32_e64 s[0:1], s30, v114
	v_mfma_f32_16x16x32_bf16 v[10:13], v[94:97], v[46:49], v[10:13]
	s_nop 0
	v_cndmask_b32_e64 v114, v114, v115, s[0:1]
	v_rsq_f32_e32 v140, v114
	v_mfma_f32_16x16x32_bf16 v[114:117], v[66:69], v[118:121], v[106:109]
	s_nop 2
	v_mul_f32_e32 v106, 0x45800000, v140
	s_waitcnt vmcnt(1)
	v_lshlrev_b32_e32 v108, 16, v194
	v_mul_f32_e32 v144, 0xbfb8aa3b, v108
	v_exp_f32_e32 v145, v144
	v_and_b32_e32 v144, 0xffff0000, v194
	v_mul_f32_e32 v172, 0xbfb8aa3b, v144
	v_exp_f32_e32 v173, v172
	v_lshlrev_b32_e32 v109, 16, v195
	v_add_f32_e32 v145, 1.0, v145
	v_rcp_f32_e32 v172, v145
	v_add_f32_e32 v173, 1.0, v173
	v_rcp_f32_e32 v174, v173
	v_mul_f32_e32 v173, 0xbfb8aa3b, v109
	v_exp_f32_e32 v173, v173
	v_and_b32_e32 v145, 0xffff0000, v195
	v_mul_f32_e32 v175, 0xbfb8aa3b, v145
	v_exp_f32_e32 v175, v175
	v_add_f32_e32 v173, 1.0, v173
	v_rcp_f32_e32 v173, v173
	v_cndmask_b32_e64 v140, v140, v106, s[0:1]
	v_lshlrev_b64 v[106:107], 11, v[192:193]
	v_pk_mul_f32 v[178:179], v[178:179], v[140:141] op_sel_hi:[1,0]
	v_pk_mul_f32 v[108:109], v[172:173], v[108:109]
	v_add_f32_e32 v172, 1.0, v175
	v_rcp_f32_e32 v175, v172
	v_mov_b32_e32 v192, v180
	v_mov_b32_e32 v193, v182
	v_pk_mul_f32 v[178:179], v[192:193], v[178:179]
	v_pk_mul_f32 v[172:173], v[186:187], v[140:141] op_sel_hi:[1,0]
	v_mov_b32_e32 v182, v181
	v_pk_mul_f32 v[108:109], v[108:109], v[178:179]
	v_pk_mul_f32 v[172:173], v[182:183], v[172:173]
	v_pk_mul_f32 v[144:145], v[174:175], v[144:145]
	v_lshl_add_u64 v[106:107], s[8:9], 0, v[106:107]
	v_pk_mul_f32 v[144:145], v[144:145], v[172:173]
	v_and_b32_sdwa v172, v109, v151 dst_sel:DWORD dst_unused:UNUSED_PAD src0_sel:WORD_1 src1_sel:DWORD
	v_and_b32_sdwa v173, v108, v151 dst_sel:DWORD dst_unused:UNUSED_PAD src0_sel:WORD_1 src1_sel:DWORD
	v_add3_u32 v108, v108, v173, s28
	v_add3_u32 v109, v109, v172, s28
	v_and_b32_sdwa v172, v145, v151 dst_sel:DWORD dst_unused:UNUSED_PAD src0_sel:WORD_1 src1_sel:DWORD
	v_and_b32_sdwa v173, v144, v151 dst_sel:DWORD dst_unused:UNUSED_PAD src0_sel:WORD_1 src1_sel:DWORD
	v_add3_u32 v145, v145, v172, s28
	v_add3_u32 v144, v144, v173, s28
	v_and_b32_e32 v145, 0xffff0000, v145
	v_and_b32_e32 v144, 0xffff0000, v144
	v_or_b32_sdwa v109, v145, v109 dst_sel:DWORD dst_unused:UNUSED_PAD src0_sel:DWORD src1_sel:WORD_1
	v_or_b32_sdwa v108, v144, v108 dst_sel:DWORD dst_unused:UNUSED_PAD src0_sel:DWORD src1_sel:WORD_1
	v_lshl_add_u64 v[144:145], v[106:107], 0, v[136:137]
	global_store_dwordx2 v[144:145], v[108:109], off
	global_load_dwordx4 v[172:175], v[134:135], off offset:64
	v_mfma_f32_16x16x32_bf16 v[106:109], v[38:41], v[118:121], v[102:105]
	s_waitcnt vmcnt(2)
	v_lshlrev_b32_e32 v119, 16, v176
	v_and_b32_e32 v179, 0xffff0000, v176
	v_mul_f32_e32 v118, v188, v140
	v_mul_f32_e32 v102, 0xbfb8aa3b, v119
	v_exp_f32_e32 v120, v102
	v_lshlrev_b32_e32 v181, 16, v177
	v_and_b32_e32 v177, 0xffff0000, v177
	v_mul_f32_e32 v178, v189, v140
	v_add_f32_e32 v120, 1.0, v120
	v_rcp_f32_e32 v121, v120
	v_mul_f32_e32 v176, v191, v140
	v_mul_f32_e32 v180, v190, v140
	v_mfma_f32_16x16x32_bf16 v[102:105], v[42:45], v[98:101], 0
	v_cmp_ge_i32_e64 s[0:1], v153, v168
	s_waitcnt vmcnt(0)
	v_mov_b32_e32 v120, v172
	v_mul_f32_e32 v172, 0xbfb8aa3b, v179
	v_exp_f32_e32 v172, v172
	v_pk_mul_f32 v[118:119], v[120:121], v[118:119]
	v_mov_b32_e32 v120, v173
	v_pk_mul_f32 v[118:119], v[118:119], v[118:119] op_sel:[0,1] op_sel_hi:[1,0]
	v_mfma_f32_16x16x32_bf16 v[98:101], v[30:33], v[98:101], 0
	v_add_f32_e32 v119, 1.0, v172
	v_rcp_f32_e32 v121, v119
	v_mul_f32_e32 v119, 0xbfb8aa3b, v181
	v_exp_f32_e32 v119, v119
	v_mov_b32_e32 v172, v174
	v_pk_mul_f32 v[120:121], v[120:121], v[178:179]
	v_mov_b32_e32 v178, v175
	v_add_f32_e32 v119, 1.0, v119
	v_rcp_f32_e32 v173, v119
	v_mul_f32_e32 v119, 0xbfb8aa3b, v177
	v_exp_f32_e32 v119, v119
	v_pk_mul_f32 v[120:121], v[120:121], v[120:121] op_sel:[0,1] op_sel_hi:[1,0]
	v_pk_mul_f32 v[172:173], v[172:173], v[180:181]
	v_cndmask_b32_e64 v102, 0, v102, s[0:1]
	v_add_f32_e32 v119, 1.0, v119
	v_rcp_f32_e32 v179, v119
	v_bfe_u32 v119, v118, 16, 1
	v_add3_u32 v118, v118, v119, s28
	v_bfe_u32 v119, v120, 16, 1
	v_pk_mul_f32 v[174:175], v[178:179], v[176:177]
	global_load_dwordx2 v[176:177], v[142:143], off offset:1088
	v_pk_mul_f32 v[172:173], v[172:173], v[172:173] op_sel:[0,1] op_sel_hi:[1,0]
	v_lshrrev_b32_e32 v118, 16, v118
	v_add3_u32 v119, v120, v119, s28
	v_pk_mul_f32 v[174:175], v[174:175], v[174:175] op_sel:[0,1] op_sel_hi:[1,0]
	v_and_or_b32 v118, v119, s29, v118
	v_bfe_u32 v119, v172, 16, 1
	v_add3_u32 v119, v172, v119, s28
	v_bfe_u32 v120, v174, 16, 1
	v_lshrrev_b32_e32 v119, 16, v119
	v_add3_u32 v120, v174, v120, s28
	v_and_or_b32 v119, v120, s29, v119
	global_store_dwordx2 v[144:145], v[118:119], off offset:32
	global_load_dwordx4 v[172:175], v[134:135], off offset:128
	v_cmp_ge_i32_e64 s[0:1], v167, v168
	global_load_dwordx2 v[142:143], v[142:143], off offset:1120
	v_mfma_f32_16x16x32_bf16 v[6:9], v[94:97], v[18:21], v[6:9]
	v_cndmask_b32_e64 v118, 0, v98, s[0:1]
	v_cmp_ge_i32_e64 s[0:1], v155, v168
	v_mfma_f32_16x16x32_bf16 v[14:17], v[90:93], v[46:49], v[14:17]
	s_nop 0
	v_cndmask_b32_e64 v98, 0, v103, s[0:1]
	v_cmp_ge_i32_e64 s[0:1], v154, v168
	v_mfma_f32_16x16x32_bf16 v[2:5], v[90:93], v[18:21], v[2:5]
	s_nop 0
	v_cndmask_b32_e64 v103, 0, v99, s[0:1]
	v_cmp_ge_i32_e64 s[0:1], v157, v168
	s_nop 1
	v_cndmask_b32_e64 v99, 0, v104, s[0:1]
	v_cmp_ge_i32_e64 s[0:1], v156, v168
	s_nop 1
	v_cndmask_b32_e64 v104, 0, v100, s[0:1]
	v_cmp_ge_i32_e64 s[0:1], v159, v168
	s_nop 1
	v_cndmask_b32_e64 v100, 0, v105, s[0:1]
	v_bfe_u32 v105, v98, 16, 1
	v_add3_u32 v98, v98, v105, s28
	v_bfe_u32 v105, v102, 16, 1
	v_add3_u32 v102, v102, v105, s28
	v_lshrrev_b32_e32 v102, 16, v102
	v_and_or_b32 v98, v98, s29, v102
	v_bfe_u32 v102, v100, 16, 1
	v_add3_u32 v100, v100, v102, s28
	v_bfe_u32 v102, v99, 16, 1
	v_add3_u32 v99, v99, v102, s28
	v_lshrrev_b32_e32 v99, 16, v99
	v_bfe_u32 v102, v118, 16, 1
	v_cmp_ge_i32_e64 s[0:1], v158, v168
	v_and_or_b32 v99, v100, s29, v99
	v_bfe_u32 v100, v103, 16, 1
	v_add3_u32 v102, v118, v102, s28
	v_cndmask_b32_e64 v101, 0, v101, s[0:1]
	v_add3_u32 v100, v103, v100, s28
	v_lshrrev_b32_e32 v102, 16, v102
	v_and_or_b32 v100, v100, s29, v102
	v_bfe_u32 v102, v101, 16, 1
	v_add3_u32 v101, v101, v102, s28
	v_bfe_u32 v102, v104, 16, 1
	v_add3_u32 v102, v104, v102, s28
	v_lshrrev_b32_e32 v102, 16, v102
	v_and_or_b32 v101, v101, s29, v102
	v_mul_f32_e32 v102, v126, v140
	s_waitcnt vmcnt(3)
	v_lshlrev_b32_e32 v103, 16, v176
	v_mul_f32_e32 v104, 0xbfb8aa3b, v103
	v_exp_f32_e32 v104, v104
	v_mfma_f32_16x16x32_bf16 v[118:121], v[70:73], v[98:101], v[130:133]
	v_add_f32_e32 v104, 1.0, v104
	v_rcp_f32_e32 v105, v104
	s_nop 0
	v_and_b32_e32 v131, 0xffff0000, v176
	v_mul_f32_e32 v126, 0xbfb8aa3b, v131
	v_exp_f32_e32 v126, v126
	v_mul_f32_e32 v130, v127, v140
	v_lshlrev_b32_e32 v127, 16, v177
	s_waitcnt vmcnt(1)
	v_mov_b32_e32 v104, v172
	v_pk_mul_f32 v[102:103], v[104:105], v[102:103]
	v_mov_b32_e32 v104, v173
	v_pk_mul_f32 v[102:103], v[102:103], v[102:103] op_sel:[0,1] op_sel_hi:[1,0]
	v_and_b32_e32 v133, 0xffff0000, v177
	v_add_f32_e32 v103, 1.0, v126
	v_rcp_f32_e32 v105, v103
	v_mul_f32_e32 v103, 0xbfb8aa3b, v127
	v_exp_f32_e32 v103, v103
	v_mul_f32_e32 v126, v128, v140
	v_pk_mul_f32 v[104:105], v[104:105], v[130:131]
	v_mov_b32_e32 v130, v174
	v_add_f32_e32 v103, 1.0, v103
	v_rcp_f32_e32 v131, v103
	v_mul_f32_e32 v103, 0xbfb8aa3b, v133
	v_exp_f32_e32 v103, v103
	v_pk_mul_f32 v[104:105], v[104:105], v[104:105] op_sel:[0,1] op_sel_hi:[1,0]
	v_pk_mul_f32 v[126:127], v[130:131], v[126:127]
	v_mul_f32_e32 v132, v129, v140
	v_add_f32_e32 v103, 1.0, v103
	v_rcp_f32_e32 v131, v103
	v_bfe_u32 v103, v102, 16, 1
	v_mov_b32_e32 v130, v175
	v_add3_u32 v102, v102, v103, s28
	v_bfe_u32 v103, v104, 16, 1
	v_pk_mul_f32 v[126:127], v[126:127], v[126:127] op_sel:[0,1] op_sel_hi:[1,0]
	v_pk_mul_f32 v[128:129], v[130:131], v[132:133]
	v_lshrrev_b32_e32 v102, 16, v102
	v_add3_u32 v103, v104, v103, s28
	v_pk_mul_f32 v[128:129], v[128:129], v[128:129] op_sel:[0,1] op_sel_hi:[1,0]
	v_and_or_b32 v102, v103, s29, v102
	v_bfe_u32 v103, v126, 16, 1
	v_add3_u32 v103, v126, v103, s28
	v_bfe_u32 v104, v128, 16, 1
	v_lshrrev_b32_e32 v103, 16, v103
	v_add3_u32 v104, v128, v104, s28
	v_and_or_b32 v103, v104, s29, v103
	global_store_dwordx2 v[144:145], v[102:103], off offset:64
	global_load_dwordx4 v[126:129], v[134:135], off offset:192
	s_waitcnt vmcnt(2)
	v_lshlrev_b32_e32 v131, 16, v142
	v_mul_f32_e32 v102, 0xbfb8aa3b, v131
	v_exp_f32_e32 v130, v102
	v_mfma_f32_16x16x32_bf16 v[102:105], v[50:53], v[98:101], v[114:117]
	s_nop 2
	v_add_f32_e32 v115, 1.0, v130
	v_rcp_f32_e32 v115, v115
	v_and_b32_e32 v117, 0xffff0000, v142
	v_mul_f32_e32 v116, 0xbfb8aa3b, v117
	v_exp_f32_e32 v116, v116
	v_mul_f32_e32 v114, v122, v140
	v_mul_f32_e32 v122, v123, v140
	v_mfma_f32_16x16x32_bf16 v[110:113], v[54:57], v[98:101], v[110:113]
	s_waitcnt vmcnt(0)
	v_mov_b32_e32 v130, v126
	v_pk_mul_f32 v[114:115], v[114:115], v[130:131]
	v_lshlrev_b32_e32 v131, 16, v143
	v_pk_mul_f32 v[114:115], v[114:115], v[114:115] op_sel:[0,1] op_sel_hi:[1,0]
	v_mov_b32_e32 v130, v128
	v_add_f32_e32 v115, 1.0, v116
	v_rcp_f32_e32 v123, v115
	v_mul_f32_e32 v115, 0xbfb8aa3b, v131
	v_exp_f32_e32 v115, v115
	v_mov_b32_e32 v116, v127
	v_and_b32_e32 v127, 0xffff0000, v143
	v_pk_mul_f32 v[116:117], v[122:123], v[116:117]
	v_add_f32_e32 v115, 1.0, v115
	v_rcp_f32_e32 v123, v115
	v_mul_f32_e32 v115, 0xbfb8aa3b, v127
	v_exp_f32_e32 v115, v115
	v_mul_f32_e32 v122, v124, v140
	v_pk_mul_f32 v[122:123], v[122:123], v[130:131]
	v_pk_mul_f32 v[116:117], v[116:117], v[116:117] op_sel:[0,1] op_sel_hi:[1,0]
	v_add_f32_e32 v115, 1.0, v115
	v_rcp_f32_e32 v131, v115
	v_bfe_u32 v115, v114, 16, 1
	v_mul_f32_e32 v130, v125, v140
	v_mov_b32_e32 v126, v129
	v_add3_u32 v114, v114, v115, s28
	v_bfe_u32 v115, v116, 16, 1
	v_pk_mul_f32 v[124:125], v[130:131], v[126:127]
	v_lshrrev_b32_e32 v114, 16, v114
	v_add3_u32 v115, v116, v115, s28
	v_or_b32_e32 v126, s31, v168
	v_and_or_b32 v116, v115, s29, v114
	v_mad_i64_i32 v[114:115], s[0:1], v126, s27, v[138:139]
	v_lshl_add_u64 v[114:115], v[114:115], 0, s[18:19]
	v_lshl_add_u64 v[114:115], v[114:115], 0, v[136:137]
	global_load_dwordx2 v[128:129], v[114:115], off offset:1024
	v_pk_mul_f32 v[122:123], v[122:123], v[122:123] op_sel:[0,1] op_sel_hi:[1,0]
	v_pk_mul_f32 v[124:125], v[124:125], v[124:125] op_sel:[0,1] op_sel_hi:[1,0]
	v_bfe_u32 v117, v122, 16, 1
	v_add3_u32 v117, v122, v117, s28
	v_bfe_u32 v122, v124, 16, 1
	v_lshrrev_b32_e32 v117, 16, v117
	v_add3_u32 v122, v124, v122, s28
	v_and_or_b32 v117, v122, s29, v117
	global_store_dwordx2 v[144:145], v[116:117], off offset:96
	global_load_dwordx4 v[122:125], v[134:135], off
	v_mul_f32_e32 v116, v119, v119
	v_fmac_f32_e32 v116, v118, v118
	v_fmac_f32_e32 v116, v120, v120
	v_fmac_f32_e32 v116, v121, v121
	v_fmac_f32_e32 v116, v110, v110
	v_fmac_f32_e32 v116, v111, v111
	v_fmac_f32_e32 v116, v112, v112
	v_mfma_f32_16x16x32_bf16 v[98:101], v[34:37], v[98:101], v[106:109]
	v_fmac_f32_e32 v116, v113, v113
	v_ashrrev_i32_e32 v127, 31, v126
	s_nop 0
	v_pk_mul_f32 v[108:109], v[102:103], v[102:103]
	v_pk_mul_f32 v[106:107], v[104:105], v[104:105]
	v_add_f32_e32 v108, v116, v108
	v_add_f32_e32 v108, v109, v108
	v_add_f32_e32 v106, v106, v108
	v_add_f32_e32 v116, v107, v106
	v_pk_mul_f32 v[108:109], v[98:99], v[98:99]
	v_pk_mul_f32 v[106:107], v[100:101], v[100:101]
	v_add_f32_e32 v108, v116, v108
	v_add_f32_e32 v108, v109, v108
	v_add_f32_e32 v106, v106, v108
	v_add_f32_e32 v106, v107, v106
	ds_bpermute_b32 v107, v170, v106
	global_load_dwordx2 v[116:117], v[114:115], off offset:1056
	s_waitcnt lgkmcnt(0)
	v_add_f32_e32 v106, v106, v107
	ds_bpermute_b32 v107, v171, v106
	s_waitcnt lgkmcnt(0)
	v_add_f32_e32 v94, v106, v107
	v_fmamk_f32 v94, v94, 0x3c800000, v150
	v_mul_f32_e32 v95, 0x4b800000, v94
	v_cmp_gt_f32_e64 s[0:1], s30, v94
	s_waitcnt vmcnt(3)
	v_lshlrev_b32_e32 v96, 16, v128
	v_cndmask_b32_e64 v94, v94, v95, s[0:1]
	v_rsq_f32_e32 v94, v94
	v_mul_f32_e32 v106, 0xbfb8aa3b, v96
	v_exp_f32_e32 v107, v106
	v_and_b32_e32 v106, 0xffff0000, v128
	v_mul_f32_e32 v95, 0x45800000, v94
	v_cndmask_b32_e64 v130, v94, v95, s[0:1]
	v_mul_f32_e32 v108, 0xbfb8aa3b, v106
	v_mul_f32_e32 v97, v118, v130
	v_exp_f32_e32 v118, v108
	v_add_f32_e32 v107, 1.0, v107
	v_rcp_f32_e32 v108, v107
	s_waitcnt vmcnt(1)
	v_mov_b32_e32 v109, v122
	v_add_f32_e32 v107, 1.0, v118
	v_rcp_f32_e32 v122, v107
	v_pk_mul_f32 v[96:97], v[108:109], v[96:97]
	v_mul_f32_e32 v107, v119, v130
	v_pk_mul_f32 v[96:97], v[96:97], v[96:97] op_sel:[0,1] op_sel_hi:[1,0]
	v_pk_mul_f32 v[106:107], v[122:123], v[106:107]
	v_lshlrev_b32_e32 v108, 16, v129
	v_pk_mul_f32 v[106:107], v[106:107], v[106:107] op_sel:[0,1] op_sel_hi:[1,0]
	v_mul_f32_e32 v97, 0xbfb8aa3b, v108
	v_and_b32_e32 v118, 0xffff0000, v129
	v_exp_f32_e32 v97, v97
	v_mul_f32_e32 v107, 0xbfb8aa3b, v118
	v_exp_f32_e32 v107, v107
	v_mov_b32_e32 v123, v124
	v_add_f32_e32 v97, 1.0, v97
	v_rcp_f32_e32 v122, v97
	v_add_f32_e32 v97, 1.0, v107
	v_rcp_f32_e32 v124, v97
	v_mul_f32_e32 v109, v120, v130
	v_bfe_u32 v97, v96, 16, 1
	v_pk_mul_f32 v[108:109], v[122:123], v[108:109]
	v_mul_f32_e32 v119, v121, v130
	v_add3_u32 v96, v96, v97, s28
	v_bfe_u32 v97, v106, 16, 1
	v_pk_mul_f32 v[108:109], v[108:109], v[108:109] op_sel:[0,1] op_sel_hi:[1,0]
	v_pk_mul_f32 v[118:119], v[124:125], v[118:119]
	v_lshrrev_b32_e32 v96, 16, v96
	v_add3_u32 v97, v106, v97, s28
	v_pk_mul_f32 v[118:119], v[118:119], v[118:119] op_sel:[0,1] op_sel_hi:[1,0]
	v_and_or_b32 v96, v97, s29, v96
	v_bfe_u32 v97, v108, 16, 1
	v_lshlrev_b64 v[94:95], 11, v[126:127]
	v_add3_u32 v97, v108, v97, s28
	v_bfe_u32 v106, v118, 16, 1
	v_lshl_add_u64 v[94:95], s[8:9], 0, v[94:95]
	v_lshrrev_b32_e32 v97, 16, v97
	v_add3_u32 v106, v118, v106, s28
	v_and_or_b32 v97, v106, s29, v97
	v_lshl_add_u64 v[94:95], v[94:95], 0, v[136:137]
	global_store_dwordx2 v[94:95], v[96:97], off
	global_load_dwordx4 v[106:109], v[134:135], off offset:64
	s_waitcnt vmcnt(2)
	v_lshlrev_b32_e32 v97, 16, v116
	v_mul_f32_e32 v90, 0xbfb8aa3b, v97
	v_exp_f32_e32 v118, v90
	v_mul_f32_e32 v96, v110, v130
	v_and_b32_e32 v121, 0xffff0000, v116
	v_mul_f32_e32 v120, v111, v130
	v_add_f32_e32 v110, 1.0, v118
	v_rcp_f32_e32 v119, v110
	v_mul_f32_e32 v116, v113, v130
	v_mfma_f32_16x16x32_bf16 v[90:93], v[82:85], v[46:49], 0
	v_cmp_ge_i32_e64 s[0:1], v161, v160
	s_waitcnt vmcnt(0)
	v_mov_b32_e32 v118, v106
	v_mul_f32_e32 v106, 0xbfb8aa3b, v121
	v_exp_f32_e32 v106, v106
	v_pk_mul_f32 v[96:97], v[118:119], v[96:97]
	v_lshlrev_b32_e32 v119, 16, v117
	v_pk_mul_f32 v[96:97], v[96:97], v[96:97] op_sel:[0,1] op_sel_hi:[1,0]
	v_mov_b32_e32 v110, v107
	v_add_f32_e32 v97, 1.0, v106
	v_rcp_f32_e32 v111, v97
	v_mul_f32_e32 v97, 0xbfb8aa3b, v119
	v_exp_f32_e32 v97, v97
	v_and_b32_e32 v117, 0xffff0000, v117
	v_pk_mul_f32 v[106:107], v[110:111], v[120:121]
	v_mul_f32_e32 v118, v112, v130
	v_add_f32_e32 v97, 1.0, v97
	v_rcp_f32_e32 v111, v97
	v_mul_f32_e32 v97, 0xbfb8aa3b, v117
	v_exp_f32_e32 v97, v97
	v_mov_b32_e32 v110, v108
	v_pk_mul_f32 v[110:111], v[110:111], v[118:119]
	v_mov_b32_e32 v118, v109
	v_add_f32_e32 v97, 1.0, v97
	v_rcp_f32_e32 v119, v97
	v_pk_mul_f32 v[106:107], v[106:107], v[106:107] op_sel:[0,1] op_sel_hi:[1,0]
	v_bfe_u32 v97, v96, 16, 1
	v_add3_u32 v96, v96, v97, s28
	v_pk_mul_f32 v[108:109], v[118:119], v[116:117]
	global_load_dwordx2 v[116:117], v[114:115], off offset:1088
	v_bfe_u32 v97, v106, 16, 1
	v_pk_mul_f32 v[110:111], v[110:111], v[110:111] op_sel:[0,1] op_sel_hi:[1,0]
	v_lshrrev_b32_e32 v96, 16, v96
	v_add3_u32 v97, v106, v97, s28
	v_pk_mul_f32 v[108:109], v[108:109], v[108:109] op_sel:[0,1] op_sel_hi:[1,0]
	v_and_or_b32 v96, v97, s29, v96
	v_bfe_u32 v97, v110, 16, 1
	v_add3_u32 v97, v110, v97, s28
	v_bfe_u32 v106, v108, 16, 1
	v_lshrrev_b32_e32 v97, 16, v97
	v_add3_u32 v106, v108, v106, s28
	v_and_or_b32 v97, v106, s29, v97
	global_store_dwordx2 v[94:95], v[96:97], off offset:32
	global_load_dwordx4 v[106:109], v[134:135], off offset:128
	v_mfma_f32_16x16x32_bf16 v[110:113], v[86:89], v[46:49], 0
	v_cndmask_b32_e64 v90, v90, 0, s[6:7]
	v_bfe_u32 v97, v90, 16, 1
	v_add3_u32 v90, v90, v97, s28
	v_lshrrev_b32_e32 v90, 16, v90
	v_mfma_f32_16x16x32_bf16 v[86:89], v[86:89], v[18:21], 0
	s_nop 2
	v_cndmask_b32_e64 v96, 0, v110, s[0:1]
	v_cmp_ge_i32_e64 s[0:1], v169, v160
	v_mfma_f32_16x16x32_bf16 v[82:85], v[82:85], v[18:21], 0
	s_nop 0
	v_cndmask_b32_e64 v91, 0, v91, s[0:1]
	v_cmp_ge_i32_e64 s[0:1], v162, v160
	v_bfe_u32 v97, v91, 16, 1
	v_add3_u32 v91, v91, v97, s28
	v_cndmask_b32_e64 v118, 0, v111, s[0:1]
	v_cmp_ge_i32_e64 s[0:1], v164, v160
	v_and_or_b32 v90, v91, s29, v90
	s_nop 0
	v_cndmask_b32_e64 v92, 0, v92, s[0:1]
	v_cmp_ge_i32_e64 s[0:1], v163, v160
	v_bfe_u32 v91, v92, 16, 1
	v_add3_u32 v91, v92, v91, s28
	v_cndmask_b32_e64 v119, 0, v112, s[0:1]
	v_cmp_ge_i32_e64 s[0:1], v166, v160
	v_lshrrev_b32_e32 v91, 16, v91
	v_mul_f32_e32 v112, v103, v130
	v_cndmask_b32_e64 v93, 0, v93, s[0:1]
	v_bfe_u32 v92, v93, 16, 1
	v_add3_u32 v92, v93, v92, s28
	v_and_or_b32 v91, v92, s29, v91
	v_bfe_u32 v92, v96, 16, 1
	v_add3_u32 v92, v96, v92, s28
	global_load_dwordx2 v[96:97], v[114:115], off offset:1120
	v_cmp_ge_i32_e64 s[0:1], v165, v160
	v_lshrrev_b32_e32 v114, 16, v92
	v_mul_f32_e32 v92, v102, v130
	v_cndmask_b32_e64 v120, 0, v113, s[0:1]
	v_cmp_ge_i32_e64 s[0:1], v161, v152
	v_bfe_u32 v115, v118, 16, 1
	s_waitcnt vmcnt(3)
	v_lshlrev_b32_e32 v93, 16, v116
	v_mul_f32_e32 v110, 0xbfb8aa3b, v93
	v_exp_f32_e32 v110, v110
	v_and_b32_e32 v113, 0xffff0000, v116
	v_add_f32_e32 v102, 1.0, v110
	v_rcp_f32_e32 v111, v102
	v_mul_f32_e32 v102, 0xbfb8aa3b, v113
	v_exp_f32_e32 v102, v102
	s_waitcnt vmcnt(1)
	v_mov_b32_e32 v110, v106
	v_pk_mul_f32 v[92:93], v[110:111], v[92:93]
	v_lshlrev_b32_e32 v111, 16, v117
	v_pk_mul_f32 v[92:93], v[92:93], v[92:93] op_sel:[0,1] op_sel_hi:[1,0]
	v_mul_f32_e32 v110, v104, v130
	v_add_f32_e32 v93, 1.0, v102
	v_rcp_f32_e32 v103, v93
	v_mul_f32_e32 v93, 0xbfb8aa3b, v111
	v_exp_f32_e32 v93, v93
	v_mov_b32_e32 v102, v107
	v_pk_mul_f32 v[102:103], v[102:103], v[112:113]
	v_and_b32_e32 v113, 0xffff0000, v117
	v_add_f32_e32 v93, 1.0, v93
	v_rcp_f32_e32 v107, v93
	v_mul_f32_e32 v93, 0xbfb8aa3b, v113
	v_exp_f32_e32 v93, v93
	v_mov_b32_e32 v106, v108
	v_pk_mul_f32 v[106:107], v[106:107], v[110:111]
	v_pk_mul_f32 v[102:103], v[102:103], v[102:103] op_sel:[0,1] op_sel_hi:[1,0]
	v_add_f32_e32 v93, 1.0, v93
	v_rcp_f32_e32 v111, v93
	v_bfe_u32 v93, v92, 16, 1
	v_mul_f32_e32 v112, v105, v130
	v_mov_b32_e32 v110, v109
	v_add3_u32 v92, v92, v93, s28
	v_bfe_u32 v93, v102, 16, 1
	v_pk_mul_f32 v[106:107], v[106:107], v[106:107] op_sel:[0,1] op_sel_hi:[1,0]
	v_pk_mul_f32 v[104:105], v[110:111], v[112:113]
	v_lshrrev_b32_e32 v92, 16, v92
	v_add3_u32 v93, v102, v93, s28
	v_pk_mul_f32 v[104:105], v[104:105], v[104:105] op_sel:[0,1] op_sel_hi:[1,0]
	v_and_or_b32 v92, v93, s29, v92
	v_bfe_u32 v93, v106, 16, 1
	v_add3_u32 v93, v106, v93, s28
	v_bfe_u32 v102, v104, 16, 1
	v_lshrrev_b32_e32 v93, 16, v93
	v_add3_u32 v102, v104, v102, s28
	v_and_or_b32 v93, v102, s29, v93
	global_store_dwordx2 v[94:95], v[92:93], off offset:64
	global_load_dwordx4 v[102:105], v[134:135], off offset:192
	v_bfe_u32 v93, v119, 16, 1
	v_cndmask_b32_e64 v111, 0, v86, s[0:1]
	v_cmp_ge_i32_e64 s[0:1], v169, v152
	v_add3_u32 v93, v119, v93, s28
	v_bfe_u32 v106, v120, 16, 1
	v_cndmask_b32_e64 v86, 0, v83, s[0:1]
	v_cmp_ge_i32_e64 s[0:1], v162, v152
	v_add3_u32 v92, v118, v115, s28
	v_lshrrev_b32_e32 v93, 16, v93
	v_add3_u32 v106, v120, v106, s28
	v_cndmask_b32_e64 v112, 0, v87, s[0:1]
	v_cmp_ge_i32_e64 s[0:1], v164, v152
	v_and_or_b32 v92, v92, s29, v114
	v_and_or_b32 v93, v106, s29, v93
	v_cndmask_b32_e64 v110, v82, 0, s[4:5]
	v_cndmask_b32_e64 v113, 0, v84, s[0:1]
	v_cmp_ge_i32_e64 s[0:1], v163, v152
	v_mfma_f32_16x16x32_bf16 v[106:109], v[58:61], v[90:93], v[74:77]
	s_nop 0
	v_cndmask_b32_e64 v114, 0, v88, s[0:1]
	v_cmp_ge_i32_e64 s[0:1], v166, v152
	v_bfe_u32 v74, v110, 16, 1
	v_bfe_u32 v76, v86, 16, 1
	v_cndmask_b32_e64 v75, 0, v85, s[0:1]
	v_add3_u32 v74, v110, v74, s28
	v_add3_u32 v76, v86, v76, s28
	v_mfma_f32_16x16x32_bf16 v[84:87], v[38:41], v[90:93], v[14:17]
	v_lshrrev_b32_e32 v74, 16, v74
	v_and_or_b32 v74, v76, s29, v74
	v_cmp_ge_i32_e64 s[0:1], v165, v152
	v_bfe_u32 v14, v113, 16, 1
	v_add3_u32 v14, v113, v14, s28
	v_lshrrev_b32_e32 v76, 16, v14
	v_mfma_f32_16x16x32_bf16 v[14:17], v[42:45], v[46:49], 0
	v_cndmask_b32_e64 v115, 0, v89, s[0:1]
	v_cmp_ge_i32_e64 s[0:1], v167, v160
	v_bfe_u32 v77, v75, 16, 1
	v_mfma_f32_16x16x32_bf16 v[46:49], v[30:33], v[46:49], 0
	v_add3_u32 v75, v75, v77, s28
	s_nop 2
	v_cndmask_b32_e64 v14, v14, 0, vcc
	s_waitcnt vmcnt(2)
	v_lshlrev_b32_e32 v77, 16, v97
	v_mfma_f32_16x16x32_bf16 v[80:83], v[62:65], v[90:93], v[78:81]
	v_and_or_b32 v75, v75, s29, v76
	s_waitcnt vmcnt(0)
	v_mov_b32_e32 v76, v104
	v_mfma_f32_16x16x32_bf16 v[10:13], v[66:69], v[90:93], v[10:13]
	v_cndmask_b32_e64 v92, 0, v46, s[0:1]
	v_cmp_ge_i32_e64 s[0:1], v155, v160
	v_and_b32_e32 v79, 0xffff0000, v97
	v_mov_b32_e32 v78, v105
	v_cndmask_b32_e64 v15, 0, v15, s[0:1]
	v_bfe_u32 v46, v15, 16, 1
	v_cmp_ge_i32_e64 s[0:1], v154, v160
	v_add3_u32 v15, v15, v46, s28
	v_bfe_u32 v46, v14, 16, 1
	v_cndmask_b32_e64 v93, 0, v47, s[0:1]
	v_cmp_ge_i32_e64 s[0:1], v157, v160
	v_add3_u32 v14, v14, v46, s28
	v_lshrrev_b32_e32 v14, 16, v14
	v_cndmask_b32_e64 v16, 0, v16, s[0:1]
	v_cmp_ge_i32_e64 s[0:1], v156, v160
	v_and_or_b32 v46, v15, s29, v14
	v_bfe_u32 v15, v16, 16, 1
	v_cndmask_b32_e64 v110, 0, v48, s[0:1]
	v_cmp_ge_i32_e64 s[0:1], v159, v160
	v_add3_u32 v15, v16, v15, s28
	v_lshrrev_b32_e32 v16, 16, v15
	v_cndmask_b32_e64 v17, 0, v17, s[0:1]
	v_bfe_u32 v14, v17, 16, 1
	v_lshlrev_b32_e32 v15, 16, v96
	v_add3_u32 v14, v17, v14, s28
	v_mul_f32_e32 v17, 0xbfb8aa3b, v15
	v_exp_f32_e32 v17, v17
	v_cmp_ge_i32_e64 s[0:1], v158, v160
	v_and_or_b32 v47, v14, s29, v16
	v_mul_f32_e32 v16, v98, v130
	v_add_f32_e32 v14, 1.0, v17
	v_cndmask_b32_e64 v113, 0, v49, s[0:1]
	v_rcp_f32_e32 v17, v14
	v_and_b32_e32 v49, 0xffff0000, v96
	v_mul_f32_e32 v48, 0xbfb8aa3b, v49
	v_exp_f32_e32 v48, v48
	v_mov_b32_e32 v14, v102
	v_pk_mul_f32 v[14:15], v[16:17], v[14:15]
	v_mul_f32_e32 v16, v99, v130
	v_pk_mul_f32 v[14:15], v[14:15], v[14:15] op_sel:[0,1] op_sel_hi:[1,0]
	v_or_b32_e32 v96, s31, v160
	v_add_f32_e32 v15, 1.0, v48
	v_rcp_f32_e32 v17, v15
	v_mul_f32_e32 v15, 0xbfb8aa3b, v77
	v_exp_f32_e32 v15, v15
	v_mov_b32_e32 v48, v103
	v_pk_mul_f32 v[16:17], v[16:17], v[48:49]
	v_mul_f32_e32 v48, v100, v130
	v_add_f32_e32 v15, 1.0, v15
	v_rcp_f32_e32 v49, v15
	v_mul_f32_e32 v15, 0xbfb8aa3b, v79
	v_exp_f32_e32 v15, v15
	v_pk_mul_f32 v[16:17], v[16:17], v[16:17] op_sel:[0,1] op_sel_hi:[1,0]
	v_pk_mul_f32 v[48:49], v[48:49], v[76:77]
	v_mul_f32_e32 v76, v101, v130
	v_add_f32_e32 v15, 1.0, v15
	v_rcp_f32_e32 v77, v15
	v_bfe_u32 v15, v14, 16, 1
	v_add3_u32 v14, v14, v15, s28
	v_bfe_u32 v15, v16, 16, 1
	v_add3_u32 v15, v16, v15, s28
	v_mad_i64_i32 v[16:17], s[0:1], v96, s27, v[138:139]
	v_lshl_add_u64 v[16:17], v[16:17], 0, s[18:19]
	v_pk_mul_f32 v[76:77], v[76:77], v[78:79]
	v_lshl_add_u64 v[78:79], v[16:17], 0, v[136:137]
	global_load_dwordx2 v[98:99], v[78:79], off offset:1024
	v_pk_mul_f32 v[48:49], v[48:49], v[48:49] op_sel:[0,1] op_sel_hi:[1,0]
	v_lshrrev_b32_e32 v14, 16, v14
	v_pk_mul_f32 v[76:77], v[76:77], v[76:77] op_sel:[0,1] op_sel_hi:[1,0]
	v_and_or_b32 v14, v15, s29, v14
	v_bfe_u32 v15, v48, 16, 1
	v_add3_u32 v15, v48, v15, s28
	v_bfe_u32 v16, v76, 16, 1
	v_lshrrev_b32_e32 v15, 16, v15
	v_add3_u32 v16, v76, v16, s28
	v_and_or_b32 v15, v16, s29, v15
	global_store_dwordx2 v[94:95], v[14:15], off offset:96
	global_load_dwordx4 v[88:91], v[134:135], off
	v_bfe_u32 v15, v92, 16, 1
	v_bfe_u32 v116, v93, 16, 1
	v_add3_u32 v15, v92, v15, s28
	v_add3_u32 v14, v93, v116, s28
	v_lshrrev_b32_e32 v15, 16, v15
	v_and_or_b32 v48, v14, s29, v15
	v_bfe_u32 v15, v110, 16, 1
	v_bfe_u32 v14, v113, 16, 1
	v_add3_u32 v15, v110, v15, s28
	v_add3_u32 v14, v113, v14, s28
	v_lshrrev_b32_e32 v15, 16, v15
	v_and_or_b32 v49, v14, s29, v15
	v_bfe_u32 v14, v111, 16, 1
	v_add3_u32 v14, v111, v14, s28
	v_mfma_f32_16x16x32_bf16 v[92:95], v[70:73], v[46:49], v[106:109]
	v_bfe_u32 v15, v112, 16, 1
	v_lshrrev_b32_e32 v14, 16, v14
	v_add3_u32 v15, v112, v15, s28
	v_and_or_b32 v76, v15, s29, v14
	v_mfma_f32_16x16x32_bf16 v[14:17], v[50:53], v[46:49], v[10:13]
	v_ashrrev_i32_e32 v97, 31, v96
	s_nop 1
	v_bfe_u32 v10, v114, 16, 1
	v_add3_u32 v10, v114, v10, s28
	v_mfma_f32_16x16x32_bf16 v[80:83], v[54:57], v[46:49], v[80:83]
	v_lshrrev_b32_e32 v77, 16, v10
	v_mfma_f32_16x16x32_bf16 v[10:13], v[34:37], v[46:49], v[84:87]
	v_mul_f32_e64 v48, v14, v14
	v_mul_f32_e64 v49, v15, v15
	v_pk_mul_f32 v[46:47], v[16:17], v[16:17]
	v_mul_f32_e32 v84, v93, v93
	v_fmac_f32_e32 v84, v92, v92
	v_fmac_f32_e32 v84, v94, v94
	v_fmac_f32_e32 v84, v95, v95
	v_fmac_f32_e32 v84, v80, v80
	v_fmac_f32_e32 v84, v81, v81
	v_fmac_f32_e32 v84, v82, v82
	v_fmac_f32_e32 v84, v83, v83
	v_add_f32_e32 v48, v84, v48
	v_add_f32_e32 v48, v49, v48
	v_add_f32_e32 v46, v46, v48
	v_add_f32_e32 v84, v47, v46
	v_pk_mul_f32 v[48:49], v[10:11], v[10:11]
	v_pk_mul_f32 v[46:47], v[12:13], v[12:13]
	v_add_f32_e32 v48, v84, v48
	v_add_f32_e32 v48, v49, v48
	v_add_f32_e32 v46, v46, v48
	v_add_f32_e32 v84, v47, v46
	ds_bpermute_b32 v85, v170, v84
	v_bfe_u32 v46, v115, 16, 1
	v_add3_u32 v46, v115, v46, s28
	v_and_or_b32 v77, v46, s29, v77
	s_nop 1
	v_mfma_f32_16x16x32_bf16 v[46:49], v[58:61], v[74:77], v[22:25]
	s_waitcnt lgkmcnt(0)
	v_add_f32_e32 v58, v84, v85
	ds_bpermute_b32 v59, v171, v58
	s_waitcnt vmcnt(0)
	v_mov_b32_e32 v61, v88
	v_mfma_f32_16x16x32_bf16 v[22:25], v[62:65], v[74:77], v[26:29]
	global_load_dwordx2 v[64:65], v[78:79], off offset:1056
	s_waitcnt lgkmcnt(0)
	s_nop 0
	v_add_f32_e32 v26, v58, v59
	v_fmamk_f32 v26, v26, 0x3c800000, v150
	v_mul_f32_e32 v27, 0x4b800000, v26
	v_cmp_gt_f32_e64 s[0:1], s30, v26
	s_nop 1
	v_cndmask_b32_e64 v26, v26, v27, s[0:1]
	v_rsq_f32_e32 v58, v26
	v_mfma_f32_16x16x32_bf16 v[26:29], v[66:69], v[74:77], v[6:9]
	v_mov_b32_e32 v67, v90
	s_nop 1
	v_mul_f32_e32 v6, 0x45800000, v58
	v_lshlrev_b32_e32 v8, 16, v98
	v_cndmask_b32_e64 v68, v58, v6, s[0:1]
	v_mul_f32_e32 v58, 0xbfb8aa3b, v8
	v_exp_f32_e32 v59, v58
	v_and_b32_e32 v58, 0xffff0000, v98
	v_mul_f32_e32 v60, 0xbfb8aa3b, v58
	v_exp_f32_e32 v62, v60
	v_add_f32_e32 v59, 1.0, v59
	v_rcp_f32_e32 v60, v59
	v_mul_f32_e32 v9, v92, v68
	v_add_f32_e32 v59, 1.0, v62
	v_rcp_f32_e32 v88, v59
	v_pk_mul_f32 v[8:9], v[60:61], v[8:9]
	v_mul_f32_e32 v59, v93, v68
	v_pk_mul_f32 v[8:9], v[8:9], v[8:9] op_sel:[0,1] op_sel_hi:[1,0]
	v_pk_mul_f32 v[58:59], v[88:89], v[58:59]
	v_lshlrev_b32_e32 v60, 16, v99
	v_pk_mul_f32 v[58:59], v[58:59], v[58:59] op_sel:[0,1] op_sel_hi:[1,0]
	v_mul_f32_e32 v9, 0xbfb8aa3b, v60
	v_and_b32_e32 v62, 0xffff0000, v99
	v_exp_f32_e32 v9, v9
	v_mul_f32_e32 v59, 0xbfb8aa3b, v62
	v_exp_f32_e32 v59, v59
	v_mul_f32_e32 v61, v94, v68
	v_add_f32_e32 v9, 1.0, v9
	v_rcp_f32_e32 v66, v9
	v_add_f32_e32 v9, 1.0, v59
	v_rcp_f32_e32 v90, v9
	v_bfe_u32 v9, v8, 16, 1
	v_pk_mul_f32 v[60:61], v[66:67], v[60:61]
	v_mul_f32_e32 v63, v95, v68
	v_add3_u32 v8, v8, v9, s28
	v_bfe_u32 v9, v58, 16, 1
	v_pk_mul_f32 v[60:61], v[60:61], v[60:61] op_sel:[0,1] op_sel_hi:[1,0]
	v_pk_mul_f32 v[62:63], v[90:91], v[62:63]
	v_lshrrev_b32_e32 v8, 16, v8
	v_add3_u32 v9, v58, v9, s28
	v_pk_mul_f32 v[62:63], v[62:63], v[62:63] op_sel:[0,1] op_sel_hi:[1,0]
	v_and_or_b32 v8, v9, s29, v8
	v_bfe_u32 v9, v60, 16, 1
	v_lshlrev_b64 v[6:7], 11, v[96:97]
	v_add3_u32 v9, v60, v9, s28
	v_bfe_u32 v58, v62, 16, 1
	v_lshl_add_u64 v[6:7], s[8:9], 0, v[6:7]
	v_lshrrev_b32_e32 v9, 16, v9
	v_add3_u32 v58, v62, v58, s28
	v_and_or_b32 v9, v58, s29, v9
	v_lshl_add_u64 v[58:59], v[6:7], 0, v[136:137]
	global_store_dwordx2 v[58:59], v[8:9], off
	global_load_dwordx4 v[60:63], v[134:135], off offset:64
	v_mfma_f32_16x16x32_bf16 v[6:9], v[38:41], v[74:77], v[2:5]
	v_mul_f32_e32 v38, v80, v68
	v_cmp_ge_i32_e64 s[0:1], v153, v152
	s_waitcnt vmcnt(2)
	v_lshlrev_b32_e32 v39, 16, v64
	v_mul_f32_e32 v2, 0xbfb8aa3b, v39
	v_exp_f32_e32 v40, v2
	v_mfma_f32_16x16x32_bf16 v[2:5], v[42:45], v[18:21], 0
	v_and_b32_e32 v43, 0xffff0000, v64
	v_mul_f32_e32 v42, 0xbfb8aa3b, v43
	v_add_f32_e32 v40, 1.0, v40
	v_rcp_f32_e32 v41, v40
	v_exp_f32_e32 v44, v42
	v_lshlrev_b32_e32 v45, 16, v65
	v_mul_f32_e32 v42, v81, v68
	v_mfma_f32_16x16x32_bf16 v[18:21], v[30:33], v[18:21], 0
	v_cndmask_b32_e64 v2, 0, v2, s[0:1]
	v_bfe_u32 v30, v2, 16, 1
	v_add3_u32 v2, v2, v30, s28
	v_lshrrev_b32_e32 v2, 16, v2
	s_waitcnt vmcnt(0)
	v_mov_b32_e32 v40, v60
	v_pk_mul_f32 v[38:39], v[40:41], v[38:39]
	v_mov_b32_e32 v40, v61
	v_pk_mul_f32 v[38:39], v[38:39], v[38:39] op_sel:[0,1] op_sel_hi:[1,0]
	v_and_b32_e32 v61, 0xffff0000, v65
	v_add_f32_e32 v39, 1.0, v44
	v_rcp_f32_e32 v41, v39
	v_mul_f32_e32 v39, 0xbfb8aa3b, v45
	v_exp_f32_e32 v39, v39
	v_mul_f32_e32 v44, v82, v68
	v_pk_mul_f32 v[40:41], v[40:41], v[42:43]
	v_mov_b32_e32 v42, v62
	v_add_f32_e32 v39, 1.0, v39
	v_rcp_f32_e32 v43, v39
	v_mul_f32_e32 v39, 0xbfb8aa3b, v61
	v_exp_f32_e32 v39, v39
	v_mul_f32_e32 v60, v83, v68
	v_pk_mul_f32 v[42:43], v[42:43], v[44:45]
	v_mov_b32_e32 v44, v63
	v_add_f32_e32 v39, 1.0, v39
	v_rcp_f32_e32 v45, v39
	v_pk_mul_f32 v[40:41], v[40:41], v[40:41] op_sel:[0,1] op_sel_hi:[1,0]
	v_bfe_u32 v39, v38, 16, 1
	v_add3_u32 v38, v38, v39, s28
	v_pk_mul_f32 v[44:45], v[44:45], v[60:61]
	global_load_dwordx2 v[60:61], v[78:79], off offset:1088
	v_bfe_u32 v39, v40, 16, 1
	v_pk_mul_f32 v[42:43], v[42:43], v[42:43] op_sel:[0,1] op_sel_hi:[1,0]
	v_lshrrev_b32_e32 v38, 16, v38
	v_add3_u32 v39, v40, v39, s28
	v_pk_mul_f32 v[44:45], v[44:45], v[44:45] op_sel:[0,1] op_sel_hi:[1,0]
	v_and_or_b32 v38, v39, s29, v38
	v_bfe_u32 v39, v42, 16, 1
	v_add3_u32 v39, v42, v39, s28
	v_bfe_u32 v40, v44, 16, 1
	v_lshrrev_b32_e32 v39, 16, v39
	v_add3_u32 v40, v44, v40, s28
	v_and_or_b32 v39, v40, s29, v39
	global_store_dwordx2 v[58:59], v[38:39], off offset:32
	global_load_dwordx4 v[38:41], v[134:135], off offset:128
	v_cndmask_b32_e64 v18, v18, 0, vcc
	v_cmp_ge_i32_e32 vcc, v155, v152
	global_load_dwordx2 v[42:43], v[78:79], off offset:1120
	v_mul_f32_e32 v44, v15, v68
	v_cndmask_b32_e32 v3, 0, v3, vcc
	v_cmp_ge_i32_e32 vcc, v154, v152
	v_bfe_u32 v30, v3, 16, 1
	v_add3_u32 v3, v3, v30, s28
	v_cndmask_b32_e32 v19, 0, v19, vcc
	v_cmp_ge_i32_e32 vcc, v157, v152
	v_and_or_b32 v30, v3, s29, v2
	s_waitcnt vmcnt(3)
	v_and_b32_e32 v45, 0xffff0000, v60
	v_cndmask_b32_e32 v4, 0, v4, vcc
	v_cmp_ge_i32_e32 vcc, v156, v152
	v_bfe_u32 v2, v4, 16, 1
	v_add3_u32 v2, v4, v2, s28
	v_cndmask_b32_e32 v20, 0, v20, vcc
	v_cmp_ge_i32_e32 vcc, v159, v152
	v_lshrrev_b32_e32 v2, 16, v2
	v_lshlrev_b32_e32 v15, 16, v61
	v_cndmask_b32_e32 v5, 0, v5, vcc
	v_bfe_u32 v3, v5, 16, 1
	v_add3_u32 v3, v5, v3, s28
	v_and_or_b32 v31, v3, s29, v2
	v_bfe_u32 v2, v18, 16, 1
	v_cmp_ge_i32_e32 vcc, v158, v152
	v_add3_u32 v2, v18, v2, s28
	v_bfe_u32 v3, v19, 16, 1
	v_cndmask_b32_e32 v21, 0, v21, vcc
	v_lshrrev_b32_e32 v2, 16, v2
	v_add3_u32 v3, v19, v3, s28
	v_and_or_b32 v32, v3, s29, v2
	v_bfe_u32 v3, v21, 16, 1
	v_add3_u32 v4, v21, v3, s28
	v_lshlrev_b32_e32 v3, 16, v60
	v_mul_f32_e32 v5, 0xbfb8aa3b, v3
	v_exp_f32_e32 v5, v5
	v_bfe_u32 v2, v20, 16, 1
	v_add3_u32 v2, v20, v2, s28
	v_lshrrev_b32_e32 v2, 16, v2
	v_and_or_b32 v33, v4, s29, v2
	v_add_f32_e32 v4, 1.0, v5
	v_rcp_f32_e32 v5, v4
	v_mul_f32_e32 v2, v14, v68
	v_mul_f32_e32 v14, 0xbfb8aa3b, v45
	v_exp_f32_e32 v14, v14
	s_waitcnt vmcnt(1)
	v_mov_b32_e32 v4, v38
	v_pk_mul_f32 v[2:3], v[4:5], v[2:3]
	v_mov_b32_e32 v4, v39
	v_pk_mul_f32 v[2:3], v[2:3], v[2:3] op_sel:[0,1] op_sel_hi:[1,0]
	v_mov_b32_e32 v38, v40
	v_add_f32_e32 v3, 1.0, v14
	v_rcp_f32_e32 v5, v3
	v_mul_f32_e32 v3, 0xbfb8aa3b, v15
	v_exp_f32_e32 v3, v3
	v_mul_f32_e32 v14, v16, v68
	v_pk_mul_f32 v[4:5], v[4:5], v[44:45]
	v_and_b32_e32 v45, 0xffff0000, v61
	v_add_f32_e32 v3, 1.0, v3
	v_rcp_f32_e32 v39, v3
	v_mul_f32_e32 v3, 0xbfb8aa3b, v45
	v_exp_f32_e32 v3, v3
	v_pk_mul_f32 v[4:5], v[4:5], v[4:5] op_sel:[0,1] op_sel_hi:[1,0]
	v_pk_mul_f32 v[14:15], v[38:39], v[14:15]
	v_mul_f32_e32 v44, v17, v68
	v_add_f32_e32 v3, 1.0, v3
	v_rcp_f32_e32 v39, v3
	v_bfe_u32 v3, v2, 16, 1
	v_mov_b32_e32 v38, v41
	v_add3_u32 v2, v2, v3, s28
	v_bfe_u32 v3, v4, 16, 1
	v_pk_mul_f32 v[14:15], v[14:15], v[14:15] op_sel:[0,1] op_sel_hi:[1,0]
	v_pk_mul_f32 v[16:17], v[38:39], v[44:45]
	v_lshrrev_b32_e32 v2, 16, v2
	v_add3_u32 v3, v4, v3, s28
	v_pk_mul_f32 v[16:17], v[16:17], v[16:17] op_sel:[0,1] op_sel_hi:[1,0]
	v_and_or_b32 v2, v3, s29, v2
	v_bfe_u32 v3, v14, 16, 1
	v_add3_u32 v3, v14, v3, s28
	v_bfe_u32 v4, v16, 16, 1
	v_lshrrev_b32_e32 v3, 16, v3
	v_add3_u32 v4, v16, v4, s28
	v_and_or_b32 v3, v4, s29, v3
	global_store_dwordx2 v[58:59], v[2:3], off offset:64
	global_load_dwordx4 v[38:41], v[134:135], off offset:192
	v_mfma_f32_16x16x32_bf16 v[14:17], v[54:57], v[30:33], v[22:25]
	s_waitcnt vmcnt(2)
	s_nop 1
	v_lshlrev_b32_e32 v23, 16, v42
	v_mul_f32_e32 v2, 0xbfb8aa3b, v23
	v_exp_f32_e32 v22, v2
	v_mfma_f32_16x16x32_bf16 v[2:5], v[50:53], v[30:33], v[26:29]
	v_mul_f32_e32 v24, v10, v68
	v_add_f32_e32 v10, 1.0, v22
	s_nop 0
	v_and_b32_e32 v27, 0xffff0000, v42
	v_rcp_f32_e32 v25, v10
	v_mul_f32_e32 v10, 0xbfb8aa3b, v27
	v_exp_f32_e32 v26, v10
	v_mul_f32_e32 v10, v11, v68
	v_and_b32_e32 v29, 0xffff0000, v43
	v_mfma_f32_16x16x32_bf16 v[18:21], v[70:73], v[30:33], v[46:49]
	v_add_f32_e32 v11, 1.0, v26
	v_rcp_f32_e32 v11, v11
	s_waitcnt vmcnt(0)
	v_mov_b32_e32 v22, v38
	v_pk_mul_f32 v[22:23], v[24:25], v[22:23]
	v_lshlrev_b32_e32 v25, 16, v43
	v_pk_mul_f32 v[22:23], v[22:23], v[22:23] op_sel:[0,1] op_sel_hi:[1,0]
	v_mov_b32_e32 v26, v39
	v_mul_f32_e32 v23, 0xbfb8aa3b, v25
	v_exp_f32_e32 v23, v23
	v_pk_mul_f32 v[10:11], v[10:11], v[26:27]
	v_mul_f32_e32 v26, v12, v68
	v_pk_mul_f32 v[10:11], v[10:11], v[10:11] op_sel:[0,1] op_sel_hi:[1,0]
	v_mov_b32_e32 v24, v40
	v_add_f32_e32 v11, 1.0, v23
	v_rcp_f32_e32 v27, v11
	v_mul_f32_e32 v11, 0xbfb8aa3b, v29
	v_exp_f32_e32 v11, v11
	v_mov_b32_e32 v28, v41
	v_pk_mul_f32 v[24:25], v[26:27], v[24:25]
	v_mul_f32_e32 v26, v13, v68
	v_add_f32_e32 v11, 1.0, v11
	v_rcp_f32_e32 v27, v11
	v_bfe_u32 v11, v22, 16, 1
	v_add3_u32 v11, v22, v11, s28
	v_lshrrev_b32_e32 v11, 16, v11
	v_pk_mul_f32 v[12:13], v[26:27], v[28:29]
	v_or_b32_e32 v26, s31, v152
	v_pk_mul_f32 v[12:13], v[12:13], v[12:13] op_sel:[0,1] op_sel_hi:[1,0]
	v_pk_mul_f32 v[24:25], v[24:25], v[24:25] op_sel:[0,1] op_sel_hi:[1,0]
	v_bfe_u32 v13, v10, 16, 1
	v_add3_u32 v10, v10, v13, s28
	v_and_or_b32 v22, v10, s29, v11
	v_mad_i64_i32 v[10:11], s[0:1], v26, s27, v[138:139]
	v_lshl_add_u64 v[10:11], v[10:11], 0, s[18:19]
	v_lshl_add_u64 v[10:11], v[10:11], 0, v[136:137]
	global_load_dwordx2 v[28:29], v[10:11], off offset:1024
	v_bfe_u32 v13, v24, 16, 1
	v_add3_u32 v13, v24, v13, s28
	v_bfe_u32 v23, v12, 16, 1
	v_lshrrev_b32_e32 v13, 16, v13
	v_add3_u32 v12, v12, v23, s28
	v_and_or_b32 v23, v12, s29, v13
	global_store_dwordx2 v[58:59], v[22:23], off offset:96
	global_load_dwordx4 v[22:25], v[134:135], off
	v_mul_f32_e32 v27, v19, v19
	v_fmac_f32_e32 v27, v18, v18
	v_fmac_f32_e32 v27, v20, v20
	v_fmac_f32_e32 v27, v21, v21
	v_fmac_f32_e32 v27, v14, v14
	v_fmac_f32_e32 v27, v15, v15
	v_fmac_f32_e32 v27, v16, v16
	v_mfma_f32_16x16x32_bf16 v[6:9], v[34:37], v[30:33], v[6:9]
	v_fmac_f32_e32 v27, v17, v17
	v_pk_mul_f32 v[30:31], v[2:3], v[2:3]
	v_pk_mul_f32 v[12:13], v[4:5], v[4:5]
	v_add_f32_e32 v27, v27, v30
	v_add_f32_e32 v27, v31, v27
	v_add_f32_e32 v12, v12, v27
	v_add_f32_e32 v27, v13, v12
	s_nop 0
	v_pk_mul_f32 v[30:31], v[6:7], v[6:7]
	v_pk_mul_f32 v[12:13], v[8:9], v[8:9]
	v_add_f32_e32 v27, v27, v30
	v_add_f32_e32 v27, v31, v27
	v_add_f32_e32 v12, v12, v27
	v_add_f32_e32 v12, v13, v12
	ds_bpermute_b32 v13, v170, v12
	v_ashrrev_i32_e32 v27, 31, v26
	global_load_dwordx2 v[30:31], v[10:11], off offset:1056
	s_waitcnt lgkmcnt(0)
	v_add_f32_e32 v12, v12, v13
	ds_bpermute_b32 v13, v171, v12
	s_waitcnt lgkmcnt(0)
	v_add_f32_e32 v12, v12, v13
	v_fmamk_f32 v12, v12, 0x3c800000, v150
	v_mul_f32_e32 v13, 0x4b800000, v12
	v_cmp_gt_f32_e32 vcc, s30, v12
	s_waitcnt vmcnt(1)
	v_mov_b32_e32 v33, v22
	v_cndmask_b32_e32 v12, v12, v13, vcc
	v_rsq_f32_e32 v12, v12
	s_nop 0
	v_mul_f32_e32 v13, 0x45800000, v12
	v_cndmask_b32_e32 v34, v12, v13, vcc
	v_lshlrev_b64 v[12:13], 11, v[26:27]
	v_lshlrev_b32_e32 v26, 16, v28
	v_mul_f32_e32 v27, v18, v34
	v_mul_f32_e32 v18, 0xbfb8aa3b, v26
	v_exp_f32_e32 v32, v18
	v_and_b32_e32 v18, 0xffff0000, v28
	v_mul_f32_e32 v28, 0xbfb8aa3b, v18
	v_exp_f32_e32 v28, v28
	v_add_f32_e32 v32, 1.0, v32
	v_rcp_f32_e32 v32, v32
	v_mul_f32_e32 v19, v19, v34
	v_add_f32_e32 v22, 1.0, v28
	v_rcp_f32_e32 v22, v22
	v_pk_mul_f32 v[26:27], v[32:33], v[26:27]
	v_mul_f32_e32 v21, v21, v34
	v_pk_mul_f32 v[26:27], v[26:27], v[26:27] op_sel:[0,1] op_sel_hi:[1,0]
	v_pk_mul_f32 v[18:19], v[22:23], v[18:19]
	v_lshlrev_b32_e32 v22, 16, v29
	v_pk_mul_f32 v[18:19], v[18:19], v[18:19] op_sel:[0,1] op_sel_hi:[1,0]
	v_mul_f32_e32 v23, v20, v34
	v_mul_f32_e32 v19, 0xbfb8aa3b, v22
	v_and_b32_e32 v20, 0xffff0000, v29
	v_exp_f32_e32 v19, v19
	v_mul_f32_e32 v27, 0xbfb8aa3b, v20
	v_exp_f32_e32 v27, v27
	v_mov_b32_e32 v29, v24
	v_add_f32_e32 v19, 1.0, v19
	v_rcp_f32_e32 v28, v19
	v_add_f32_e32 v19, 1.0, v27
	v_rcp_f32_e32 v24, v19
	v_bfe_u32 v19, v26, 16, 1
	v_pk_mul_f32 v[22:23], v[28:29], v[22:23]
	v_add3_u32 v19, v26, v19, s28
	v_pk_mul_f32 v[20:21], v[24:25], v[20:21]
	v_pk_mul_f32 v[22:23], v[22:23], v[22:23] op_sel:[0,1] op_sel_hi:[1,0]
	v_pk_mul_f32 v[20:21], v[20:21], v[20:21] op_sel:[0,1] op_sel_hi:[1,0]
	v_lshrrev_b32_e32 v19, 16, v19
	v_bfe_u32 v21, v18, 16, 1
	v_add3_u32 v18, v18, v21, s28
	v_and_or_b32 v18, v18, s29, v19
	v_bfe_u32 v19, v22, 16, 1
	v_add3_u32 v19, v22, v19, s28
	v_bfe_u32 v21, v20, 16, 1
	v_lshl_add_u64 v[12:13], s[8:9], 0, v[12:13]
	v_lshrrev_b32_e32 v19, 16, v19
	v_add3_u32 v20, v20, v21, s28
	v_and_or_b32 v19, v20, s29, v19
	v_lshl_add_u64 v[12:13], v[12:13], 0, v[136:137]
	global_store_dwordx2 v[12:13], v[18:19], off
	global_load_dwordx4 v[18:21], v[134:135], off offset:64
	s_waitcnt vmcnt(2)
	v_lshlrev_b32_e32 v23, 16, v30
	v_mul_f32_e32 v22, 0xbfb8aa3b, v23
	v_exp_f32_e32 v24, v22
	v_mul_f32_e32 v22, v14, v34
	v_and_b32_e32 v27, 0xffff0000, v30
	v_mul_f32_e32 v26, v15, v34
	v_add_f32_e32 v14, 1.0, v24
	v_rcp_f32_e32 v25, v14
	v_mul_f32_e32 v14, 0xbfb8aa3b, v27
	v_exp_f32_e32 v14, v14
	s_waitcnt vmcnt(0)
	v_mov_b32_e32 v24, v18
	v_add_f32_e32 v14, 1.0, v14
	v_pk_mul_f32 v[22:23], v[24:25], v[22:23]
	v_rcp_f32_e32 v15, v14
	v_lshlrev_b32_e32 v25, 16, v31
	v_mul_f32_e32 v14, 0xbfb8aa3b, v25
	v_exp_f32_e32 v18, v14
	v_mov_b32_e32 v14, v19
	v_pk_mul_f32 v[14:15], v[14:15], v[26:27]
	v_and_b32_e32 v27, 0xffff0000, v31
	v_pk_mul_f32 v[14:15], v[14:15], v[14:15] op_sel:[0,1] op_sel_hi:[1,0]
	v_mul_f32_e32 v24, v16, v34
	v_add_f32_e32 v15, 1.0, v18
	v_rcp_f32_e32 v19, v15
	v_mul_f32_e32 v15, 0xbfb8aa3b, v27
	v_exp_f32_e32 v15, v15
	v_mov_b32_e32 v18, v20
	v_pk_mul_f32 v[18:19], v[18:19], v[24:25]
	v_mov_b32_e32 v24, v21
	v_add_f32_e32 v15, 1.0, v15
	v_rcp_f32_e32 v25, v15
	global_load_dwordx2 v[20:21], v[10:11], off offset:1088
	v_mul_f32_e32 v26, v17, v34
	v_pk_mul_f32 v[22:23], v[22:23], v[22:23] op_sel:[0,1] op_sel_hi:[1,0]
	v_pk_mul_f32 v[16:17], v[24:25], v[26:27]
	v_bfe_u32 v15, v22, 16, 1
	v_pk_mul_f32 v[16:17], v[16:17], v[16:17] op_sel:[0,1] op_sel_hi:[1,0]
	v_add3_u32 v15, v22, v15, s28
	v_bfe_u32 v17, v14, 16, 1
	v_pk_mul_f32 v[18:19], v[18:19], v[18:19] op_sel:[0,1] op_sel_hi:[1,0]
	v_lshrrev_b32_e32 v15, 16, v15
	v_add3_u32 v14, v14, v17, s28
	v_and_or_b32 v14, v14, s29, v15
	v_bfe_u32 v15, v18, 16, 1
	v_add3_u32 v15, v18, v15, s28
	v_bfe_u32 v17, v16, 16, 1
	v_lshrrev_b32_e32 v15, 16, v15
	v_add3_u32 v16, v16, v17, s28
	v_and_or_b32 v15, v16, s29, v15
	global_store_dwordx2 v[12:13], v[14:15], off offset:32
	global_load_dwordx4 v[14:17], v[134:135], off offset:128
	s_nop 0
	global_load_dwordx2 v[10:11], v[10:11], off offset:1120
	v_mul_f32_e32 v24, v3, v34
	s_waitcnt vmcnt(3)
	v_lshlrev_b32_e32 v19, 16, v20
	v_mul_f32_e32 v18, 0xbfb8aa3b, v19
	v_exp_f32_e32 v22, v18
	v_mul_f32_e32 v18, v2, v34
	v_and_b32_e32 v25, 0xffff0000, v20
	v_mul_f32_e32 v20, v5, v34
	v_add_f32_e32 v2, 1.0, v22
	v_rcp_f32_e32 v23, v2
	v_mul_f32_e32 v2, 0xbfb8aa3b, v25
	v_exp_f32_e32 v2, v2
	s_waitcnt vmcnt(1)
	v_mov_b32_e32 v22, v14
	v_add_f32_e32 v2, 1.0, v2
	v_pk_mul_f32 v[18:19], v[22:23], v[18:19]
	v_rcp_f32_e32 v3, v2
	v_lshlrev_b32_e32 v23, 16, v21
	v_mul_f32_e32 v2, 0xbfb8aa3b, v23
	v_exp_f32_e32 v14, v2
	v_mov_b32_e32 v2, v15
	v_pk_mul_f32 v[2:3], v[2:3], v[24:25]
	v_and_b32_e32 v21, 0xffff0000, v21
	v_pk_mul_f32 v[2:3], v[2:3], v[2:3] op_sel:[0,1] op_sel_hi:[1,0]
	v_mul_f32_e32 v22, v4, v34
	v_add_f32_e32 v3, 1.0, v14
	v_rcp_f32_e32 v15, v3
	v_mul_f32_e32 v3, 0xbfb8aa3b, v21
	v_exp_f32_e32 v3, v3
	v_mov_b32_e32 v14, v16
	v_pk_mul_f32 v[14:15], v[14:15], v[22:23]
	v_mov_b32_e32 v22, v17
	v_add_f32_e32 v3, 1.0, v3
	v_rcp_f32_e32 v23, v3
	v_pk_mul_f32 v[18:19], v[18:19], v[18:19] op_sel:[0,1] op_sel_hi:[1,0]
	v_pk_mul_f32 v[14:15], v[14:15], v[14:15] op_sel:[0,1] op_sel_hi:[1,0]
	v_bfe_u32 v3, v18, 16, 1
	v_pk_mul_f32 v[4:5], v[22:23], v[20:21]
	v_add3_u32 v3, v18, v3, s28
	v_pk_mul_f32 v[4:5], v[4:5], v[4:5] op_sel:[0,1] op_sel_hi:[1,0]
	v_lshrrev_b32_e32 v3, 16, v3
	v_bfe_u32 v5, v2, 16, 1
	v_add3_u32 v2, v2, v5, s28
	v_and_or_b32 v2, v2, s29, v3
	v_bfe_u32 v3, v14, 16, 1
	v_add3_u32 v3, v14, v3, s28
	v_bfe_u32 v5, v4, 16, 1
	v_lshrrev_b32_e32 v3, 16, v3
	v_add3_u32 v4, v4, v5, s28
	v_and_or_b32 v3, v4, s29, v3
	global_store_dwordx2 v[12:13], v[2:3], off offset:64
	global_load_dwordx4 v[2:5], v[134:135], off offset:192
	s_waitcnt vmcnt(2)
	v_lshlrev_b32_e32 v15, 16, v10
	v_mul_f32_e32 v14, 0xbfb8aa3b, v15
	v_exp_f32_e32 v14, v14
	v_and_b32_e32 v19, 0xffff0000, v10
	v_mul_f32_e32 v16, v6, v34
	v_add_f32_e32 v6, 1.0, v14
	v_rcp_f32_e32 v17, v6
	v_mul_f32_e32 v6, v7, v34
	s_waitcnt vmcnt(0)
	v_mov_b32_e32 v14, v2
	v_mul_f32_e32 v2, 0xbfb8aa3b, v19
	v_exp_f32_e32 v2, v2
	v_pk_mul_f32 v[14:15], v[16:17], v[14:15]
	v_lshlrev_b32_e32 v17, 16, v11
	v_mov_b32_e32 v18, v3
	v_add_f32_e32 v2, 1.0, v2
	v_rcp_f32_e32 v7, v2
	v_mul_f32_e32 v2, 0xbfb8aa3b, v17
	v_exp_f32_e32 v10, v2
	v_and_b32_e32 v11, 0xffff0000, v11
	v_pk_mul_f32 v[2:3], v[6:7], v[18:19]
	v_mul_f32_e32 v6, v8, v34
	v_pk_mul_f32 v[2:3], v[2:3], v[2:3] op_sel:[0,1] op_sel_hi:[1,0]
	v_mov_b32_e32 v16, v4
	v_add_f32_e32 v3, 1.0, v10
	v_rcp_f32_e32 v7, v3
	v_mul_f32_e32 v3, 0xbfb8aa3b, v11
	v_exp_f32_e32 v3, v3
	v_mov_b32_e32 v10, v5
	v_pk_mul_f32 v[6:7], v[6:7], v[16:17]
	v_mul_f32_e32 v16, v9, v34
	v_add_f32_e32 v3, 1.0, v3
	v_rcp_f32_e32 v17, v3
	v_pk_mul_f32 v[14:15], v[14:15], v[14:15] op_sel:[0,1] op_sel_hi:[1,0]
	v_pk_mul_f32 v[6:7], v[6:7], v[6:7] op_sel:[0,1] op_sel_hi:[1,0]
	v_bfe_u32 v3, v14, 16, 1
	v_pk_mul_f32 v[4:5], v[16:17], v[10:11]
	v_add3_u32 v3, v14, v3, s28
	v_pk_mul_f32 v[4:5], v[4:5], v[4:5] op_sel:[0,1] op_sel_hi:[1,0]
	v_lshrrev_b32_e32 v3, 16, v3
	v_bfe_u32 v5, v2, 16, 1
	v_add3_u32 v2, v2, v5, s28
	v_and_or_b32 v2, v2, s29, v3
	v_bfe_u32 v3, v6, 16, 1
	v_add3_u32 v3, v6, v3, s28
	v_bfe_u32 v5, v4, 16, 1
	v_lshrrev_b32_e32 v3, 16, v3
	v_add3_u32 v4, v4, v5, s28
	v_and_or_b32 v3, v4, s29, v3
	global_store_dwordx2 v[12:13], v[2:3], off offset:96
	s_waitcnt lgkmcnt(0)
	s_cbranch_scc0 .LBB0_1015

.LBB0_1917:
	v_ashrrev_i32_e32 v65, 3, v64
	v_add_u32_e32 v2, s10, v65
	v_lshlrev_b32_e32 v4, 7, v64
	v_mad_i64_i32 v[22:23], s[6:7], v2, s3, v[20:21]
	v_and_b32_e32 v18, 0x200, v4
	v_lshl_add_u64 v[2:3], v[22:23], 0, v[18:19]
	v_and_b32_e32 v18, 0x180, v4
	v_lshl_add_u64 v[2:3], v[2:3], 0, v[18:19]
	global_load_dwordx4 v[28:31], v[2:3], off offset:3136
	global_load_dwordx4 v[32:35], v[2:3], off offset:3152
	global_load_dwordx4 v[68:71], v[2:3], off offset:3168
	global_load_dwordx4 v[72:75], v[2:3], off offset:3184
	global_load_dwordx4 v[14:17], v[2:3], off offset:3200
	global_load_dwordx4 v[10:13], v[2:3], off offset:3216
	global_load_dwordx4 v[6:9], v[2:3], off offset:3232
	s_nop 0
	global_load_dwordx4 v[2:5], v[2:3], off offset:3248
	v_and_b32_e32 v120, 7, v64
	v_lshlrev_b32_e32 v120, 7, v120
	v_mov_b32_e32 v121, 0
	v_lshl_add_u64 v[122:123], v[22:23], 0, v[120:121]
	global_load_dword v124, v[122:123], off offset:2112
	v_add_u32_e32 v126, 0x800, v120
	v_mov_b32_e32 v127, 0
	v_lshl_add_u64 v[126:127], v[22:23], 0, v[126:127]
	global_load_dword v125, v[126:127], off offset:2112
	v_add_u32_e32 v18, s14, v65
	v_add_u32_e32 v18, 0xffffff00, v18
	v_bfe_u32 v66, v64, 2, 1
	v_ashrrev_i32_e32 v25, 3, v18
	v_and_b32_e32 v67, 3, v64
	v_lshlrev_b32_e32 v18, 9, v66
	v_and_b32_e32 v26, -8, v25
	s_cmp_gt_i32 s2, 3
	v_and_b32_e32 v24, 0x1f8, v64
	v_lshl_add_u64 v[22:23], v[22:23], 0, v[18:19]
	v_lshlrev_b32_e32 v18, 7, v67
	v_lshlrev_b32_e32 v26, 1, v26
	s_cselect_b64 s[18:19], -1, 0
	s_cmp_lt_i32 s2, 4
	v_lshl_add_u64 v[22:23], v[22:23], 0, v[18:19]
	v_lshlrev_b32_e32 v18, 3, v24
	v_ashrrev_i32_e32 v27, 31, v26
	v_lshl_or_b32 v24, v25, 1, 14
	s_waitcnt vmcnt(9)
	v_lshlrev_b32_e32 v49, 16, v29
	v_lshlrev_b32_e32 v48, 16, v28
	v_and_b32_e32 v45, 0xffff0000, v29
	v_and_b32_e32 v44, 0xffff0000, v28
	s_waitcnt vmcnt(8)
	v_lshlrev_b32_e32 v61, 16, v33
	v_lshlrev_b32_e32 v60, 16, v32
	v_and_b32_e32 v59, 0xffff0000, v33
	v_and_b32_e32 v58, 0xffff0000, v32
	v_lshlrev_b32_e32 v41, 16, v31
	v_lshlrev_b32_e32 v40, 16, v30
	v_and_b32_e32 v39, 0xffff0000, v31
	v_and_b32_e32 v38, 0xffff0000, v30
	v_lshlrev_b32_e32 v57, 16, v35
	v_lshlrev_b32_e32 v56, 16, v34
	v_and_b32_e32 v55, 0xffff0000, v35
	v_and_b32_e32 v54, 0xffff0000, v34
	s_waitcnt vmcnt(7)
	v_and_b32_e32 v30, 0xffff0000, v70
	v_lshlrev_b32_e32 v37, 16, v69
	v_lshlrev_b32_e32 v36, 16, v68
	v_and_b32_e32 v35, 0xffff0000, v69
	v_and_b32_e32 v34, 0xffff0000, v68
	s_waitcnt vmcnt(6)
	v_lshlrev_b32_e32 v53, 16, v73
	v_lshlrev_b32_e32 v52, 16, v72
	v_and_b32_e32 v51, 0xffff0000, v73
	v_and_b32_e32 v50, 0xffff0000, v72
	v_and_b32_e32 v28, 0xffff0000, v74
	v_lshlrev_b32_e32 v33, 16, v71
	v_lshlrev_b32_e32 v32, 16, v70
	v_lshlrev_b32_e32 v47, 16, v75
	v_lshlrev_b32_e32 v46, 16, v74
	v_and_b32_e32 v43, 0xffff0000, v71
	v_and_b32_e32 v42, 0xffff0000, v75
	s_cbranch_scc1 .LBB0_1919
	v_lshl_add_u64 v[80:81], v[26:27], 2, s[8:9]
	v_lshl_add_u64 v[84:85], s[8:9], 0, v[18:19]
	v_ashrrev_i32_e32 v25, 31, v24
	global_load_dwordx4 v[68:71], v[80:81], off
	global_load_dwordx4 v[72:75], v[80:81], off offset:16
	global_load_dwordx4 v[76:79], v[80:81], off offset:32
	global_load_dwordx2 v[96:97], v[80:81], off offset:48
	v_lshl_add_u64 v[92:93], v[84:85], 0, s[12:13]
	v_lshl_add_u64 v[86:87], v[24:25], 2, s[8:9]
	global_load_dwordx4 v[80:83], v[92:93], off offset:48
	global_load_dwordx2 v[98:99], v[86:87], off
	v_add_co_u32_e32 v84, vcc, s25, v84
	s_waitcnt vmcnt(5)
	v_mov_b32_e32 v100, v68
	v_addc_co_u32_e32 v85, vcc, 0, v85, vcc
	global_load_dwordx4 v[84:87], v[84:85], off
	s_nop 0
	global_load_dwordx4 v[88:91], v[92:93], off offset:16
	s_nop 0
	global_load_dwordx4 v[92:95], v[92:93], off offset:32
	s_waitcnt vmcnt(7)
	v_mov_b32_e32 v101, v72
	v_mov_b32_e32 v72, v69
	v_mov_b32_e32 v69, v74
	v_mov_b32_e32 v74, v71
	s_waitcnt vmcnt(5)
	v_mov_b32_e32 v71, v96
	v_mov_b32_e32 v96, v77
	v_mov_b32_e32 v68, v70
	v_mov_b32_e32 v70, v76
	v_mov_b32_e32 v76, v78
	v_pk_mul_f32 v[104:105], v[72:73], v[48:49]
	v_pk_mul_f32 v[106:107], v[74:75], v[44:45]
	v_pk_mul_f32 v[72:73], v[72:73], v[60:61]
	v_pk_mul_f32 v[110:111], v[96:97], v[40:41]
	s_waitcnt vmcnt(3)
	v_mov_b32_e32 v77, v98
	v_mov_b32_e32 v98, v79
	v_pk_mul_f32 v[78:79], v[96:97], v[56:57]
	v_pk_mul_f32 v[74:75], v[74:75], v[58:59]
	v_pk_fma_f32 v[96:97], v[100:101], v[60:61], v[104:105]
	v_pk_fma_f32 v[104:105], v[68:69], v[58:59], v[106:107]
	v_pk_fma_f32 v[48:49], v[100:101], v[48:49], v[72:73] neg_lo:[0,0,1] neg_hi:[0,0,1]
	v_pk_fma_f32 v[72:73], v[70:71], v[56:57], v[110:111]
	v_pk_mul_f32 v[56:57], v[98:99], v[38:39]
	v_pk_fma_f32 v[40:41], v[70:71], v[40:41], v[78:79] neg_lo:[0,0,1] neg_hi:[0,0,1]
	v_pk_mul_f32 v[58:59], v[98:99], v[54:55]
	v_pk_fma_f32 v[44:45], v[68:69], v[44:45], v[74:75] neg_lo:[0,0,1] neg_hi:[0,0,1]
	v_pk_fma_f32 v[74:75], v[76:77], v[54:55], v[56:57]
	v_pk_fma_f32 v[38:39], v[76:77], v[38:39], v[58:59] neg_lo:[0,0,1] neg_hi:[0,0,1]
	v_bfe_u32 v54, v41, 16, 1
	v_bfe_u32 v55, v48, 16, 1
	v_bfe_u32 v56, v49, 16, 1
	v_bfe_u32 v25, v45, 16, 1
	v_bfe_u32 v31, v40, 16, 1
	v_bfe_u32 v57, v105, 16, 1
	v_bfe_u32 v59, v72, 16, 1
	v_bfe_u32 v60, v73, 16, 1
	v_bfe_u32 v69, v39, 16, 1
	v_bfe_u32 v70, v38, 16, 1
	v_add3_u32 v56, v49, v56, s26
	v_add3_u32 v55, v48, v55, s26
	v_add3_u32 v54, v41, v54, s26
	v_bfe_u32 v29, v44, 16, 1
	v_bfe_u32 v61, v96, 16, 1
	v_bfe_u32 v68, v97, 16, 1
	v_add3_u32 v25, v45, v25, s26
	v_add3_u32 v31, v40, v31, s26
	v_bfe_u32 v71, v75, 16, 1
	v_add3_u32 v77, v105, v57, s26
	v_add3_u32 v60, v73, v60, s26
	v_add3_u32 v57, v72, v59, s26
	v_add3_u32 v59, v38, v70, s26
	v_add3_u32 v69, v39, v69, s26
	v_lshrrev_b32_e32 v70, 16, v54
	v_lshrrev_b32_e32 v54, 16, v55
	v_lshrrev_b32_e32 v55, 16, v56
	v_add3_u32 v29, v44, v29, s26
	v_bfe_u32 v76, v74, 16, 1
	v_add3_u32 v68, v97, v68, s26
	v_add3_u32 v61, v96, v61, s26
	v_lshrrev_b32_e32 v31, 16, v31
	v_add3_u32 v71, v75, v71, s26
	v_lshrrev_b32_e32 v78, 16, v57
	v_and_or_b32 v55, v25, s24, v55
	v_and_or_b32 v57, v69, s24, v70
	v_lshrrev_b32_e32 v25, 16, v60
	v_add3_u32 v76, v74, v76, s26
	v_and_or_b32 v54, v29, s24, v54
	v_and_or_b32 v56, v59, s24, v31
	v_lshrrev_b32_e32 v29, 16, v61
	v_lshrrev_b32_e32 v31, 16, v68
	v_and_or_b32 v61, v71, s24, v25
	v_and_or_b32 v59, v77, s24, v31
	v_and_or_b32 v60, v76, s24, v78
	v_bfe_u32 v58, v104, 16, 1
	v_add3_u32 v58, v104, v58, s26
	v_pk_mul_f32 v[102:103], v[82:83], v[42:43]
	v_and_or_b32 v58, v58, s24, v29
	v_mov_b32_e32 v29, v42
	s_waitcnt vmcnt(2)
	v_mov_b32_e32 v68, v84
	s_waitcnt vmcnt(1)
	v_mov_b32_e32 v69, v88
	v_mov_b32_e32 v88, v85
	v_pk_mul_f32 v[70:71], v[88:89], v[36:37]
	v_mov_b32_e32 v31, v43
	v_pk_fma_f32 v[76:77], v[68:69], v[52:53], v[70:71]
	v_mov_b32_e32 v71, v90
	v_mov_b32_e32 v90, v87
	v_mov_b32_e32 v70, v86
	v_pk_mul_f32 v[78:79], v[90:91], v[34:35]
	v_pk_mul_f32 v[52:53], v[88:89], v[52:53]
	v_pk_fma_f32 v[78:79], v[70:71], v[50:51], v[78:79]
	v_pk_mul_f32 v[50:51], v[90:91], v[50:51]
	v_pk_fma_f32 v[36:37], v[68:69], v[36:37], v[52:53] neg_lo:[0,0,1] neg_hi:[0,0,1]
	v_pk_fma_f32 v[34:35], v[70:71], v[34:35], v[50:51] neg_lo:[0,0,1] neg_hi:[0,0,1]
	v_mov_b32_e32 v51, v80
	s_waitcnt vmcnt(0)
	v_mov_b32_e32 v80, v93
	v_mov_b32_e32 v50, v92
	v_pk_mul_f32 v[52:53], v[80:81], v[32:33]
	v_mov_b32_e32 v71, v82
	v_mov_b32_e32 v82, v95
	v_pk_fma_f32 v[84:85], v[50:51], v[46:47], v[52:53]
	v_mul_f32_e32 v52, v94, v28
	v_mov_b32_e32 v70, v94
	v_pk_mul_f32 v[28:29], v[82:83], v[28:29]
	v_mul_f32_e32 v68, v95, v30
	v_pk_fma_f32 v[30:31], v[70:71], v[30:31], v[28:29] neg_lo:[0,0,1] neg_hi:[0,0,1]
	v_pk_mul_f32 v[28:29], v[80:81], v[46:47]
	v_mov_b32_e32 v53, v102
	v_pk_fma_f32 v[32:33], v[50:51], v[32:33], v[28:29] neg_lo:[0,0,1] neg_hi:[0,0,1]
	v_mov_b32_e32 v69, v103
	v_bfe_u32 v47, v32, 16, 1
	v_bfe_u32 v50, v33, 16, 1
	v_bfe_u32 v51, v36, 16, 1
	v_pk_add_f32 v[28:29], v[52:53], v[68:69]
	v_bfe_u32 v25, v31, 16, 1
	v_bfe_u32 v42, v30, 16, 1
	v_bfe_u32 v46, v34, 16, 1
	v_bfe_u32 v52, v37, 16, 1
	v_add3_u32 v50, v33, v50, s26
	v_add3_u32 v47, v32, v47, s26
	v_add3_u32 v51, v36, v51, s26
	v_bfe_u32 v43, v35, 16, 1
	v_add3_u32 v42, v30, v42, s26
	v_add3_u32 v25, v31, v25, s26
	v_add3_u32 v46, v34, v46, s26
	v_add3_u32 v52, v37, v52, s26
	v_lshrrev_b32_e32 v47, 16, v47
	v_lshrrev_b32_e32 v50, 16, v50
	v_lshrrev_b32_e32 v68, 16, v51
	v_add3_u32 v43, v35, v43, s26
	v_lshrrev_b32_e32 v51, 16, v52
	v_and_or_b32 v53, v25, s24, v50
	v_and_or_b32 v52, v42, s24, v47
	v_and_or_b32 v50, v46, s24, v68
	v_bfe_u32 v47, v84, 16, 1
	v_bfe_u32 v68, v85, 16, 1
	v_bfe_u32 v69, v76, 16, 1
	v_bfe_u32 v70, v77, 16, 1
	v_and_or_b32 v51, v43, s24, v51
	v_bfe_u32 v25, v29, 16, 1
	v_bfe_u32 v42, v28, 16, 1
	v_bfe_u32 v43, v79, 16, 1
	v_bfe_u32 v46, v78, 16, 1
	v_add3_u32 v68, v85, v68, s26
	v_add3_u32 v47, v84, v47, s26
	v_add3_u32 v70, v77, v70, s26
	v_add3_u32 v69, v76, v69, s26
	v_add3_u32 v46, v78, v46, s26
	v_add3_u32 v43, v79, v43, s26
	v_add3_u32 v42, v28, v42, s26
	v_add3_u32 v25, v29, v25, s26
	v_lshrrev_b32_e32 v47, 16, v47
	v_lshrrev_b32_e32 v68, 16, v68
	v_lshrrev_b32_e32 v80, 16, v69
	v_lshrrev_b32_e32 v69, 16, v70
	v_and_or_b32 v71, v25, s24, v68
	v_and_or_b32 v70, v42, s24, v47
	v_and_or_b32 v69, v43, s24, v69
	v_and_or_b32 v68, v46, s24, v80
	global_store_dwordx4 v[22:23], v[54:57], off offset:3136
	global_store_dwordx4 v[22:23], v[58:61], off offset:3152
	global_store_dwordx4 v[22:23], v[50:53], off offset:3168
	global_store_dwordx4 v[22:23], v[68:71], off offset:3184
	v_mov_b32_e32 v60, v96
	v_mov_b32_e32 v58, v104
	v_mov_b32_e32 v61, v97
	v_mov_b32_e32 v59, v105
	v_mov_b32_e32 v56, v72
	v_mov_b32_e32 v54, v74
	v_mov_b32_e32 v57, v73
	v_mov_b32_e32 v55, v75
	v_mov_b32_e32 v43, v31
	v_mov_b32_e32 v52, v76
	v_mov_b32_e32 v50, v78
	v_mov_b32_e32 v53, v77
	v_mov_b32_e32 v51, v79
	v_mov_b32_e32 v46, v84
	v_mov_b32_e32 v47, v85
	v_mov_b32_e32 v42, v29

.LBB0_2159:
	s_waitcnt lgkmcnt(1)
	v_mfma_f32_16x16x32_bf16 v[170:173], v[130:133], v[34:37], v[2:5]
	ds_read_b128 v[182:185], v247 offset:2048
	v_mfma_f32_16x16x32_bf16 v[178:181], v[130:133], v[38:41], v[10:13]
	ds_read_b128 v[130:133], v247
	s_nop 2
	s_nop 1
	v_exp_f32_e32 v198, v170
	v_exp_f32_e32 v199, v173
	s_waitcnt lgkmcnt(2)
	v_mfma_f32_16x16x32_bf16 v[174:177], v[166:169], v[34:37], v[2:5]
	v_exp_f32_e32 v178, v178
	ds_read_b64 v[214:215], v248 offset:37376
	ds_read_b64 v[216:217], v248 offset:37408
	v_mfma_f32_16x16x32_bf16 v[166:169], v[166:169], v[38:41], v[10:13]
	ds_read_b64 v[218:219], v248 offset:39680
	ds_read_b64 v[220:221], v248 offset:39712
	s_nop 2
	v_exp_f32_e32 v202, v174
	v_exp_f32_e32 v174, v171
	s_waitcnt lgkmcnt(4)
	v_mfma_f32_16x16x32_bf16 v[186:189], v[130:133], v[42:45], v[6:9]
	v_exp_f32_e32 v203, v175
	v_exp_f32_e32 v211, v166
	v_exp_f32_e32 v166, v179
	v_mfma_f32_16x16x32_bf16 v[194:197], v[130:133], v[46:49], v[14:17]
	ds_read_b128 v[130:133], v246 offset:4096
	v_exp_f32_e32 v179, v167
	v_exp_f32_e32 v167, v180
	v_exp_f32_e32 v180, v168
	v_exp_f32_e32 v168, v181
	v_exp_f32_e32 v169, v169
	v_exp_f32_e32 v175, v172
	v_cvt_pk_bf16_f32 v166, v178, v166
	v_cvt_pk_bf16_f32 v167, v167, v168
	v_cvt_pk_bf16_f32 v168, v211, v179
	v_cvt_pk_bf16_f32 v169, v180, v169
	ds_read_b64 v[178:179], v248 offset:32768
	ds_read_b64 v[180:181], v248 offset:32800
	ds_read_b64 v[210:211], v248 offset:35072
	ds_read_b64 v[212:213], v248 offset:35104
	ds_read_b128 v[170:173], v246 offset:6144
	v_cvt_pk_bf16_f32 v174, v198, v174
	v_cvt_pk_bf16_f32 v175, v175, v199
	s_waitcnt lgkmcnt(5)
	v_mfma_f32_16x16x32_bf16 v[198:201], v[130:133], v[34:37], v[2:5]
	v_exp_f32_e32 v229, v188
	v_exp_f32_e32 v204, v176
	v_exp_f32_e32 v177, v177
	v_mfma_f32_16x16x32_bf16 v[206:209], v[130:133], v[38:41], v[10:13]
	v_exp_f32_e32 v186, v186
	v_mfma_f32_16x16x32_bf16 v[190:193], v[182:185], v[42:45], v[6:9]
	v_exp_f32_e32 v187, v187
	v_exp_f32_e32 v194, v194
	v_cvt_pk_bf16_f32 v176, v202, v203
	v_mfma_f32_16x16x32_bf16 v[182:185], v[182:185], v[46:49], v[14:17]
	v_cvt_pk_bf16_f32 v177, v204, v177
	s_nop 2
	v_exp_f32_e32 v190, v190
	v_exp_f32_e32 v191, v191
	v_mfma_f32_16x16x32_bf16 v[86:89], v[240:243], v[166:169], v[86:89]
	v_exp_f32_e32 v192, v192
	v_exp_f32_e32 v185, v185
	ds_read_b128 v[222:225], v247 offset:4096
	s_waitcnt lgkmcnt(4)
	v_mfma_f32_16x16x32_bf16 v[78:81], v[178:181], v[166:169], v[78:81]
	s_add_i32 s36, s36, 2
	s_addk_i32 s10, 0x80
	v_lshl_add_u64 v[146:147], v[146:147], 0, s[14:15]
	s_waitcnt lgkmcnt(2)
	v_mfma_f32_16x16x32_bf16 v[74:77], v[210:213], v[166:169], v[74:77]
	s_and_b64 vcc, exec, s[0:1]
	v_mfma_f32_16x16x32_bf16 v[70:73], v[214:217], v[166:169], v[70:73]
	v_mfma_f32_16x16x32_bf16 v[62:65], v[218:221], v[166:169], v[62:65]
	v_exp_f32_e32 v167, v189
	v_exp_f32_e32 v169, v193
	v_cvt_pk_bf16_f32 v166, v186, v187
	s_waitcnt lgkmcnt(1)
	v_mfma_f32_16x16x32_bf16 v[202:205], v[170:173], v[34:37], v[2:5]
	v_cvt_pk_bf16_f32 v167, v229, v167
	v_exp_f32_e32 v229, v182
	v_exp_f32_e32 v182, v195
	v_exp_f32_e32 v195, v183
	v_exp_f32_e32 v183, v196
	v_exp_f32_e32 v196, v184
	v_exp_f32_e32 v184, v197
	v_cvt_pk_bf16_f32 v168, v190, v191
	v_cvt_pk_bf16_f32 v169, v192, v169
	v_cvt_pk_bf16_f32 v182, v194, v182
	v_cvt_pk_bf16_f32 v183, v183, v184
	v_cvt_pk_bf16_f32 v184, v229, v195
	v_cvt_pk_bf16_f32 v185, v196, v185
	v_mfma_f32_16x16x32_bf16 v[170:173], v[170:173], v[38:41], v[10:13]
	v_exp_f32_e32 v194, v198
	v_exp_f32_e32 v195, v202
	v_exp_f32_e32 v196, v199
	v_mfma_f32_16x16x32_bf16 v[122:125], v[178:181], v[174:177], v[122:125]
	v_exp_f32_e32 v198, v205
	v_exp_f32_e32 v197, v201
	v_mfma_f32_16x16x32_bf16 v[102:105], v[178:181], v[166:169], v[102:105]
	v_mfma_f32_16x16x32_bf16 v[58:61], v[178:181], v[182:185], v[58:61]
	v_exp_f32_e32 v180, v203
	v_exp_f32_e32 v181, v204
	v_exp_f32_e32 v179, v200
	v_mfma_f32_16x16x32_bf16 v[126:129], v[240:243], v[174:177], v[126:129]
	v_cvt_pk_bf16_f32 v178, v194, v196
	v_cvt_pk_bf16_f32 v180, v195, v180
	v_cvt_pk_bf16_f32 v181, v181, v198
	v_mfma_f32_16x16x32_bf16 v[118:121], v[210:213], v[174:177], v[118:121]
	v_exp_f32_e32 v194, v206
	v_exp_f32_e32 v195, v170
	v_exp_f32_e32 v170, v207
	v_mfma_f32_16x16x32_bf16 v[110:113], v[214:217], v[174:177], v[110:113]
	v_exp_f32_e32 v198, v172
	v_cvt_pk_bf16_f32 v179, v179, v197
	v_exp_f32_e32 v196, v171
	v_mfma_f32_16x16x32_bf16 v[106:109], v[218:221], v[174:177], v[106:109]
	ds_read_b128 v[174:177], v247 offset:6144
	v_exp_f32_e32 v197, v208
	ds_read_b128 v[202:205], v246 offset:14336
	v_mfma_f32_16x16x32_bf16 v[114:117], v[240:243], v[166:169], v[114:117]
	v_mfma_f32_16x16x32_bf16 v[98:101], v[210:213], v[166:169], v[98:101]
	v_mfma_f32_16x16x32_bf16 v[94:97], v[214:217], v[166:169], v[94:97]
	v_mfma_f32_16x16x32_bf16 v[90:93], v[218:221], v[166:169], v[90:93]
	v_exp_f32_e32 v169, v173
	v_exp_f32_e32 v167, v209
	v_cvt_pk_bf16_f32 v166, v194, v170
	v_mfma_f32_16x16x32_bf16 v[82:85], v[240:243], v[182:185], v[82:85]
	v_cvt_pk_bf16_f32 v169, v198, v169
	v_mfma_f32_16x16x32_bf16 v[54:57], v[210:213], v[182:185], v[54:57]
	ds_read_b64 v[170:171], v248 offset:32832
	ds_read_b64 v[172:173], v248 offset:32864
	v_cvt_pk_bf16_f32 v167, v197, v167
	v_mfma_f32_16x16x32_bf16 v[50:53], v[214:217], v[182:185], v[50:53]
	v_cvt_pk_bf16_f32 v168, v195, v196
	ds_read_b64 v[194:195], v248 offset:37440
	ds_read_b64 v[196:197], v248 offset:37472
	ds_read_b64 v[198:199], v248 offset:39744
	ds_read_b64 v[200:201], v248 offset:39776
	v_mfma_f32_16x16x32_bf16 v[66:69], v[218:221], v[182:185], v[66:69]
	ds_read_b64 v[182:183], v248 offset:35136
	ds_read_b64 v[184:185], v248 offset:35168
	s_waitcnt lgkmcnt(10)
	v_mfma_f32_16x16x32_bf16 v[186:189], v[222:225], v[42:45], v[6:9]
	ds_read_b64 v[214:215], v248 offset:46592
	ds_read_b64 v[216:217], v248 offset:46624
	s_waitcnt lgkmcnt(11)
	v_mfma_f32_16x16x32_bf16 v[190:193], v[174:177], v[42:45], v[6:9]
	ds_read_b64 v[218:219], v248 offset:48896
	ds_read_b64 v[220:221], v248 offset:48928
	s_nop 1
	v_exp_f32_e32 v186, v186
	v_exp_f32_e32 v187, v187
	v_mfma_f32_16x16x32_bf16 v[222:225], v[222:225], v[46:49], v[14:17]
	v_exp_f32_e32 v188, v188
	s_nop 0
	v_exp_f32_e32 v190, v190
	v_exp_f32_e32 v191, v191
	v_mfma_f32_16x16x32_bf16 v[174:177], v[174:177], v[46:49], v[14:17]
	v_exp_f32_e32 v189, v189
	v_exp_f32_e32 v192, v192
	v_exp_f32_e32 v193, v193
	v_mfma_f32_16x16x32_bf16 v[126:129], v[240:243], v[178:181], v[126:129]
	v_cvt_pk_bf16_f32 v186, v186, v187
	v_cvt_pk_bf16_f32 v187, v188, v189
	v_cvt_pk_bf16_f32 v188, v190, v191
	v_mfma_f32_16x16x32_bf16 v[86:89], v[240:243], v[166:169], v[86:89]
	v_exp_f32_e32 v190, v222
	v_exp_f32_e32 v174, v174
	v_exp_f32_e32 v191, v223
	s_waitcnt lgkmcnt(10)
	v_mfma_f32_16x16x32_bf16 v[122:125], v[170:173], v[178:181], v[122:125]
	v_exp_f32_e32 v175, v175
	v_exp_f32_e32 v176, v176
	v_cvt_pk_bf16_f32 v189, v192, v193
	v_mfma_f32_16x16x32_bf16 v[78:81], v[170:173], v[166:169], v[78:81]
	s_waitcnt lgkmcnt(4)
	v_mfma_f32_16x16x32_bf16 v[118:121], v[182:185], v[178:181], v[118:121]
	v_mfma_f32_16x16x32_bf16 v[74:77], v[182:185], v[166:169], v[74:77]
	v_mfma_f32_16x16x32_bf16 v[110:113], v[194:197], v[178:181], v[110:113]
	v_mfma_f32_16x16x32_bf16 v[70:73], v[194:197], v[166:169], v[70:73]
	v_mfma_f32_16x16x32_bf16 v[106:109], v[198:201], v[178:181], v[106:109]
	v_exp_f32_e32 v178, v224
	v_mfma_f32_16x16x32_bf16 v[62:65], v[198:201], v[166:169], v[62:65]
	v_exp_f32_e32 v167, v225
	v_exp_f32_e32 v169, v177
	v_cvt_pk_bf16_f32 v166, v190, v191
	v_cvt_pk_bf16_f32 v168, v174, v175
	v_cvt_pk_bf16_f32 v167, v178, v167
	v_cvt_pk_bf16_f32 v169, v176, v169
	v_mfma_f32_16x16x32_bf16 v[102:105], v[170:173], v[186:189], v[102:105]
	ds_read_b128 v[222:225], v247 offset:12288
	v_mfma_f32_16x16x32_bf16 v[82:85], v[240:243], v[166:169], v[82:85]
	v_mfma_f32_16x16x32_bf16 v[58:61], v[170:173], v[166:169], v[58:61]
	ds_read_b128 v[170:173], v246 offset:8192
	v_mfma_f32_16x16x32_bf16 v[54:57], v[182:185], v[166:169], v[54:57]
	v_mfma_f32_16x16x32_bf16 v[50:53], v[194:197], v[166:169], v[50:53]
	v_mfma_f32_16x16x32_bf16 v[66:69], v[198:201], v[166:169], v[66:69]
	ds_read_b128 v[166:169], v246 offset:10240
	s_waitcnt lgkmcnt(1)
	v_mfma_f32_16x16x32_bf16 v[174:177], v[170:173], v[34:37], v[2:5]
	s_waitcnt lgkmcnt(0)
	v_mfma_f32_16x16x32_bf16 v[178:181], v[166:169], v[34:37], v[2:5]
	s_nop 5
	v_exp_f32_e32 v174, v174
	v_mfma_f32_16x16x32_bf16 v[170:173], v[170:173], v[38:41], v[10:13]
	v_exp_f32_e32 v206, v178
	v_exp_f32_e32 v175, v175
	v_exp_f32_e32 v207, v179
	v_mfma_f32_16x16x32_bf16 v[166:169], v[166:169], v[38:41], v[10:13]
	v_exp_f32_e32 v176, v176
	s_nop 2
	v_exp_f32_e32 v170, v170
	v_exp_f32_e32 v208, v180
	v_mfma_f32_16x16x32_bf16 v[114:117], v[240:243], v[186:189], v[114:117]
	v_exp_f32_e32 v177, v177
	v_exp_f32_e32 v211, v166
	v_exp_f32_e32 v166, v171
	v_exp_f32_e32 v171, v167
	v_exp_f32_e32 v167, v172
	v_exp_f32_e32 v172, v168
	v_exp_f32_e32 v168, v173
	v_exp_f32_e32 v169, v169
	v_mfma_f32_16x16x32_bf16 v[98:101], v[182:185], v[186:189], v[98:101]
	ds_read_b128 v[182:185], v247 offset:8192
	v_cvt_pk_bf16_f32 v166, v170, v166
	v_cvt_pk_bf16_f32 v167, v167, v168
	v_mfma_f32_16x16x32_bf16 v[94:97], v[194:197], v[186:189], v[94:97]
	v_cvt_pk_bf16_f32 v168, v211, v171
	v_cvt_pk_bf16_f32 v169, v172, v169
	ds_read_b64 v[170:171], v248 offset:41984
	ds_read_b64 v[172:173], v248 offset:42016
	v_mfma_f32_16x16x32_bf16 v[90:93], v[198:201], v[186:189], v[90:93]
	ds_read_b128 v[186:189], v247 offset:10240
	ds_read_b64 v[210:211], v248 offset:44288
	ds_read_b64 v[212:213], v248 offset:44320
	ds_read_b128 v[198:201], v246 offset:12288
	s_waitcnt lgkmcnt(6)
	v_mfma_f32_16x16x32_bf16 v[190:193], v[182:185], v[42:45], v[6:9]
	v_exp_f32_e32 v209, v181
	v_cvt_pk_bf16_f32 v174, v174, v175
	v_cvt_pk_bf16_f32 v175, v176, v177
	s_waitcnt lgkmcnt(3)
	v_mfma_f32_16x16x32_bf16 v[194:197], v[186:189], v[42:45], v[6:9]
	v_cvt_pk_bf16_f32 v176, v206, v207
	s_nop 1
	v_exp_f32_e32 v190, v190
	v_exp_f32_e32 v191, v191
	v_mfma_f32_16x16x32_bf16 v[182:185], v[182:185], v[46:49], v[14:17]
	s_nop 1
	v_exp_f32_e32 v194, v194
	v_exp_f32_e32 v195, v195
	v_exp_f32_e32 v226, v192
	v_mfma_f32_16x16x32_bf16 v[186:189], v[186:189], v[46:49], v[14:17]
	v_exp_f32_e32 v196, v196
	s_nop 0
	v_exp_f32_e32 v182, v182
	v_exp_f32_e32 v183, v183
	v_mfma_f32_16x16x32_bf16 v[86:89], v[240:243], v[166:169], v[86:89]
	v_exp_f32_e32 v184, v184
	s_nop 1
	v_exp_f32_e32 v186, v186
	v_exp_f32_e32 v187, v187
	v_mfma_f32_16x16x32_bf16 v[78:81], v[170:173], v[166:169], v[78:81]
	v_exp_f32_e32 v188, v188
	v_exp_f32_e32 v185, v185
	v_exp_f32_e32 v189, v189
	s_waitcnt lgkmcnt(1)
	v_mfma_f32_16x16x32_bf16 v[74:77], v[210:213], v[166:169], v[74:77]
	v_cvt_pk_bf16_f32 v177, v208, v209
	v_cvt_pk_bf16_f32 v182, v182, v183
	v_cvt_pk_bf16_f32 v183, v184, v185
	v_mfma_f32_16x16x32_bf16 v[70:73], v[214:217], v[166:169], v[70:73]
	v_cvt_pk_bf16_f32 v184, v186, v187
	v_cvt_pk_bf16_f32 v185, v188, v189
	v_mfma_f32_16x16x32_bf16 v[62:65], v[218:221], v[166:169], v[62:65]
	v_exp_f32_e32 v167, v193
	v_exp_f32_e32 v169, v197
	v_cvt_pk_bf16_f32 v166, v190, v191
	s_waitcnt lgkmcnt(0)
	v_mfma_f32_16x16x32_bf16 v[178:181], v[198:201], v[34:37], v[2:5]
	v_cvt_pk_bf16_f32 v167, v226, v167
	v_cvt_pk_bf16_f32 v168, v194, v195
	v_cvt_pk_bf16_f32 v169, v196, v169
	v_mfma_f32_16x16x32_bf16 v[206:209], v[202:205], v[34:37], v[2:5]
	v_mfma_f32_16x16x32_bf16 v[198:201], v[198:201], v[38:41], v[10:13]
	s_nop 2
	v_exp_f32_e32 v178, v178
	s_nop 2
	v_exp_f32_e32 v186, v206
	v_mfma_f32_16x16x32_bf16 v[202:205], v[202:205], v[38:41], v[10:13]
	v_mfma_f32_16x16x32_bf16 v[122:125], v[170:173], v[174:177], v[122:125]
	v_exp_f32_e32 v188, v200
	s_nop 5
	v_exp_f32_e32 v187, v203
	v_exp_f32_e32 v189, v205
	v_mfma_f32_16x16x32_bf16 v[102:105], v[170:173], v[166:169], v[102:105]
	v_mfma_f32_16x16x32_bf16 v[58:61], v[170:173], v[182:185], v[58:61]
	v_exp_f32_e32 v170, v179
	v_exp_f32_e32 v172, v207
	v_exp_f32_e32 v171, v180
	v_exp_f32_e32 v179, v181
	v_mfma_f32_16x16x32_bf16 v[126:129], v[240:243], v[174:177], v[126:129]
	v_exp_f32_e32 v173, v208
	v_exp_f32_e32 v180, v209
	v_cvt_pk_bf16_f32 v170, v178, v170
	v_mfma_f32_16x16x32_bf16 v[118:121], v[210:213], v[174:177], v[118:121]
	v_cvt_pk_bf16_f32 v171, v171, v179
	v_cvt_pk_bf16_f32 v172, v186, v172
	v_exp_f32_e32 v178, v198
	v_mfma_f32_16x16x32_bf16 v[110:113], v[214:217], v[174:177], v[110:113]
	v_exp_f32_e32 v186, v202
	v_exp_f32_e32 v179, v199
	v_cvt_pk_bf16_f32 v173, v173, v180
	v_mfma_f32_16x16x32_bf16 v[106:109], v[218:221], v[174:177], v[106:109]
	ds_read_b128 v[174:177], v247 offset:14336
	v_mfma_f32_16x16x32_bf16 v[114:117], v[240:243], v[166:169], v[114:117]
	v_mfma_f32_16x16x32_bf16 v[98:101], v[210:213], v[166:169], v[98:101]
	v_mfma_f32_16x16x32_bf16 v[94:97], v[214:217], v[166:169], v[94:97]
	v_mfma_f32_16x16x32_bf16 v[90:93], v[218:221], v[166:169], v[90:93]
	v_exp_f32_e32 v169, v204
	v_exp_f32_e32 v167, v201
	v_mfma_f32_16x16x32_bf16 v[82:85], v[240:243], v[182:185], v[82:85]
	v_cvt_pk_bf16_f32 v166, v178, v179
	ds_read_b64 v[178:179], v248 offset:42048
	ds_read_b64 v[180:181], v248 offset:42080
	v_cvt_pk_bf16_f32 v168, v186, v187
	v_mfma_f32_16x16x32_bf16 v[54:57], v[210:213], v[182:185], v[54:57]
	v_cvt_pk_bf16_f32 v167, v188, v167
	v_cvt_pk_bf16_f32 v169, v169, v189
	v_mfma_f32_16x16x32_bf16 v[50:53], v[214:217], v[182:185], v[50:53]
	ds_read_b64 v[186:187], v248 offset:46656
	ds_read_b64 v[188:189], v248 offset:46688
	ds_read_b64 v[198:199], v248 offset:48960
	ds_read_b64 v[200:201], v248 offset:48992
	v_mfma_f32_16x16x32_bf16 v[66:69], v[218:221], v[182:185], v[66:69]
	ds_read_b64 v[182:183], v248 offset:44352
	ds_read_b64 v[184:185], v248 offset:44384
	v_mfma_f32_16x16x32_bf16 v[190:193], v[222:225], v[42:45], v[6:9]
	s_waitcnt lgkmcnt(8)
	v_mfma_f32_16x16x32_bf16 v[194:197], v[174:177], v[42:45], v[6:9]
	v_mfma_f32_16x16x32_bf16 v[222:225], v[222:225], v[46:49], v[14:17]
	s_nop 4
	v_exp_f32_e32 v190, v190
	s_nop 0
	v_exp_f32_e32 v194, v194
	v_exp_f32_e32 v191, v191
	v_mfma_f32_16x16x32_bf16 v[174:177], v[174:177], v[46:49], v[14:17]
	v_exp_f32_e32 v195, v195
	v_exp_f32_e32 v192, v192
	v_exp_f32_e32 v193, v193
	v_mfma_f32_16x16x32_bf16 v[126:129], v[240:243], v[170:173], v[126:129]
	v_exp_f32_e32 v196, v196
	v_exp_f32_e32 v197, v197
	v_cvt_pk_bf16_f32 v190, v190, v191
	v_mfma_f32_16x16x32_bf16 v[86:89], v[240:243], v[166:169], v[86:89]
	v_cvt_pk_bf16_f32 v191, v192, v193
	v_cvt_pk_bf16_f32 v192, v194, v195
	v_exp_f32_e32 v194, v222
	s_waitcnt lgkmcnt(6)
	v_mfma_f32_16x16x32_bf16 v[122:125], v[178:181], v[170:173], v[122:125]
	v_exp_f32_e32 v174, v174
	v_exp_f32_e32 v195, v223
	v_cvt_pk_bf16_f32 v193, v196, v197
	v_mfma_f32_16x16x32_bf16 v[78:81], v[178:181], v[166:169], v[78:81]
	s_waitcnt lgkmcnt(0)
	v_mfma_f32_16x16x32_bf16 v[118:121], v[182:185], v[170:173], v[118:121]
	v_mfma_f32_16x16x32_bf16 v[74:77], v[182:185], v[166:169], v[74:77]
	v_mfma_f32_16x16x32_bf16 v[110:113], v[186:189], v[170:173], v[110:113]
	v_mfma_f32_16x16x32_bf16 v[70:73], v[186:189], v[166:169], v[70:73]
	v_mfma_f32_16x16x32_bf16 v[106:109], v[198:201], v[170:173], v[106:109]
	v_exp_f32_e32 v170, v175
	v_exp_f32_e32 v171, v224
	v_exp_f32_e32 v172, v176
	v_mfma_f32_16x16x32_bf16 v[62:65], v[198:201], v[166:169], v[62:65]
	v_exp_f32_e32 v167, v225
	v_exp_f32_e32 v169, v177
	v_cvt_pk_bf16_f32 v166, v194, v195
	v_cvt_pk_bf16_f32 v168, v174, v170
	v_cvt_pk_bf16_f32 v167, v171, v167
	v_cvt_pk_bf16_f32 v169, v172, v169
	v_mfma_f32_16x16x32_bf16 v[114:117], v[240:243], v[190:193], v[114:117]
	s_nop 0
	v_mfma_f32_16x16x32_bf16 v[82:85], v[240:243], v[166:169], v[82:85]
	v_mfma_f32_16x16x32_bf16 v[102:105], v[178:181], v[190:193], v[102:105]
	v_mfma_f32_16x16x32_bf16 v[58:61], v[178:181], v[166:169], v[58:61]
	v_mfma_f32_16x16x32_bf16 v[98:101], v[182:185], v[190:193], v[98:101]
	v_mfma_f32_16x16x32_bf16 v[54:57], v[182:185], v[166:169], v[54:57]
	v_mfma_f32_16x16x32_bf16 v[94:97], v[186:189], v[190:193], v[94:97]
	v_mfma_f32_16x16x32_bf16 v[50:53], v[186:189], v[166:169], v[50:53]
	v_mfma_f32_16x16x32_bf16 v[90:93], v[198:201], v[190:193], v[90:93]
	v_mfma_f32_16x16x32_bf16 v[66:69], v[198:201], v[166:169], v[66:69]
	v_xor_b32_e32 v246, 0x4000, v246
	v_xor_b32_e32 v247, 0x4000, v247
	v_xor_b32_e32 v244, 0x4000, v244
	v_add_u32_e32 v248, s99, v248
	v_add_u32_e32 v245, s99, v245
	s_sub_i32 s99, 0, s99
	s_cbranch_vccnz .LBB0_2162
.LBB0_2160:
	s_and_b32 s0, s10, 0x80
	s_lshl_b32 s1, s0, 7
	s_add_i32 s37, s1, 0
	s_lshl_b32 s0, s0, 4
	s_add_i32 s2, s37, s0
	s_cmpk_gt_u32 s36, 0x101
	s_cselect_b64 s[0:1], -1, 0
	s_and_b64 vcc, exec, s[0:1]
	s_waitcnt vmcnt(3)
	ds_write_b128 v244, v[18:21]
	s_waitcnt vmcnt(1)
	ds_write_b128 v245, v[22:25] offset:32768
	s_waitcnt vmcnt(1)
	ds_write_b128 v244, v[26:29] offset:8192
	s_waitcnt vmcnt(0)
	ds_write_b128 v245, v[30:33] offset:41984
	s_waitcnt lgkmcnt(0)
	s_barrier
	ds_read_b128 v[130:133], v246
	ds_read_b128 v[166:169], v246 offset:2048
	s_cbranch_vccnz .LBB0_2159
	s_add_i32 s38, s33, s10
	s_add_i32 s39, s38, 0xffffff80
	s_sub_i32 s40, s38, 64
	s_cmp_eq_u32 s10, 0
	s_cselect_b32 s38, s34, s39
	v_add_u32_e32 v18, s38, v159
	v_mad_i64_i32 v[18:19], s[38:39], v18, s19, v[144:145]
	s_cselect_b32 s38, s35, s40
	s_nop 0
	v_add_u32_e32 v20, s38, v159
	v_mad_i64_i32 v[22:23], s[38:39], v20, s19, v[144:145]
	global_load_dwordx4 v[18:21], v[18:19], off offset:3648
	s_nop 0
	global_load_dwordx4 v[26:29], v[22:23], off offset:3648
	s_nop 0
	global_load_dwordx4 v[22:25], v[146:147], off
	global_load_dwordx4 v[30:33], v[146:147], off offset:128
	s_branch .LBB0_2159
